# loop-edge edit: GEMM K-loop counter/pointer SALU and exit compare hoisted in front of the body's last s_barrier
# baseline (speedup 1.0000x reference)
; #define PG8_STAGE(bufoff, gbase, voff) do { _Pragma("unroll") for (int _i = 0; _i < 2; ++_i) \
;         __builtin_amdgcn_global_load_lds((const unsigned*)((const char*)(gbase) + (voff)[_i]), (PG8_LAS unsigned*)(lds + (bufoff) + ldsw + _i * 8192), 16, 0, 0); } while (0)
; #define PG8_LDA(dst, b, h) do { _Pragma("unroll") for (int m = 0; m < 4; ++m) _Pragma("unroll") for (int k = 0; k < 2; ++k) dst[m][k] = *(const PG8_LAS bf16x8*)(lds + PG8_SA(b, h) + aoff + m * 2048 + k * 1024); } while (0)
; #define PG8_LDB(dst, b, h) do { _Pragma("unroll") for (int n = 0; n < 2; ++n) _Pragma("unroll") for (int k = 0; k < 2; ++k) dst[n][k] = *(const PG8_LAS bf16x8*)(lds + PG8_SB(b, h) + boff + n * 2048 + k * 1024); } while (0)
; #define PG8_MMA(ai, bj, At, Bt) do { __builtin_amdgcn_s_setprio(1); _Pragma("unroll") for (int m = 0; m < 4; ++m) _Pragma("unroll") for (int n = 0; n < 2; ++n) _Pragma("unroll") for (int k = 0; k < 2; ++k) \
;         acc[ai][bj][m][n] = __builtin_amdgcn_mfma_f32_16x16x32_bf16(Bt[n][k], At[m][k], acc[ai][bj][m][n], 0, 0, 0); __builtin_amdgcn_s_setprio(0); } while (0)
; #define PG8_WAIT_V(n) asm volatile("s_waitcnt vmcnt(" #n ")" ::: "memory")
; #define PG8_WAIT_L(n) asm volatile("s_waitcnt lgkmcnt(" #n ")" ::: "memory")
; #define PG8_BAR __builtin_amdgcn_s_barrier()
; #define PG8_SCHED __builtin_amdgcn_sched_barrier(0)
; template <class Epi, class Sched, bool ALIGN_EPI = false, bool SP2 = false>
; __device__ __forceinline__ void gemm_phase(PG8_LAS unsigned char* lds, const Gemm g, const Sched& S, const Epi& E) {
;     ...
;             const bool last = (t == nt - 2);
;             const char* a1 = cA + (size_t)(t + 1) * kstep;
;             const char* a2 = last ? nA : cA + (size_t)(t + 2) * kstep; const char* b2 = last ? nB : cB + (size_t)(t + 2) * kstep;
;             const char* a3 = a2 + kstep; const char* b3 = b2 + kstep;
;             if (last && has_next) S.a_ready(nxt);
;             if constexpr (SP2) {
;             PG8_LDB(B0, 0, 0); PG8_LDB(B1, 0, 1); PG8_SCHED; PG8_LDA(At, 0, 0); PG8_STAGE(PG8_SA(1, 1), a1 + hstep, voffA);
;             PG8_WAIT_V(8); PG8_WAIT_L(0); PG8_BAR; PG8_MMA(0, 0, At, B0); PG8_MMA(0, 1, At, B1); PG8_BAR; PG8_SCHED;
;             PG8_LDA(At, 0, 1); PG8_STAGE(PG8_SB(0, 0), b2, voffB); PG8_STAGE(PG8_SB(0, 1), b2 + hstep, voffB); PG8_STAGE(PG8_SA(0, 0), a2, voffA);
.LBB0_179:
	ds_read_b128 v[146:149], v152
	ds_read_b128 v[156:159], v152 offset:1024
	ds_read_b128 v[162:165], v152 offset:2048
	ds_read_b128 v[166:169], v152 offset:3072
	ds_read_b128 v[170:173], v153
	ds_read_b128 v[178:181], v153 offset:1024
	ds_read_b128 v[182:185], v153 offset:2048
	ds_read_b128 v[186:189], v153 offset:3072
	s_add_u32 s8, s52, 0xfffc0080
	s_addc_u32 s9, s53, -1
	s_cmp_eq_u32 s86, 12
	s_cselect_b32 s57, s37, s9
	s_cselect_b32 s56, s80, s8
	s_cselect_b32 s55, s19, s83
	s_cselect_b32 s54, s81, s82
	v_lshl_add_u64 v[174:175], s[52:53], 0, v[136:137]
	s_add_i32 m0, s51, 0xc000
	ds_read_b128 v[190:193], v154
	ds_read_b128 v[194:197], v154 offset:1024
	ds_read_b128 v[198:201], v154 offset:2048
	ds_read_b128 v[202:205], v154 offset:3072
	ds_read_b128 v[206:209], v154 offset:4096
	ds_read_b128 v[210:213], v154 offset:5120
	ds_read_b128 v[214:217], v154 offset:6144
	ds_read_b128 v[218:221], v154 offset:7168
	global_load_lds_dwordx4 v[174:175], off
	v_lshl_add_u64 v[174:175], s[52:53], 0, v[138:139]
	s_add_i32 m0, s51, 0xe000
	s_nop 0
	global_load_lds_dwordx4 v[174:175], off
	s_waitcnt vmcnt(8)
	s_waitcnt lgkmcnt(0)
	s_barrier
	s_setprio 1
	s_waitcnt lgkmcnt(0)
	v_mfma_f32_16x16x32_bf16 v[124:127], v[146:149], v[190:193], v[124:127]
	v_mfma_f32_16x16x32_bf16 v[120:123], v[162:165], v[190:193], v[120:123]
	v_mfma_f32_16x16x32_bf16 v[112:115], v[146:149], v[198:201], v[112:115]
	v_mfma_f32_16x16x32_bf16 v[104:107], v[162:165], v[198:201], v[104:107]
	v_mfma_f32_16x16x32_bf16 v[96:99], v[146:149], v[206:209], v[96:99]
	v_mfma_f32_16x16x32_bf16 v[88:91], v[162:165], v[206:209], v[88:91]
	v_mfma_f32_16x16x32_bf16 v[80:83], v[146:149], v[214:217], v[80:83]
	v_mfma_f32_16x16x32_bf16 v[72:75], v[162:165], v[214:217], v[72:75]
	v_mfma_f32_16x16x32_bf16 v[124:127], v[156:159], v[194:197], v[124:127]
	v_mfma_f32_16x16x32_bf16 v[120:123], v[166:169], v[194:197], v[120:123]
	v_mfma_f32_16x16x32_bf16 v[112:115], v[156:159], v[202:205], v[112:115]
	v_mfma_f32_16x16x32_bf16 v[104:107], v[166:169], v[202:205], v[104:107]
	v_mfma_f32_16x16x32_bf16 v[96:99], v[156:159], v[210:213], v[96:99]
	v_mfma_f32_16x16x32_bf16 v[88:91], v[166:169], v[210:213], v[88:91]
	v_mfma_f32_16x16x32_bf16 v[80:83], v[156:159], v[218:221], v[80:83]
	v_mfma_f32_16x16x32_bf16 v[72:75], v[166:169], v[218:221], v[72:75]
	s_setprio 0
	s_setprio 1
	v_mfma_f32_16x16x32_bf16 v[116:119], v[170:173], v[190:193], v[116:119]
	v_mfma_f32_16x16x32_bf16 v[108:111], v[182:185], v[190:193], v[108:111]
	v_mfma_f32_16x16x32_bf16 v[100:103], v[170:173], v[198:201], v[100:103]
	v_mfma_f32_16x16x32_bf16 v[92:95], v[182:185], v[198:201], v[92:95]
	v_mfma_f32_16x16x32_bf16 v[84:87], v[170:173], v[206:209], v[84:87]
	v_mfma_f32_16x16x32_bf16 v[76:79], v[182:185], v[206:209], v[76:79]
	v_mfma_f32_16x16x32_bf16 v[68:71], v[170:173], v[214:217], v[68:71]
	v_mfma_f32_16x16x32_bf16 v[64:67], v[182:185], v[214:217], v[64:67]
	v_mfma_f32_16x16x32_bf16 v[116:119], v[178:181], v[194:197], v[116:119]
	v_mfma_f32_16x16x32_bf16 v[108:111], v[186:189], v[194:197], v[108:111]
	v_mfma_f32_16x16x32_bf16 v[100:103], v[178:181], v[202:205], v[100:103]
	v_mfma_f32_16x16x32_bf16 v[92:95], v[186:189], v[202:205], v[92:95]
	v_mfma_f32_16x16x32_bf16 v[84:87], v[178:181], v[210:213], v[84:87]
	v_mfma_f32_16x16x32_bf16 v[76:79], v[186:189], v[210:213], v[76:79]
	v_mfma_f32_16x16x32_bf16 v[68:71], v[178:181], v[218:221], v[68:71]
	v_mfma_f32_16x16x32_bf16 v[64:67], v[186:189], v[218:221], v[64:67]
	s_setprio 0
	s_barrier
	s_add_i32 s8, s76, s3
	v_lshl_add_u64 v[174:175], s[54:55], 0, v[132:133]
	s_mov_b32 m0, s8
	ds_read_b128 v[190:193], v154 offset:16384
	ds_read_b128 v[194:197], v154 offset:17408
	ds_read_b128 v[198:201], v154 offset:18432
	ds_read_b128 v[202:205], v154 offset:19456
	ds_read_b128 v[206:209], v154 offset:20480
	ds_read_b128 v[210:213], v154 offset:21504
	ds_read_b128 v[214:217], v154 offset:22528
	ds_read_b128 v[218:221], v154 offset:23552
	global_load_lds_dwordx4 v[174:175], off
	s_add_i32 m0, s8, 0x2000
	s_add_u32 s8, s54, 0x40000
	v_lshl_add_u64 v[222:223], s[54:55], 0, v[128:129]
	s_addc_u32 s9, s55, 0
	s_add_i32 s60, s77, s3
	global_load_lds_dwordx4 v[222:223], off
	v_lshl_add_u64 v[224:225], s[8:9], 0, v[132:133]
	s_mov_b32 m0, s60
	v_lshl_add_u64 v[226:227], s[56:57], 0, v[130:131]
	global_load_lds_dwordx4 v[224:225], off
	v_lshl_add_u64 v[224:225], s[8:9], 0, v[128:129]
	s_add_i32 m0, s60, 0x2000
	s_nop 0
	global_load_lds_dwordx4 v[224:225], off
	v_lshl_add_u64 v[224:225], s[56:57], 0, v[134:135]
	s_mov_b32 m0, s51
	s_nop 0
	global_load_lds_dwordx4 v[224:225], off
	s_mov_b32 m0, s68
	s_nop 0
	global_load_lds_dwordx4 v[226:227], off
	s_waitcnt vmcnt(8)
	s_waitcnt lgkmcnt(0)
	s_barrier
; #define PG8_STAGE(bufoff, gbase, voff) do { _Pragma("unroll") for (int _i = 0; _i < 2; ++_i) \
;         __builtin_amdgcn_global_load_lds((const unsigned*)((const char*)(gbase) + (voff)[_i]), (PG8_LAS unsigned*)(lds + (bufoff) + ldsw + _i * 8192), 16, 0, 0); } while (0)
; #define PG8_LDA(dst, b, h) do { _Pragma("unroll") for (int m = 0; m < 4; ++m) _Pragma("unroll") for (int k = 0; k < 2; ++k) dst[m][k] = *(const PG8_LAS bf16x8*)(lds + PG8_SA(b, h) + aoff + m * 2048 + k * 1024); } while (0)
; #define PG8_LDB(dst, b, h) do { _Pragma("unroll") for (int n = 0; n < 2; ++n) _Pragma("unroll") for (int k = 0; k < 2; ++k) dst[n][k] = *(const PG8_LAS bf16x8*)(lds + PG8_SB(b, h) + boff + n * 2048 + k * 1024); } while (0)
; #define PG8_MMA(ai, bj, At, Bt) do { __builtin_amdgcn_s_setprio(1); _Pragma("unroll") for (int m = 0; m < 4; ++m) _Pragma("unroll") for (int n = 0; n < 2; ++n) _Pragma("unroll") for (int k = 0; k < 2; ++k) \
;         acc[ai][bj][m][n] = __builtin_amdgcn_mfma_f32_16x16x32_bf16(Bt[n][k], At[m][k], acc[ai][bj][m][n], 0, 0, 0); __builtin_amdgcn_s_setprio(0); } while (0)
; #define PG8_WAIT_V(n) asm volatile("s_waitcnt vmcnt(" #n ")" ::: "memory")
; #define PG8_WAIT_L(n) asm volatile("s_waitcnt lgkmcnt(" #n ")" ::: "memory")
; #define PG8_BAR __builtin_amdgcn_s_barrier()
; #define PG8_SCHED __builtin_amdgcn_sched_barrier(0)
; template <class Epi, class Sched, bool ALIGN_EPI = false, bool SP2 = false>
; __device__ __forceinline__ void gemm_phase(PG8_LAS unsigned char* lds, const Gemm g, const Sched& S, const Epi& E) {
;     ...
;             PG8_WAIT_V(8); PG8_WAIT_L(0); PG8_BAR; PG8_MMA(1, 0, At, B0); PG8_MMA(1, 1, At, B1); PG8_BAR; PG8_SCHED;
;             PG8_LDB(B0, 1, 0); PG8_LDB(B1, 1, 1); PG8_SCHED; PG8_LDA(At, 1, 0); PG8_STAGE(PG8_SA(0, 1), a2 + hstep, voffA);
;             PG8_WAIT_V(8); PG8_WAIT_L(0); PG8_BAR; PG8_MMA(0, 0, At, B0); PG8_MMA(0, 1, At, B1); PG8_BAR; PG8_SCHED;
	s_setprio 1
	s_waitcnt lgkmcnt(0)
	v_mfma_f32_16x16x32_bf16 v[60:63], v[146:149], v[190:193], v[60:63]
	v_mfma_f32_16x16x32_bf16 v[56:59], v[162:165], v[190:193], v[56:59]
	v_mfma_f32_16x16x32_bf16 v[48:51], v[146:149], v[198:201], v[48:51]
	v_mfma_f32_16x16x32_bf16 v[40:43], v[162:165], v[198:201], v[40:43]
	v_mfma_f32_16x16x32_bf16 v[32:35], v[146:149], v[206:209], v[32:35]
	v_mfma_f32_16x16x32_bf16 v[24:27], v[162:165], v[206:209], v[24:27]
	v_mfma_f32_16x16x32_bf16 v[16:19], v[146:149], v[214:217], v[16:19]
	v_mfma_f32_16x16x32_bf16 v[8:11], v[162:165], v[214:217], v[8:11]
	v_mfma_f32_16x16x32_bf16 v[60:63], v[156:159], v[194:197], v[60:63]
	v_mfma_f32_16x16x32_bf16 v[56:59], v[166:169], v[194:197], v[56:59]
	v_mfma_f32_16x16x32_bf16 v[48:51], v[156:159], v[202:205], v[48:51]
	v_mfma_f32_16x16x32_bf16 v[40:43], v[166:169], v[202:205], v[40:43]
	v_mfma_f32_16x16x32_bf16 v[32:35], v[156:159], v[210:213], v[32:35]
	v_mfma_f32_16x16x32_bf16 v[24:27], v[166:169], v[210:213], v[24:27]
	v_mfma_f32_16x16x32_bf16 v[16:19], v[156:159], v[218:221], v[16:19]
	v_mfma_f32_16x16x32_bf16 v[8:11], v[166:169], v[218:221], v[8:11]
	s_setprio 0
	s_setprio 1
	v_mfma_f32_16x16x32_bf16 v[52:55], v[170:173], v[190:193], v[52:55]
	v_mfma_f32_16x16x32_bf16 v[44:47], v[182:185], v[190:193], v[44:47]
	v_mfma_f32_16x16x32_bf16 v[36:39], v[170:173], v[198:201], v[36:39]
	v_mfma_f32_16x16x32_bf16 v[28:31], v[182:185], v[198:201], v[28:31]
	v_mfma_f32_16x16x32_bf16 v[20:23], v[170:173], v[206:209], v[20:23]
	v_mfma_f32_16x16x32_bf16 v[12:15], v[182:185], v[206:209], v[12:15]
	v_mfma_f32_16x16x32_bf16 v[4:7], v[170:173], v[214:217], v[4:7]
	v_mfma_f32_16x16x32_bf16 v[0:3], v[182:185], v[214:217], v[0:3]
	v_mfma_f32_16x16x32_bf16 v[52:55], v[178:181], v[194:197], v[52:55]
	v_mfma_f32_16x16x32_bf16 v[44:47], v[186:189], v[194:197], v[44:47]
	v_mfma_f32_16x16x32_bf16 v[36:39], v[178:181], v[202:205], v[36:39]
	v_mfma_f32_16x16x32_bf16 v[28:31], v[186:189], v[202:205], v[28:31]
	v_mfma_f32_16x16x32_bf16 v[20:23], v[178:181], v[210:213], v[20:23]
	v_mfma_f32_16x16x32_bf16 v[12:15], v[186:189], v[210:213], v[12:15]
	v_mfma_f32_16x16x32_bf16 v[4:7], v[178:181], v[218:221], v[4:7]
	v_mfma_f32_16x16x32_bf16 v[0:3], v[186:189], v[218:221], v[0:3]
	s_setprio 0
	s_barrier
	s_add_i32 s60, 0, 0x18000
	v_add_u32_e32 v144, s60, v150
	s_add_i32 s61, 0, 0x1c000
	ds_read_b128 v[146:149], v144
	ds_read_b128 v[156:159], v144 offset:1024
	ds_read_b128 v[162:165], v144 offset:2048
	ds_read_b128 v[166:169], v144 offset:3072
	v_add_u32_e32 v144, s61, v150
	ds_read_b128 v[170:173], v144
	ds_read_b128 v[178:181], v144 offset:1024
	ds_read_b128 v[182:185], v144 offset:2048
	ds_read_b128 v[186:189], v144 offset:3072
	s_add_u32 s8, s56, 0x40000
	s_addc_u32 s9, s57, 0
	s_mov_b32 m0, s69
	v_lshl_add_u64 v[228:229], s[8:9], 0, v[134:135]
	ds_read_b128 v[190:193], v154 offset:32768
	ds_read_b128 v[194:197], v154 offset:33792
	ds_read_b128 v[198:201], v154 offset:34816
	ds_read_b128 v[202:205], v154 offset:35840
	ds_read_b128 v[206:209], v154 offset:36864
	ds_read_b128 v[210:213], v154 offset:37888
	ds_read_b128 v[214:217], v154 offset:38912
	ds_read_b128 v[218:221], v154 offset:39936
	global_load_lds_dwordx4 v[228:229], off
	v_lshl_add_u64 v[228:229], s[8:9], 0, v[130:131]
	s_mov_b32 m0, s70
	s_nop 0
	global_load_lds_dwordx4 v[228:229], off
	s_waitcnt vmcnt(8)
	s_waitcnt lgkmcnt(0)
	s_barrier
	s_setprio 1
	s_waitcnt lgkmcnt(0)
	v_mfma_f32_16x16x32_bf16 v[124:127], v[146:149], v[190:193], v[124:127]
	v_mfma_f32_16x16x32_bf16 v[120:123], v[162:165], v[190:193], v[120:123]
	v_mfma_f32_16x16x32_bf16 v[112:115], v[146:149], v[198:201], v[112:115]
	v_mfma_f32_16x16x32_bf16 v[104:107], v[162:165], v[198:201], v[104:107]
	v_mfma_f32_16x16x32_bf16 v[96:99], v[146:149], v[206:209], v[96:99]
	v_mfma_f32_16x16x32_bf16 v[88:91], v[162:165], v[206:209], v[88:91]
	v_mfma_f32_16x16x32_bf16 v[80:83], v[146:149], v[214:217], v[80:83]
	v_mfma_f32_16x16x32_bf16 v[72:75], v[162:165], v[214:217], v[72:75]
	v_mfma_f32_16x16x32_bf16 v[124:127], v[156:159], v[194:197], v[124:127]
	v_mfma_f32_16x16x32_bf16 v[120:123], v[166:169], v[194:197], v[120:123]
	v_mfma_f32_16x16x32_bf16 v[112:115], v[156:159], v[202:205], v[112:115]
	v_mfma_f32_16x16x32_bf16 v[104:107], v[166:169], v[202:205], v[104:107]
	v_mfma_f32_16x16x32_bf16 v[96:99], v[156:159], v[210:213], v[96:99]
	v_mfma_f32_16x16x32_bf16 v[88:91], v[166:169], v[210:213], v[88:91]
	v_mfma_f32_16x16x32_bf16 v[80:83], v[156:159], v[218:221], v[80:83]
	v_mfma_f32_16x16x32_bf16 v[72:75], v[166:169], v[218:221], v[72:75]
	s_setprio 0
	s_setprio 1
	v_mfma_f32_16x16x32_bf16 v[116:119], v[170:173], v[190:193], v[116:119]
	v_mfma_f32_16x16x32_bf16 v[108:111], v[182:185], v[190:193], v[108:111]
	v_mfma_f32_16x16x32_bf16 v[100:103], v[170:173], v[198:201], v[100:103]
	v_mfma_f32_16x16x32_bf16 v[92:95], v[182:185], v[198:201], v[92:95]
	v_mfma_f32_16x16x32_bf16 v[84:87], v[170:173], v[206:209], v[84:87]
	v_mfma_f32_16x16x32_bf16 v[76:79], v[182:185], v[206:209], v[76:79]
	v_mfma_f32_16x16x32_bf16 v[68:71], v[170:173], v[214:217], v[68:71]
	v_mfma_f32_16x16x32_bf16 v[64:67], v[182:185], v[214:217], v[64:67]
	v_mfma_f32_16x16x32_bf16 v[116:119], v[178:181], v[194:197], v[116:119]
	v_mfma_f32_16x16x32_bf16 v[108:111], v[186:189], v[194:197], v[108:111]
	v_mfma_f32_16x16x32_bf16 v[100:103], v[178:181], v[202:205], v[100:103]
	v_mfma_f32_16x16x32_bf16 v[92:95], v[186:189], v[202:205], v[92:95]
	v_mfma_f32_16x16x32_bf16 v[84:87], v[178:181], v[210:213], v[84:87]
	v_mfma_f32_16x16x32_bf16 v[76:79], v[186:189], v[210:213], v[76:79]
	v_mfma_f32_16x16x32_bf16 v[68:71], v[178:181], v[218:221], v[68:71]
	v_mfma_f32_16x16x32_bf16 v[64:67], v[186:189], v[218:221], v[64:67]
	s_setprio 0
	s_barrier
; #define PG8_STAGE(bufoff, gbase, voff) do { _Pragma("unroll") for (int _i = 0; _i < 2; ++_i) \
;         __builtin_amdgcn_global_load_lds((const unsigned*)((const char*)(gbase) + (voff)[_i]), (PG8_LAS unsigned*)(lds + (bufoff) + ldsw + _i * 8192), 16, 0, 0); } while (0)
; #define PG8_LDA(dst, b, h) do { _Pragma("unroll") for (int m = 0; m < 4; ++m) _Pragma("unroll") for (int k = 0; k < 2; ++k) dst[m][k] = *(const PG8_LAS bf16x8*)(lds + PG8_SA(b, h) + aoff + m * 2048 + k * 1024); } while (0)
; #define PG8_MMA(ai, bj, At, Bt) do { __builtin_amdgcn_s_setprio(1); _Pragma("unroll") for (int m = 0; m < 4; ++m) _Pragma("unroll") for (int n = 0; n < 2; ++n) _Pragma("unroll") for (int k = 0; k < 2; ++k) \
;         acc[ai][bj][m][n] = __builtin_amdgcn_mfma_f32_16x16x32_bf16(Bt[n][k], At[m][k], acc[ai][bj][m][n], 0, 0, 0); __builtin_amdgcn_s_setprio(0); } while (0)
; #define PG8_WAIT_V(n) asm volatile("s_waitcnt vmcnt(" #n ")" ::: "memory")
; #define PG8_WAIT_L(n) asm volatile("s_waitcnt lgkmcnt(" #n ")" ::: "memory")
; #define PG8_BAR __builtin_amdgcn_s_barrier()
; #define PG8_SCHED __builtin_amdgcn_sched_barrier(0)
; template <class Epi, class Sched, bool ALIGN_EPI = false, bool SP2 = false>
; __device__ __forceinline__ void gemm_phase(PG8_LAS unsigned char* lds, const Gemm g, const Sched& S, const Epi& E) {
;     ...
;         for (int t = 0; t < nt; t += 2) {
;     ...
;             PG8_LDA(At, 1, 1); PG8_STAGE(PG8_SB(1, 0), b3, voffB); PG8_STAGE(PG8_SB(1, 1), b3 + hstep, voffB); PG8_STAGE(PG8_SA(1, 0), a3, voffA);
;             PG8_WAIT_V(8); PG8_WAIT_L(0); PG8_BAR; PG8_MMA(1, 0, At, B0); PG8_MMA(1, 1, At, B1); PG8_BAR; PG8_SCHED;
	s_add_i32 s8, s60, s3
	v_lshl_add_u64 v[174:175], v[174:175], 0, s[6:7]
	s_mov_b32 m0, s8
	ds_read_b128 v[190:193], v154 offset:49152
	ds_read_b128 v[194:197], v154 offset:50176
	ds_read_b128 v[198:201], v154 offset:51200
	ds_read_b128 v[202:205], v154 offset:52224
	ds_read_b128 v[206:209], v154 offset:53248
	ds_read_b128 v[210:213], v154 offset:54272
	ds_read_b128 v[214:217], v154 offset:55296
	ds_read_b128 v[218:221], v154 offset:56320
	global_load_lds_dwordx4 v[174:175], off
	s_add_i32 m0, s8, 0x2000
	s_add_u32 s8, s54, 0x40080
	v_lshl_add_u64 v[174:175], v[222:223], 0, s[6:7]
	s_addc_u32 s9, s55, 0
	s_add_i32 s54, s61, s3
	global_load_lds_dwordx4 v[174:175], off
	v_lshl_add_u64 v[174:175], s[8:9], 0, v[132:133]
	s_mov_b32 m0, s54
	s_nop 0
	global_load_lds_dwordx4 v[174:175], off
	v_lshl_add_u64 v[174:175], s[8:9], 0, v[128:129]
	s_add_i32 m0, s54, 0x2000
	s_nop 0
	global_load_lds_dwordx4 v[174:175], off
	v_lshl_add_u64 v[174:175], v[224:225], 0, s[6:7]
	s_mov_b32 m0, s72
	s_nop 0
	global_load_lds_dwordx4 v[174:175], off
	v_lshl_add_u64 v[174:175], v[226:227], 0, s[6:7]
	s_mov_b32 m0, s73
	s_nop 0
	global_load_lds_dwordx4 v[174:175], off
	s_waitcnt vmcnt(8)
	s_waitcnt lgkmcnt(0)
	s_barrier
	s_setprio 1
	s_waitcnt lgkmcnt(0)
	v_mfma_f32_16x16x32_bf16 v[60:63], v[146:149], v[190:193], v[60:63]
	v_mfma_f32_16x16x32_bf16 v[56:59], v[162:165], v[190:193], v[56:59]
	v_mfma_f32_16x16x32_bf16 v[48:51], v[146:149], v[198:201], v[48:51]
	v_mfma_f32_16x16x32_bf16 v[40:43], v[162:165], v[198:201], v[40:43]
	v_mfma_f32_16x16x32_bf16 v[32:35], v[146:149], v[206:209], v[32:35]
	v_mfma_f32_16x16x32_bf16 v[24:27], v[162:165], v[206:209], v[24:27]
	v_mfma_f32_16x16x32_bf16 v[16:19], v[146:149], v[214:217], v[16:19]
	v_mfma_f32_16x16x32_bf16 v[8:11], v[162:165], v[214:217], v[8:11]
	v_mfma_f32_16x16x32_bf16 v[60:63], v[156:159], v[194:197], v[60:63]
	v_mfma_f32_16x16x32_bf16 v[56:59], v[166:169], v[194:197], v[56:59]
	v_mfma_f32_16x16x32_bf16 v[48:51], v[156:159], v[202:205], v[48:51]
	v_mfma_f32_16x16x32_bf16 v[40:43], v[166:169], v[202:205], v[40:43]
	v_mfma_f32_16x16x32_bf16 v[32:35], v[156:159], v[210:213], v[32:35]
	v_mfma_f32_16x16x32_bf16 v[24:27], v[166:169], v[210:213], v[24:27]
	v_mfma_f32_16x16x32_bf16 v[16:19], v[156:159], v[218:221], v[16:19]
	v_mfma_f32_16x16x32_bf16 v[8:11], v[166:169], v[218:221], v[8:11]
	s_setprio 0
	s_setprio 1
	v_mfma_f32_16x16x32_bf16 v[52:55], v[170:173], v[190:193], v[52:55]
	v_mfma_f32_16x16x32_bf16 v[44:47], v[182:185], v[190:193], v[44:47]
	v_mfma_f32_16x16x32_bf16 v[36:39], v[170:173], v[198:201], v[36:39]
	v_mfma_f32_16x16x32_bf16 v[28:31], v[182:185], v[198:201], v[28:31]
	v_mfma_f32_16x16x32_bf16 v[20:23], v[170:173], v[206:209], v[20:23]
	v_mfma_f32_16x16x32_bf16 v[12:15], v[182:185], v[206:209], v[12:15]
	v_mfma_f32_16x16x32_bf16 v[4:7], v[170:173], v[214:217], v[4:7]
	v_mfma_f32_16x16x32_bf16 v[0:3], v[182:185], v[214:217], v[0:3]
	v_mfma_f32_16x16x32_bf16 v[52:55], v[178:181], v[194:197], v[52:55]
	v_mfma_f32_16x16x32_bf16 v[44:47], v[186:189], v[194:197], v[44:47]
	v_mfma_f32_16x16x32_bf16 v[36:39], v[178:181], v[202:205], v[36:39]
	v_mfma_f32_16x16x32_bf16 v[28:31], v[186:189], v[202:205], v[28:31]
	v_mfma_f32_16x16x32_bf16 v[20:23], v[178:181], v[210:213], v[20:23]
	v_mfma_f32_16x16x32_bf16 v[12:15], v[186:189], v[210:213], v[12:15]
	v_mfma_f32_16x16x32_bf16 v[4:7], v[178:181], v[218:221], v[4:7]
	v_mfma_f32_16x16x32_bf16 v[0:3], v[186:189], v[218:221], v[0:3]
	s_setprio 0
	s_add_i32 s86, s86, 2
	s_add_u32 s52, s52, 0x100
	s_addc_u32 s53, s53, 0
	s_add_u32 s82, s82, 0x100
	s_addc_u32 s83, s83, 0
	s_cmp_gt_u32 s86, 13
	s_barrier
	s_cbranch_scc0 .LBB0_179
	s_and_b64 vcc, exec, s[16:17]
	s_cbranch_vccz .LBB0_182
	s_barrier

; #define PG8_STAGE(bufoff, gbase, voff) do { _Pragma("unroll") for (int _i = 0; _i < 2; ++_i) \
;         __builtin_amdgcn_global_load_lds((const unsigned*)((const char*)(gbase) + (voff)[_i]), (PG8_LAS unsigned*)(lds + (bufoff) + ldsw + _i * 8192), 16, 0, 0); } while (0)
; #define PG8_LDA(dst, b, h) do { _Pragma("unroll") for (int m = 0; m < 4; ++m) _Pragma("unroll") for (int k = 0; k < 2; ++k) dst[m][k] = *(const PG8_LAS bf16x8*)(lds + PG8_SA(b, h) + aoff + m * 2048 + k * 1024); } while (0)
; #define PG8_LDB(dst, b, h) do { _Pragma("unroll") for (int n = 0; n < 2; ++n) _Pragma("unroll") for (int k = 0; k < 2; ++k) dst[n][k] = *(const PG8_LAS bf16x8*)(lds + PG8_SB(b, h) + boff + n * 2048 + k * 1024); } while (0)
; #define PG8_MMA(ai, bj, At, Bt) do { __builtin_amdgcn_s_setprio(1); _Pragma("unroll") for (int m = 0; m < 4; ++m) _Pragma("unroll") for (int n = 0; n < 2; ++n) _Pragma("unroll") for (int k = 0; k < 2; ++k) \
;         acc[ai][bj][m][n] = __builtin_amdgcn_mfma_f32_16x16x32_bf16(Bt[n][k], At[m][k], acc[ai][bj][m][n], 0, 0, 0); __builtin_amdgcn_s_setprio(0); } while (0)
; #define PG8_WAIT_V(n) asm volatile("s_waitcnt vmcnt(" #n ")" ::: "memory")
; #define PG8_WAIT_L(n) asm volatile("s_waitcnt lgkmcnt(" #n ")" ::: "memory")
; #define PG8_BAR __builtin_amdgcn_s_barrier()
; #define PG8_SCHED __builtin_amdgcn_sched_barrier(0)
; template <class Epi, class Sched, bool ALIGN_EPI = false, bool SP2 = false>
; __device__ __forceinline__ void gemm_phase(PG8_LAS unsigned char* lds, const Gemm g, const Sched& S, const Epi& E) {
;     ...
;             const bool last = (t == nt - 2);
;             const char* a1 = cA + (size_t)(t + 1) * kstep;
;             const char* a2 = last ? nA : cA + (size_t)(t + 2) * kstep; const char* b2 = last ? nB : cB + (size_t)(t + 2) * kstep;
;             const char* a3 = a2 + kstep; const char* b3 = b2 + kstep;
;             if (last && has_next) S.a_ready(nxt);
;             if constexpr (SP2) {
;             PG8_LDB(B0, 0, 0); PG8_LDB(B1, 0, 1); PG8_SCHED; PG8_LDA(At, 0, 0); PG8_STAGE(PG8_SA(1, 1), a1 + hstep, voffA);
;             PG8_WAIT_V(8); PG8_WAIT_L(0); PG8_BAR; PG8_MMA(0, 0, At, B0); PG8_MMA(0, 1, At, B1); PG8_BAR; PG8_SCHED;
;             PG8_LDA(At, 0, 1); PG8_STAGE(PG8_SB(0, 0), b2, voffB); PG8_STAGE(PG8_SB(0, 1), b2 + hstep, voffB); PG8_STAGE(PG8_SA(0, 0), a2, voffA);
.LBB0_375:
	ds_read_b128 v[154:157], v150
	ds_read_b128 v[162:165], v150 offset:1024
	ds_read_b128 v[166:169], v150 offset:2048
	ds_read_b128 v[170:173], v150 offset:3072
	ds_read_b128 v[178:181], v151
	ds_read_b128 v[182:185], v151 offset:1024
	ds_read_b128 v[186:189], v151 offset:2048
	ds_read_b128 v[190:193], v151 offset:3072
	s_add_u32 s8, s68, 0xfffc0080
	s_addc_u32 s9, s69, -1
	s_cmp_eq_u32 s97, 12
	s_cselect_b32 s73, s53, s9
	s_cselect_b32 s72, s93, s8
	s_cselect_b32 s71, s51, s96
	s_cselect_b32 s70, s94, s95
	v_lshl_add_u64 v[146:147], s[68:69], 0, v[136:137]
	s_add_i32 m0, s67, 0xc000
	ds_read_b128 v[194:197], v152
	ds_read_b128 v[198:201], v152 offset:1024
	ds_read_b128 v[202:205], v152 offset:2048
	ds_read_b128 v[206:209], v152 offset:3072
	ds_read_b128 v[210:213], v152 offset:4096
	ds_read_b128 v[214:217], v152 offset:5120
	ds_read_b128 v[218:221], v152 offset:6144
	ds_read_b128 v[222:225], v152 offset:7168
	global_load_lds_dwordx4 v[146:147], off
	v_lshl_add_u64 v[146:147], s[68:69], 0, v[138:139]
	s_add_i32 m0, s67, 0xe000
	s_nop 0
	global_load_lds_dwordx4 v[146:147], off
	s_waitcnt vmcnt(8)
	s_waitcnt lgkmcnt(0)
	s_barrier
	s_setprio 1
	s_waitcnt lgkmcnt(0)
	v_mfma_f32_16x16x32_bf16 v[124:127], v[154:157], v[194:197], v[124:127]
	v_mfma_f32_16x16x32_bf16 v[120:123], v[166:169], v[194:197], v[120:123]
	v_mfma_f32_16x16x32_bf16 v[112:115], v[154:157], v[202:205], v[112:115]
	v_mfma_f32_16x16x32_bf16 v[104:107], v[166:169], v[202:205], v[104:107]
	v_mfma_f32_16x16x32_bf16 v[96:99], v[154:157], v[210:213], v[96:99]
	v_mfma_f32_16x16x32_bf16 v[88:91], v[166:169], v[210:213], v[88:91]
	v_mfma_f32_16x16x32_bf16 v[80:83], v[154:157], v[218:221], v[80:83]
	v_mfma_f32_16x16x32_bf16 v[72:75], v[166:169], v[218:221], v[72:75]
	v_mfma_f32_16x16x32_bf16 v[124:127], v[162:165], v[198:201], v[124:127]
	v_mfma_f32_16x16x32_bf16 v[120:123], v[170:173], v[198:201], v[120:123]
	v_mfma_f32_16x16x32_bf16 v[112:115], v[162:165], v[206:209], v[112:115]
	v_mfma_f32_16x16x32_bf16 v[104:107], v[170:173], v[206:209], v[104:107]
	v_mfma_f32_16x16x32_bf16 v[96:99], v[162:165], v[214:217], v[96:99]
	v_mfma_f32_16x16x32_bf16 v[88:91], v[170:173], v[214:217], v[88:91]
	v_mfma_f32_16x16x32_bf16 v[80:83], v[162:165], v[222:225], v[80:83]
	v_mfma_f32_16x16x32_bf16 v[72:75], v[170:173], v[222:225], v[72:75]
	s_setprio 0
	s_setprio 1
	v_mfma_f32_16x16x32_bf16 v[116:119], v[178:181], v[194:197], v[116:119]
	v_mfma_f32_16x16x32_bf16 v[108:111], v[186:189], v[194:197], v[108:111]
	v_mfma_f32_16x16x32_bf16 v[100:103], v[178:181], v[202:205], v[100:103]
	v_mfma_f32_16x16x32_bf16 v[92:95], v[186:189], v[202:205], v[92:95]
	v_mfma_f32_16x16x32_bf16 v[84:87], v[178:181], v[210:213], v[84:87]
	v_mfma_f32_16x16x32_bf16 v[76:79], v[186:189], v[210:213], v[76:79]
	v_mfma_f32_16x16x32_bf16 v[68:71], v[178:181], v[218:221], v[68:71]
	v_mfma_f32_16x16x32_bf16 v[64:67], v[186:189], v[218:221], v[64:67]
	v_mfma_f32_16x16x32_bf16 v[116:119], v[182:185], v[198:201], v[116:119]
	v_mfma_f32_16x16x32_bf16 v[108:111], v[190:193], v[198:201], v[108:111]
	v_mfma_f32_16x16x32_bf16 v[100:103], v[182:185], v[206:209], v[100:103]
	v_mfma_f32_16x16x32_bf16 v[92:95], v[190:193], v[206:209], v[92:95]
	v_mfma_f32_16x16x32_bf16 v[84:87], v[182:185], v[214:217], v[84:87]
	v_mfma_f32_16x16x32_bf16 v[76:79], v[190:193], v[214:217], v[76:79]
	v_mfma_f32_16x16x32_bf16 v[68:71], v[182:185], v[222:225], v[68:71]
	v_mfma_f32_16x16x32_bf16 v[64:67], v[190:193], v[222:225], v[64:67]
	s_setprio 0
	s_barrier
	s_add_i32 s8, s86, s75
	v_lshl_add_u64 v[146:147], s[70:71], 0, v[130:131]
	s_mov_b32 m0, s8
	ds_read_b128 v[194:197], v152 offset:16384
	ds_read_b128 v[198:201], v152 offset:17408
	ds_read_b128 v[202:205], v152 offset:18432
	ds_read_b128 v[206:209], v152 offset:19456
	ds_read_b128 v[210:213], v152 offset:20480
	ds_read_b128 v[214:217], v152 offset:21504
	ds_read_b128 v[218:221], v152 offset:22528
	ds_read_b128 v[222:225], v152 offset:23552
	global_load_lds_dwordx4 v[146:147], off
	s_add_i32 m0, s8, 0x2000
	s_add_u32 s8, s70, 0x40000
	v_lshl_add_u64 v[158:159], s[70:71], 0, v[134:135]
	s_addc_u32 s9, s71, 0
	s_add_i32 s60, s87, s75
	global_load_lds_dwordx4 v[158:159], off
	v_lshl_add_u64 v[174:175], s[8:9], 0, v[130:131]
	s_mov_b32 m0, s60
	v_lshl_add_u64 v[226:227], s[72:73], 0, v[132:133]
	global_load_lds_dwordx4 v[174:175], off
	v_lshl_add_u64 v[174:175], s[8:9], 0, v[134:135]
	s_add_i32 m0, s60, 0x2000
	s_nop 0
	global_load_lds_dwordx4 v[174:175], off
	v_lshl_add_u64 v[174:175], s[72:73], 0, v[128:129]
	s_mov_b32 m0, s67
	s_nop 0
	global_load_lds_dwordx4 v[174:175], off
	s_mov_b32 m0, s76
	s_nop 0
	global_load_lds_dwordx4 v[226:227], off
	s_waitcnt vmcnt(8)
	s_waitcnt lgkmcnt(0)
	s_barrier
; #define PG8_STAGE(bufoff, gbase, voff) do { _Pragma("unroll") for (int _i = 0; _i < 2; ++_i) \
;         __builtin_amdgcn_global_load_lds((const unsigned*)((const char*)(gbase) + (voff)[_i]), (PG8_LAS unsigned*)(lds + (bufoff) + ldsw + _i * 8192), 16, 0, 0); } while (0)
; #define PG8_LDA(dst, b, h) do { _Pragma("unroll") for (int m = 0; m < 4; ++m) _Pragma("unroll") for (int k = 0; k < 2; ++k) dst[m][k] = *(const PG8_LAS bf16x8*)(lds + PG8_SA(b, h) + aoff + m * 2048 + k * 1024); } while (0)
; #define PG8_LDB(dst, b, h) do { _Pragma("unroll") for (int n = 0; n < 2; ++n) _Pragma("unroll") for (int k = 0; k < 2; ++k) dst[n][k] = *(const PG8_LAS bf16x8*)(lds + PG8_SB(b, h) + boff + n * 2048 + k * 1024); } while (0)
; #define PG8_MMA(ai, bj, At, Bt) do { __builtin_amdgcn_s_setprio(1); _Pragma("unroll") for (int m = 0; m < 4; ++m) _Pragma("unroll") for (int n = 0; n < 2; ++n) _Pragma("unroll") for (int k = 0; k < 2; ++k) \
;         acc[ai][bj][m][n] = __builtin_amdgcn_mfma_f32_16x16x32_bf16(Bt[n][k], At[m][k], acc[ai][bj][m][n], 0, 0, 0); __builtin_amdgcn_s_setprio(0); } while (0)
; #define PG8_WAIT_V(n) asm volatile("s_waitcnt vmcnt(" #n ")" ::: "memory")
; #define PG8_WAIT_L(n) asm volatile("s_waitcnt lgkmcnt(" #n ")" ::: "memory")
; #define PG8_BAR __builtin_amdgcn_s_barrier()
; #define PG8_SCHED __builtin_amdgcn_sched_barrier(0)
; template <class Epi, class Sched, bool ALIGN_EPI = false, bool SP2 = false>
; __device__ __forceinline__ void gemm_phase(PG8_LAS unsigned char* lds, const Gemm g, const Sched& S, const Epi& E) {
;     ...
;             PG8_WAIT_V(8); PG8_WAIT_L(0); PG8_BAR; PG8_MMA(1, 0, At, B0); PG8_MMA(1, 1, At, B1); PG8_BAR; PG8_SCHED;
;             PG8_LDB(B0, 1, 0); PG8_LDB(B1, 1, 1); PG8_SCHED; PG8_LDA(At, 1, 0); PG8_STAGE(PG8_SA(0, 1), a2 + hstep, voffA);
;             PG8_WAIT_V(8); PG8_WAIT_L(0); PG8_BAR; PG8_MMA(0, 0, At, B0); PG8_MMA(0, 1, At, B1); PG8_BAR; PG8_SCHED;
	s_setprio 1
	s_waitcnt lgkmcnt(0)
	v_mfma_f32_16x16x32_bf16 v[60:63], v[154:157], v[194:197], v[60:63]
	v_mfma_f32_16x16x32_bf16 v[56:59], v[166:169], v[194:197], v[56:59]
	v_mfma_f32_16x16x32_bf16 v[48:51], v[154:157], v[202:205], v[48:51]
	v_mfma_f32_16x16x32_bf16 v[40:43], v[166:169], v[202:205], v[40:43]
	v_mfma_f32_16x16x32_bf16 v[32:35], v[154:157], v[210:213], v[32:35]
	v_mfma_f32_16x16x32_bf16 v[24:27], v[166:169], v[210:213], v[24:27]
	v_mfma_f32_16x16x32_bf16 v[16:19], v[154:157], v[218:221], v[16:19]
	v_mfma_f32_16x16x32_bf16 v[8:11], v[166:169], v[218:221], v[8:11]
	v_mfma_f32_16x16x32_bf16 v[60:63], v[162:165], v[198:201], v[60:63]
	v_mfma_f32_16x16x32_bf16 v[56:59], v[170:173], v[198:201], v[56:59]
	v_mfma_f32_16x16x32_bf16 v[48:51], v[162:165], v[206:209], v[48:51]
	v_mfma_f32_16x16x32_bf16 v[40:43], v[170:173], v[206:209], v[40:43]
	v_mfma_f32_16x16x32_bf16 v[32:35], v[162:165], v[214:217], v[32:35]
	v_mfma_f32_16x16x32_bf16 v[24:27], v[170:173], v[214:217], v[24:27]
	v_mfma_f32_16x16x32_bf16 v[16:19], v[162:165], v[222:225], v[16:19]
	v_mfma_f32_16x16x32_bf16 v[8:11], v[170:173], v[222:225], v[8:11]
	s_setprio 0
	s_setprio 1
	v_mfma_f32_16x16x32_bf16 v[52:55], v[178:181], v[194:197], v[52:55]
	v_mfma_f32_16x16x32_bf16 v[44:47], v[186:189], v[194:197], v[44:47]
	v_mfma_f32_16x16x32_bf16 v[36:39], v[178:181], v[202:205], v[36:39]
	v_mfma_f32_16x16x32_bf16 v[28:31], v[186:189], v[202:205], v[28:31]
	v_mfma_f32_16x16x32_bf16 v[20:23], v[178:181], v[210:213], v[20:23]
	v_mfma_f32_16x16x32_bf16 v[12:15], v[186:189], v[210:213], v[12:15]
	v_mfma_f32_16x16x32_bf16 v[4:7], v[178:181], v[218:221], v[4:7]
	v_mfma_f32_16x16x32_bf16 v[0:3], v[186:189], v[218:221], v[0:3]
	v_mfma_f32_16x16x32_bf16 v[52:55], v[182:185], v[198:201], v[52:55]
	v_mfma_f32_16x16x32_bf16 v[44:47], v[190:193], v[198:201], v[44:47]
	v_mfma_f32_16x16x32_bf16 v[36:39], v[182:185], v[206:209], v[36:39]
	v_mfma_f32_16x16x32_bf16 v[28:31], v[190:193], v[206:209], v[28:31]
	v_mfma_f32_16x16x32_bf16 v[20:23], v[182:185], v[214:217], v[20:23]
	v_mfma_f32_16x16x32_bf16 v[12:15], v[190:193], v[214:217], v[12:15]
	v_mfma_f32_16x16x32_bf16 v[4:7], v[182:185], v[222:225], v[4:7]
	v_mfma_f32_16x16x32_bf16 v[0:3], v[190:193], v[222:225], v[0:3]
	s_setprio 0
	s_barrier
	s_add_i32 s60, 0, 0x18000
	v_add_u32_e32 v144, s60, v148
	s_add_i32 s61, 0, 0x1c000
	ds_read_b128 v[154:157], v144
	ds_read_b128 v[162:165], v144 offset:1024
	ds_read_b128 v[166:169], v144 offset:2048
	ds_read_b128 v[170:173], v144 offset:3072
	v_add_u32_e32 v144, s61, v148
	ds_read_b128 v[178:181], v144
	ds_read_b128 v[182:185], v144 offset:1024
	ds_read_b128 v[186:189], v144 offset:2048
	ds_read_b128 v[190:193], v144 offset:3072
	s_add_u32 s8, s72, 0x40000
	s_addc_u32 s9, s73, 0
	s_mov_b32 m0, s77
	v_lshl_add_u64 v[228:229], s[8:9], 0, v[128:129]
	ds_read_b128 v[194:197], v152 offset:32768
	ds_read_b128 v[198:201], v152 offset:33792
	ds_read_b128 v[202:205], v152 offset:34816
	ds_read_b128 v[206:209], v152 offset:35840
	ds_read_b128 v[210:213], v152 offset:36864
	ds_read_b128 v[214:217], v152 offset:37888
	ds_read_b128 v[218:221], v152 offset:38912
	ds_read_b128 v[222:225], v152 offset:39936
	global_load_lds_dwordx4 v[228:229], off
	v_lshl_add_u64 v[228:229], s[8:9], 0, v[132:133]
	s_mov_b32 m0, s78
	s_nop 0
	global_load_lds_dwordx4 v[228:229], off
	s_waitcnt vmcnt(8)
	s_waitcnt lgkmcnt(0)
	s_barrier
	s_setprio 1
	s_waitcnt lgkmcnt(0)
	v_mfma_f32_16x16x32_bf16 v[124:127], v[154:157], v[194:197], v[124:127]
	v_mfma_f32_16x16x32_bf16 v[120:123], v[166:169], v[194:197], v[120:123]
	v_mfma_f32_16x16x32_bf16 v[112:115], v[154:157], v[202:205], v[112:115]
	v_mfma_f32_16x16x32_bf16 v[104:107], v[166:169], v[202:205], v[104:107]
	v_mfma_f32_16x16x32_bf16 v[96:99], v[154:157], v[210:213], v[96:99]
	v_mfma_f32_16x16x32_bf16 v[88:91], v[166:169], v[210:213], v[88:91]
	v_mfma_f32_16x16x32_bf16 v[80:83], v[154:157], v[218:221], v[80:83]
	v_mfma_f32_16x16x32_bf16 v[72:75], v[166:169], v[218:221], v[72:75]
	v_mfma_f32_16x16x32_bf16 v[124:127], v[162:165], v[198:201], v[124:127]
	v_mfma_f32_16x16x32_bf16 v[120:123], v[170:173], v[198:201], v[120:123]
	v_mfma_f32_16x16x32_bf16 v[112:115], v[162:165], v[206:209], v[112:115]
	v_mfma_f32_16x16x32_bf16 v[104:107], v[170:173], v[206:209], v[104:107]
	v_mfma_f32_16x16x32_bf16 v[96:99], v[162:165], v[214:217], v[96:99]
	v_mfma_f32_16x16x32_bf16 v[88:91], v[170:173], v[214:217], v[88:91]
	v_mfma_f32_16x16x32_bf16 v[80:83], v[162:165], v[222:225], v[80:83]
	v_mfma_f32_16x16x32_bf16 v[72:75], v[170:173], v[222:225], v[72:75]
	s_setprio 0
	s_setprio 1
	v_mfma_f32_16x16x32_bf16 v[116:119], v[178:181], v[194:197], v[116:119]
	v_mfma_f32_16x16x32_bf16 v[108:111], v[186:189], v[194:197], v[108:111]
	v_mfma_f32_16x16x32_bf16 v[100:103], v[178:181], v[202:205], v[100:103]
	v_mfma_f32_16x16x32_bf16 v[92:95], v[186:189], v[202:205], v[92:95]
	v_mfma_f32_16x16x32_bf16 v[84:87], v[178:181], v[210:213], v[84:87]
	v_mfma_f32_16x16x32_bf16 v[76:79], v[186:189], v[210:213], v[76:79]
	v_mfma_f32_16x16x32_bf16 v[68:71], v[178:181], v[218:221], v[68:71]
	v_mfma_f32_16x16x32_bf16 v[64:67], v[186:189], v[218:221], v[64:67]
	v_mfma_f32_16x16x32_bf16 v[116:119], v[182:185], v[198:201], v[116:119]
	v_mfma_f32_16x16x32_bf16 v[108:111], v[190:193], v[198:201], v[108:111]
	v_mfma_f32_16x16x32_bf16 v[100:103], v[182:185], v[206:209], v[100:103]
	v_mfma_f32_16x16x32_bf16 v[92:95], v[190:193], v[206:209], v[92:95]
	v_mfma_f32_16x16x32_bf16 v[84:87], v[182:185], v[214:217], v[84:87]
	v_mfma_f32_16x16x32_bf16 v[76:79], v[190:193], v[214:217], v[76:79]
	v_mfma_f32_16x16x32_bf16 v[68:71], v[182:185], v[222:225], v[68:71]
	v_mfma_f32_16x16x32_bf16 v[64:67], v[190:193], v[222:225], v[64:67]
	s_setprio 0
	s_barrier
; #define PG8_STAGE(bufoff, gbase, voff) do { _Pragma("unroll") for (int _i = 0; _i < 2; ++_i) \
;         __builtin_amdgcn_global_load_lds((const unsigned*)((const char*)(gbase) + (voff)[_i]), (PG8_LAS unsigned*)(lds + (bufoff) + ldsw + _i * 8192), 16, 0, 0); } while (0)
; #define PG8_LDA(dst, b, h) do { _Pragma("unroll") for (int m = 0; m < 4; ++m) _Pragma("unroll") for (int k = 0; k < 2; ++k) dst[m][k] = *(const PG8_LAS bf16x8*)(lds + PG8_SA(b, h) + aoff + m * 2048 + k * 1024); } while (0)
; #define PG8_MMA(ai, bj, At, Bt) do { __builtin_amdgcn_s_setprio(1); _Pragma("unroll") for (int m = 0; m < 4; ++m) _Pragma("unroll") for (int n = 0; n < 2; ++n) _Pragma("unroll") for (int k = 0; k < 2; ++k) \
;         acc[ai][bj][m][n] = __builtin_amdgcn_mfma_f32_16x16x32_bf16(Bt[n][k], At[m][k], acc[ai][bj][m][n], 0, 0, 0); __builtin_amdgcn_s_setprio(0); } while (0)
; #define PG8_WAIT_V(n) asm volatile("s_waitcnt vmcnt(" #n ")" ::: "memory")
; #define PG8_WAIT_L(n) asm volatile("s_waitcnt lgkmcnt(" #n ")" ::: "memory")
; #define PG8_BAR __builtin_amdgcn_s_barrier()
; #define PG8_SCHED __builtin_amdgcn_sched_barrier(0)
; template <class Epi, class Sched, bool ALIGN_EPI = false, bool SP2 = false>
; __device__ __forceinline__ void gemm_phase(PG8_LAS unsigned char* lds, const Gemm g, const Sched& S, const Epi& E) {
;     ...
;         for (int t = 0; t < nt; t += 2) {
;     ...
;             PG8_LDA(At, 1, 1); PG8_STAGE(PG8_SB(1, 0), b3, voffB); PG8_STAGE(PG8_SB(1, 1), b3 + hstep, voffB); PG8_STAGE(PG8_SA(1, 0), a3, voffA);
;             PG8_WAIT_V(8); PG8_WAIT_L(0); PG8_BAR; PG8_MMA(1, 0, At, B0); PG8_MMA(1, 1, At, B1); PG8_BAR; PG8_SCHED;
	s_add_i32 s8, s60, s75
	v_lshl_add_u64 v[146:147], v[146:147], 0, s[16:17]
	s_mov_b32 m0, s8
	ds_read_b128 v[194:197], v152 offset:49152
	ds_read_b128 v[198:201], v152 offset:50176
	ds_read_b128 v[202:205], v152 offset:51200
	ds_read_b128 v[206:209], v152 offset:52224
	ds_read_b128 v[210:213], v152 offset:53248
	ds_read_b128 v[214:217], v152 offset:54272
	ds_read_b128 v[218:221], v152 offset:55296
	ds_read_b128 v[222:225], v152 offset:56320
	global_load_lds_dwordx4 v[146:147], off
	s_add_i32 m0, s8, 0x2000
	s_add_u32 s8, s70, 0x40080
	v_lshl_add_u64 v[146:147], v[158:159], 0, s[16:17]
	s_addc_u32 s9, s71, 0
	s_add_i32 s60, s61, s75
	global_load_lds_dwordx4 v[146:147], off
	v_lshl_add_u64 v[146:147], s[8:9], 0, v[130:131]
	s_mov_b32 m0, s60
	s_nop 0
	global_load_lds_dwordx4 v[146:147], off
	v_lshl_add_u64 v[146:147], s[8:9], 0, v[134:135]
	s_add_i32 m0, s60, 0x2000
	s_nop 0
	global_load_lds_dwordx4 v[146:147], off
	v_lshl_add_u64 v[146:147], v[174:175], 0, s[16:17]
	s_mov_b32 m0, s80
	s_nop 0
	global_load_lds_dwordx4 v[146:147], off
	v_lshl_add_u64 v[146:147], v[226:227], 0, s[16:17]
	s_mov_b32 m0, s81
	s_nop 0
	global_load_lds_dwordx4 v[146:147], off
	s_waitcnt vmcnt(8)
	s_waitcnt lgkmcnt(0)
	s_barrier
	s_setprio 1
	s_waitcnt lgkmcnt(0)
	v_mfma_f32_16x16x32_bf16 v[60:63], v[154:157], v[194:197], v[60:63]
	v_mfma_f32_16x16x32_bf16 v[56:59], v[166:169], v[194:197], v[56:59]
	v_mfma_f32_16x16x32_bf16 v[48:51], v[154:157], v[202:205], v[48:51]
	v_mfma_f32_16x16x32_bf16 v[40:43], v[166:169], v[202:205], v[40:43]
	v_mfma_f32_16x16x32_bf16 v[32:35], v[154:157], v[210:213], v[32:35]
	v_mfma_f32_16x16x32_bf16 v[24:27], v[166:169], v[210:213], v[24:27]
	v_mfma_f32_16x16x32_bf16 v[16:19], v[154:157], v[218:221], v[16:19]
	v_mfma_f32_16x16x32_bf16 v[8:11], v[166:169], v[218:221], v[8:11]
	v_mfma_f32_16x16x32_bf16 v[60:63], v[162:165], v[198:201], v[60:63]
	v_mfma_f32_16x16x32_bf16 v[56:59], v[170:173], v[198:201], v[56:59]
	v_mfma_f32_16x16x32_bf16 v[48:51], v[162:165], v[206:209], v[48:51]
	v_mfma_f32_16x16x32_bf16 v[40:43], v[170:173], v[206:209], v[40:43]
	v_mfma_f32_16x16x32_bf16 v[32:35], v[162:165], v[214:217], v[32:35]
	v_mfma_f32_16x16x32_bf16 v[24:27], v[170:173], v[214:217], v[24:27]
	v_mfma_f32_16x16x32_bf16 v[16:19], v[162:165], v[222:225], v[16:19]
	v_mfma_f32_16x16x32_bf16 v[8:11], v[170:173], v[222:225], v[8:11]
	s_setprio 0
	s_setprio 1
	v_mfma_f32_16x16x32_bf16 v[52:55], v[178:181], v[194:197], v[52:55]
	v_mfma_f32_16x16x32_bf16 v[44:47], v[186:189], v[194:197], v[44:47]
	v_mfma_f32_16x16x32_bf16 v[36:39], v[178:181], v[202:205], v[36:39]
	v_mfma_f32_16x16x32_bf16 v[28:31], v[186:189], v[202:205], v[28:31]
	v_mfma_f32_16x16x32_bf16 v[20:23], v[178:181], v[210:213], v[20:23]
	v_mfma_f32_16x16x32_bf16 v[12:15], v[186:189], v[210:213], v[12:15]
	v_mfma_f32_16x16x32_bf16 v[4:7], v[178:181], v[218:221], v[4:7]
	v_mfma_f32_16x16x32_bf16 v[0:3], v[186:189], v[218:221], v[0:3]
	v_mfma_f32_16x16x32_bf16 v[52:55], v[182:185], v[198:201], v[52:55]
	v_mfma_f32_16x16x32_bf16 v[44:47], v[190:193], v[198:201], v[44:47]
	v_mfma_f32_16x16x32_bf16 v[36:39], v[182:185], v[206:209], v[36:39]
	v_mfma_f32_16x16x32_bf16 v[28:31], v[190:193], v[206:209], v[28:31]
	v_mfma_f32_16x16x32_bf16 v[20:23], v[182:185], v[214:217], v[20:23]
	v_mfma_f32_16x16x32_bf16 v[12:15], v[190:193], v[214:217], v[12:15]
	v_mfma_f32_16x16x32_bf16 v[4:7], v[182:185], v[222:225], v[4:7]
	v_mfma_f32_16x16x32_bf16 v[0:3], v[190:193], v[222:225], v[0:3]
	s_setprio 0
	s_add_i32 s97, s97, 2
	s_add_u32 s68, s68, 0x100
	s_addc_u32 s69, s69, 0
	s_add_u32 s95, s95, 0x100
	s_addc_u32 s96, s96, 0
	s_cmp_gt_u32 s97, 13
	s_barrier
	s_cbranch_scc0 .LBB0_375
	s_and_b64 vcc, exec, s[18:19]
	s_cbranch_vccz .LBB0_378
	s_barrier

; #define PG8_STAGE(bufoff, gbase, voff) do { _Pragma("unroll") for (int _i = 0; _i < 2; ++_i) \
;         __builtin_amdgcn_global_load_lds((const unsigned*)((const char*)(gbase) + (voff)[_i]), (PG8_LAS unsigned*)(lds + (bufoff) + ldsw + _i * 8192), 16, 0, 0); } while (0)
; #define PG8_LDA(dst, b, h) do { _Pragma("unroll") for (int m = 0; m < 4; ++m) _Pragma("unroll") for (int k = 0; k < 2; ++k) dst[m][k] = *(const PG8_LAS bf16x8*)(lds + PG8_SA(b, h) + aoff + m * 2048 + k * 1024); } while (0)
; #define PG8_LDB(dst, b, h) do { _Pragma("unroll") for (int n = 0; n < 2; ++n) _Pragma("unroll") for (int k = 0; k < 2; ++k) dst[n][k] = *(const PG8_LAS bf16x8*)(lds + PG8_SB(b, h) + boff + n * 2048 + k * 1024); } while (0)
; #define PG8_MMA(ai, bj, At, Bt) do { __builtin_amdgcn_s_setprio(1); _Pragma("unroll") for (int m = 0; m < 4; ++m) _Pragma("unroll") for (int n = 0; n < 2; ++n) _Pragma("unroll") for (int k = 0; k < 2; ++k) \
;         acc[ai][bj][m][n] = __builtin_amdgcn_mfma_f32_16x16x32_bf16(Bt[n][k], At[m][k], acc[ai][bj][m][n], 0, 0, 0); __builtin_amdgcn_s_setprio(0); } while (0)
; #define PG8_WAIT_V(n) asm volatile("s_waitcnt vmcnt(" #n ")" ::: "memory")
; #define PG8_WAIT_L(n) asm volatile("s_waitcnt lgkmcnt(" #n ")" ::: "memory")
; #define PG8_BAR __builtin_amdgcn_s_barrier()
; #define PG8_SCHED __builtin_amdgcn_sched_barrier(0)
; template <class Epi, class Sched, bool ALIGN_EPI = false, bool SP2 = false>
; __device__ __forceinline__ void gemm_phase(PG8_LAS unsigned char* lds, const Gemm g, const Sched& S, const Epi& E) {
;     ...
;             const bool last = (t == nt - 2);
;             const char* a1 = cA + (size_t)(t + 1) * kstep;
;             const char* a2 = last ? nA : cA + (size_t)(t + 2) * kstep; const char* b2 = last ? nB : cB + (size_t)(t + 2) * kstep;
;             const char* a3 = a2 + kstep; const char* b3 = b2 + kstep;
;             if (last && has_next) S.a_ready(nxt);
;             if constexpr (SP2) {
;             PG8_LDB(B0, 0, 0); PG8_LDB(B1, 0, 1); PG8_SCHED; PG8_LDA(At, 0, 0); PG8_STAGE(PG8_SA(1, 1), a1 + hstep, voffA);
;             PG8_WAIT_V(8); PG8_WAIT_L(0); PG8_BAR; PG8_MMA(0, 0, At, B0); PG8_MMA(0, 1, At, B1); PG8_BAR; PG8_SCHED;
;             PG8_LDA(At, 0, 1); PG8_STAGE(PG8_SB(0, 0), b2, voffB); PG8_STAGE(PG8_SB(0, 1), b2 + hstep, voffB); PG8_STAGE(PG8_SA(0, 0), a2, voffA);
.LBB0_557:
	ds_read_b128 v[152:155], v149
	ds_read_b128 v[156:159], v149 offset:1024
	ds_read_b128 v[162:165], v149 offset:2048
	ds_read_b128 v[166:169], v149 offset:3072
	ds_read_b128 v[170:173], v150
	ds_read_b128 v[178:181], v150 offset:1024
	ds_read_b128 v[182:185], v150 offset:2048
	ds_read_b128 v[186:189], v150 offset:3072
	s_add_u32 s8, s50, 0xfffc0080
	s_addc_u32 s9, s51, -1
	s_cmp_eq_u32 s83, 12
	s_cselect_b32 s55, s19, s9
	s_cselect_b32 s54, s79, s8
	s_cselect_b32 s53, s15, s82
	s_cselect_b32 s52, s80, s81
	v_lshl_add_u64 v[144:145], s[50:51], 0, v[136:137]
	s_add_i32 m0, s49, 0xc000
	ds_read_b128 v[190:193], v151
	ds_read_b128 v[194:197], v151 offset:1024
	ds_read_b128 v[198:201], v151 offset:2048
	ds_read_b128 v[202:205], v151 offset:3072
	ds_read_b128 v[206:209], v151 offset:4096
	ds_read_b128 v[210:213], v151 offset:5120
	ds_read_b128 v[214:217], v151 offset:6144
	ds_read_b128 v[218:221], v151 offset:7168
	global_load_lds_dwordx4 v[144:145], off
	v_lshl_add_u64 v[144:145], s[50:51], 0, v[138:139]
	s_add_i32 m0, s49, 0xe000
	s_nop 0
	global_load_lds_dwordx4 v[144:145], off
	s_waitcnt vmcnt(8)
	s_waitcnt lgkmcnt(0)
	s_barrier
	s_setprio 1
	s_waitcnt lgkmcnt(0)
	v_mfma_f32_16x16x32_bf16 v[124:127], v[152:155], v[190:193], v[124:127]
	v_mfma_f32_16x16x32_bf16 v[120:123], v[162:165], v[190:193], v[120:123]
	v_mfma_f32_16x16x32_bf16 v[108:111], v[152:155], v[198:201], v[108:111]
	v_mfma_f32_16x16x32_bf16 v[104:107], v[162:165], v[198:201], v[104:107]
	v_mfma_f32_16x16x32_bf16 v[92:95], v[152:155], v[206:209], v[92:95]
	v_mfma_f32_16x16x32_bf16 v[88:91], v[162:165], v[206:209], v[88:91]
	v_mfma_f32_16x16x32_bf16 v[76:79], v[152:155], v[214:217], v[76:79]
	v_mfma_f32_16x16x32_bf16 v[72:75], v[162:165], v[214:217], v[72:75]
	v_mfma_f32_16x16x32_bf16 v[124:127], v[156:159], v[194:197], v[124:127]
	v_mfma_f32_16x16x32_bf16 v[120:123], v[166:169], v[194:197], v[120:123]
	v_mfma_f32_16x16x32_bf16 v[108:111], v[156:159], v[202:205], v[108:111]
	v_mfma_f32_16x16x32_bf16 v[104:107], v[166:169], v[202:205], v[104:107]
	v_mfma_f32_16x16x32_bf16 v[92:95], v[156:159], v[210:213], v[92:95]
	v_mfma_f32_16x16x32_bf16 v[88:91], v[166:169], v[210:213], v[88:91]
	v_mfma_f32_16x16x32_bf16 v[76:79], v[156:159], v[218:221], v[76:79]
	v_mfma_f32_16x16x32_bf16 v[72:75], v[166:169], v[218:221], v[72:75]
	s_setprio 0
	s_setprio 1
	v_mfma_f32_16x16x32_bf16 v[116:119], v[170:173], v[190:193], v[116:119]
	v_mfma_f32_16x16x32_bf16 v[112:115], v[182:185], v[190:193], v[112:115]
	v_mfma_f32_16x16x32_bf16 v[100:103], v[170:173], v[198:201], v[100:103]
	v_mfma_f32_16x16x32_bf16 v[96:99], v[182:185], v[198:201], v[96:99]
	v_mfma_f32_16x16x32_bf16 v[84:87], v[170:173], v[206:209], v[84:87]
	v_mfma_f32_16x16x32_bf16 v[80:83], v[182:185], v[206:209], v[80:83]
	v_mfma_f32_16x16x32_bf16 v[68:71], v[170:173], v[214:217], v[68:71]
	v_mfma_f32_16x16x32_bf16 v[64:67], v[182:185], v[214:217], v[64:67]
	v_mfma_f32_16x16x32_bf16 v[116:119], v[178:181], v[194:197], v[116:119]
	v_mfma_f32_16x16x32_bf16 v[112:115], v[186:189], v[194:197], v[112:115]
	v_mfma_f32_16x16x32_bf16 v[100:103], v[178:181], v[202:205], v[100:103]
	v_mfma_f32_16x16x32_bf16 v[96:99], v[186:189], v[202:205], v[96:99]
	v_mfma_f32_16x16x32_bf16 v[84:87], v[178:181], v[210:213], v[84:87]
	v_mfma_f32_16x16x32_bf16 v[80:83], v[186:189], v[210:213], v[80:83]
	v_mfma_f32_16x16x32_bf16 v[68:71], v[178:181], v[218:221], v[68:71]
	v_mfma_f32_16x16x32_bf16 v[64:67], v[186:189], v[218:221], v[64:67]
	s_setprio 0
	s_barrier
	s_add_i32 s8, s75, s57
	v_lshl_add_u64 v[144:145], s[52:53], 0, v[132:133]
	s_mov_b32 m0, s8
	ds_read_b128 v[190:193], v151 offset:16384
	ds_read_b128 v[194:197], v151 offset:17408
	ds_read_b128 v[198:201], v151 offset:18432
	ds_read_b128 v[202:205], v151 offset:19456
	ds_read_b128 v[206:209], v151 offset:20480
	ds_read_b128 v[210:213], v151 offset:21504
	ds_read_b128 v[214:217], v151 offset:22528
	ds_read_b128 v[218:221], v151 offset:23552
	global_load_lds_dwordx4 v[144:145], off
	s_add_i32 m0, s8, 0x2000
	s_add_u32 s8, s52, 0x40000
	v_lshl_add_u64 v[174:175], s[52:53], 0, v[128:129]
	s_addc_u32 s9, s53, 0
	s_add_i32 s60, s76, s57
	global_load_lds_dwordx4 v[174:175], off
	v_lshl_add_u64 v[222:223], s[8:9], 0, v[132:133]
	s_mov_b32 m0, s60
	v_lshl_add_u64 v[224:225], s[54:55], 0, v[130:131]
	global_load_lds_dwordx4 v[222:223], off
	v_lshl_add_u64 v[222:223], s[8:9], 0, v[128:129]
	s_add_i32 m0, s60, 0x2000
	s_nop 0
	global_load_lds_dwordx4 v[222:223], off
	v_lshl_add_u64 v[222:223], s[54:55], 0, v[134:135]
	s_mov_b32 m0, s49
	s_nop 0
	global_load_lds_dwordx4 v[222:223], off
	s_mov_b32 m0, s67
	s_nop 0
	global_load_lds_dwordx4 v[224:225], off
	s_waitcnt vmcnt(8)
	s_waitcnt lgkmcnt(0)
	s_barrier
; #define PG8_STAGE(bufoff, gbase, voff) do { _Pragma("unroll") for (int _i = 0; _i < 2; ++_i) \
;         __builtin_amdgcn_global_load_lds((const unsigned*)((const char*)(gbase) + (voff)[_i]), (PG8_LAS unsigned*)(lds + (bufoff) + ldsw + _i * 8192), 16, 0, 0); } while (0)
; #define PG8_LDA(dst, b, h) do { _Pragma("unroll") for (int m = 0; m < 4; ++m) _Pragma("unroll") for (int k = 0; k < 2; ++k) dst[m][k] = *(const PG8_LAS bf16x8*)(lds + PG8_SA(b, h) + aoff + m * 2048 + k * 1024); } while (0)
; #define PG8_LDB(dst, b, h) do { _Pragma("unroll") for (int n = 0; n < 2; ++n) _Pragma("unroll") for (int k = 0; k < 2; ++k) dst[n][k] = *(const PG8_LAS bf16x8*)(lds + PG8_SB(b, h) + boff + n * 2048 + k * 1024); } while (0)
; #define PG8_MMA(ai, bj, At, Bt) do { __builtin_amdgcn_s_setprio(1); _Pragma("unroll") for (int m = 0; m < 4; ++m) _Pragma("unroll") for (int n = 0; n < 2; ++n) _Pragma("unroll") for (int k = 0; k < 2; ++k) \
;         acc[ai][bj][m][n] = __builtin_amdgcn_mfma_f32_16x16x32_bf16(Bt[n][k], At[m][k], acc[ai][bj][m][n], 0, 0, 0); __builtin_amdgcn_s_setprio(0); } while (0)
; #define PG8_WAIT_V(n) asm volatile("s_waitcnt vmcnt(" #n ")" ::: "memory")
; #define PG8_WAIT_L(n) asm volatile("s_waitcnt lgkmcnt(" #n ")" ::: "memory")
; #define PG8_BAR __builtin_amdgcn_s_barrier()
; #define PG8_SCHED __builtin_amdgcn_sched_barrier(0)
; template <class Epi, class Sched, bool ALIGN_EPI = false, bool SP2 = false>
; __device__ __forceinline__ void gemm_phase(PG8_LAS unsigned char* lds, const Gemm g, const Sched& S, const Epi& E) {
;     ...
;             PG8_WAIT_V(8); PG8_WAIT_L(0); PG8_BAR; PG8_MMA(1, 0, At, B0); PG8_MMA(1, 1, At, B1); PG8_BAR; PG8_SCHED;
;             PG8_LDB(B0, 1, 0); PG8_LDB(B1, 1, 1); PG8_SCHED; PG8_LDA(At, 1, 0); PG8_STAGE(PG8_SA(0, 1), a2 + hstep, voffA);
;             PG8_WAIT_V(8); PG8_WAIT_L(0); PG8_BAR; PG8_MMA(0, 0, At, B0); PG8_MMA(0, 1, At, B1); PG8_BAR; PG8_SCHED;
	s_setprio 1
	s_waitcnt lgkmcnt(0)
	v_mfma_f32_16x16x32_bf16 v[60:63], v[152:155], v[190:193], v[60:63]
	v_mfma_f32_16x16x32_bf16 v[56:59], v[162:165], v[190:193], v[56:59]
	v_mfma_f32_16x16x32_bf16 v[44:47], v[152:155], v[198:201], v[44:47]
	v_mfma_f32_16x16x32_bf16 v[40:43], v[162:165], v[198:201], v[40:43]
	v_mfma_f32_16x16x32_bf16 v[28:31], v[152:155], v[206:209], v[28:31]
	v_mfma_f32_16x16x32_bf16 v[24:27], v[162:165], v[206:209], v[24:27]
	v_mfma_f32_16x16x32_bf16 v[12:15], v[152:155], v[214:217], v[12:15]
	v_mfma_f32_16x16x32_bf16 v[8:11], v[162:165], v[214:217], v[8:11]
	v_mfma_f32_16x16x32_bf16 v[60:63], v[156:159], v[194:197], v[60:63]
	v_mfma_f32_16x16x32_bf16 v[56:59], v[166:169], v[194:197], v[56:59]
	v_mfma_f32_16x16x32_bf16 v[44:47], v[156:159], v[202:205], v[44:47]
	v_mfma_f32_16x16x32_bf16 v[40:43], v[166:169], v[202:205], v[40:43]
	v_mfma_f32_16x16x32_bf16 v[28:31], v[156:159], v[210:213], v[28:31]
	v_mfma_f32_16x16x32_bf16 v[24:27], v[166:169], v[210:213], v[24:27]
	v_mfma_f32_16x16x32_bf16 v[12:15], v[156:159], v[218:221], v[12:15]
	v_mfma_f32_16x16x32_bf16 v[8:11], v[166:169], v[218:221], v[8:11]
	s_setprio 0
	s_setprio 1
	v_mfma_f32_16x16x32_bf16 v[52:55], v[170:173], v[190:193], v[52:55]
	v_mfma_f32_16x16x32_bf16 v[48:51], v[182:185], v[190:193], v[48:51]
	v_mfma_f32_16x16x32_bf16 v[36:39], v[170:173], v[198:201], v[36:39]
	v_mfma_f32_16x16x32_bf16 v[32:35], v[182:185], v[198:201], v[32:35]
	v_mfma_f32_16x16x32_bf16 v[20:23], v[170:173], v[206:209], v[20:23]
	v_mfma_f32_16x16x32_bf16 v[16:19], v[182:185], v[206:209], v[16:19]
	v_mfma_f32_16x16x32_bf16 v[4:7], v[170:173], v[214:217], v[4:7]
	v_mfma_f32_16x16x32_bf16 v[0:3], v[182:185], v[214:217], v[0:3]
	v_mfma_f32_16x16x32_bf16 v[52:55], v[178:181], v[194:197], v[52:55]
	v_mfma_f32_16x16x32_bf16 v[48:51], v[186:189], v[194:197], v[48:51]
	v_mfma_f32_16x16x32_bf16 v[36:39], v[178:181], v[202:205], v[36:39]
	v_mfma_f32_16x16x32_bf16 v[32:35], v[186:189], v[202:205], v[32:35]
	v_mfma_f32_16x16x32_bf16 v[20:23], v[178:181], v[210:213], v[20:23]
	v_mfma_f32_16x16x32_bf16 v[16:19], v[186:189], v[210:213], v[16:19]
	v_mfma_f32_16x16x32_bf16 v[4:7], v[178:181], v[218:221], v[4:7]
	v_mfma_f32_16x16x32_bf16 v[0:3], v[186:189], v[218:221], v[0:3]
	s_setprio 0
	s_barrier
	s_add_i32 s60, 0, 0x18000
	v_add_u32_e32 v161, s60, v147
	s_add_i32 s61, 0, 0x1c000
	ds_read_b128 v[152:155], v161
	ds_read_b128 v[156:159], v161 offset:1024
	ds_read_b128 v[162:165], v161 offset:2048
	ds_read_b128 v[166:169], v161 offset:3072
	v_add_u32_e32 v161, s61, v147
	ds_read_b128 v[170:173], v161
	ds_read_b128 v[178:181], v161 offset:1024
	ds_read_b128 v[182:185], v161 offset:2048
	ds_read_b128 v[186:189], v161 offset:3072
	s_add_u32 s8, s54, 0x40000
	s_addc_u32 s9, s55, 0
	s_mov_b32 m0, s68
	v_lshl_add_u64 v[226:227], s[8:9], 0, v[134:135]
	ds_read_b128 v[190:193], v151 offset:32768
	ds_read_b128 v[194:197], v151 offset:33792
	ds_read_b128 v[198:201], v151 offset:34816
	ds_read_b128 v[202:205], v151 offset:35840
	ds_read_b128 v[206:209], v151 offset:36864
	ds_read_b128 v[210:213], v151 offset:37888
	ds_read_b128 v[214:217], v151 offset:38912
	ds_read_b128 v[218:221], v151 offset:39936
	global_load_lds_dwordx4 v[226:227], off
	v_lshl_add_u64 v[226:227], s[8:9], 0, v[130:131]
	s_mov_b32 m0, s69
	s_nop 0
	global_load_lds_dwordx4 v[226:227], off
	s_waitcnt vmcnt(8)
	s_waitcnt lgkmcnt(0)
	s_barrier
	s_setprio 1
	s_waitcnt lgkmcnt(0)
	v_mfma_f32_16x16x32_bf16 v[124:127], v[152:155], v[190:193], v[124:127]
	v_mfma_f32_16x16x32_bf16 v[120:123], v[162:165], v[190:193], v[120:123]
	v_mfma_f32_16x16x32_bf16 v[108:111], v[152:155], v[198:201], v[108:111]
	v_mfma_f32_16x16x32_bf16 v[104:107], v[162:165], v[198:201], v[104:107]
	v_mfma_f32_16x16x32_bf16 v[92:95], v[152:155], v[206:209], v[92:95]
	v_mfma_f32_16x16x32_bf16 v[88:91], v[162:165], v[206:209], v[88:91]
	v_mfma_f32_16x16x32_bf16 v[76:79], v[152:155], v[214:217], v[76:79]
	v_mfma_f32_16x16x32_bf16 v[72:75], v[162:165], v[214:217], v[72:75]
	v_mfma_f32_16x16x32_bf16 v[124:127], v[156:159], v[194:197], v[124:127]
	v_mfma_f32_16x16x32_bf16 v[120:123], v[166:169], v[194:197], v[120:123]
	v_mfma_f32_16x16x32_bf16 v[108:111], v[156:159], v[202:205], v[108:111]
	v_mfma_f32_16x16x32_bf16 v[104:107], v[166:169], v[202:205], v[104:107]
	v_mfma_f32_16x16x32_bf16 v[92:95], v[156:159], v[210:213], v[92:95]
	v_mfma_f32_16x16x32_bf16 v[88:91], v[166:169], v[210:213], v[88:91]
	v_mfma_f32_16x16x32_bf16 v[76:79], v[156:159], v[218:221], v[76:79]
	v_mfma_f32_16x16x32_bf16 v[72:75], v[166:169], v[218:221], v[72:75]
	s_setprio 0
	s_setprio 1
	v_mfma_f32_16x16x32_bf16 v[116:119], v[170:173], v[190:193], v[116:119]
	v_mfma_f32_16x16x32_bf16 v[112:115], v[182:185], v[190:193], v[112:115]
	v_mfma_f32_16x16x32_bf16 v[100:103], v[170:173], v[198:201], v[100:103]
	v_mfma_f32_16x16x32_bf16 v[96:99], v[182:185], v[198:201], v[96:99]
	v_mfma_f32_16x16x32_bf16 v[84:87], v[170:173], v[206:209], v[84:87]
	v_mfma_f32_16x16x32_bf16 v[80:83], v[182:185], v[206:209], v[80:83]
	v_mfma_f32_16x16x32_bf16 v[68:71], v[170:173], v[214:217], v[68:71]
	v_mfma_f32_16x16x32_bf16 v[64:67], v[182:185], v[214:217], v[64:67]
	v_mfma_f32_16x16x32_bf16 v[116:119], v[178:181], v[194:197], v[116:119]
	v_mfma_f32_16x16x32_bf16 v[112:115], v[186:189], v[194:197], v[112:115]
	v_mfma_f32_16x16x32_bf16 v[100:103], v[178:181], v[202:205], v[100:103]
	v_mfma_f32_16x16x32_bf16 v[96:99], v[186:189], v[202:205], v[96:99]
	v_mfma_f32_16x16x32_bf16 v[84:87], v[178:181], v[210:213], v[84:87]
	v_mfma_f32_16x16x32_bf16 v[80:83], v[186:189], v[210:213], v[80:83]
	v_mfma_f32_16x16x32_bf16 v[68:71], v[178:181], v[218:221], v[68:71]
	v_mfma_f32_16x16x32_bf16 v[64:67], v[186:189], v[218:221], v[64:67]
	s_setprio 0
	s_barrier
; #define PG8_STAGE(bufoff, gbase, voff) do { _Pragma("unroll") for (int _i = 0; _i < 2; ++_i) \
;         __builtin_amdgcn_global_load_lds((const unsigned*)((const char*)(gbase) + (voff)[_i]), (PG8_LAS unsigned*)(lds + (bufoff) + ldsw + _i * 8192), 16, 0, 0); } while (0)
; #define PG8_LDA(dst, b, h) do { _Pragma("unroll") for (int m = 0; m < 4; ++m) _Pragma("unroll") for (int k = 0; k < 2; ++k) dst[m][k] = *(const PG8_LAS bf16x8*)(lds + PG8_SA(b, h) + aoff + m * 2048 + k * 1024); } while (0)
; #define PG8_MMA(ai, bj, At, Bt) do { __builtin_amdgcn_s_setprio(1); _Pragma("unroll") for (int m = 0; m < 4; ++m) _Pragma("unroll") for (int n = 0; n < 2; ++n) _Pragma("unroll") for (int k = 0; k < 2; ++k) \
;         acc[ai][bj][m][n] = __builtin_amdgcn_mfma_f32_16x16x32_bf16(Bt[n][k], At[m][k], acc[ai][bj][m][n], 0, 0, 0); __builtin_amdgcn_s_setprio(0); } while (0)
; #define PG8_WAIT_V(n) asm volatile("s_waitcnt vmcnt(" #n ")" ::: "memory")
; #define PG8_WAIT_L(n) asm volatile("s_waitcnt lgkmcnt(" #n ")" ::: "memory")
; #define PG8_BAR __builtin_amdgcn_s_barrier()
; #define PG8_SCHED __builtin_amdgcn_sched_barrier(0)
; template <class Epi, class Sched, bool ALIGN_EPI = false, bool SP2 = false>
; __device__ __forceinline__ void gemm_phase(PG8_LAS unsigned char* lds, const Gemm g, const Sched& S, const Epi& E) {
;     ...
;         for (int t = 0; t < nt; t += 2) {
;     ...
;             PG8_LDA(At, 1, 1); PG8_STAGE(PG8_SB(1, 0), b3, voffB); PG8_STAGE(PG8_SB(1, 1), b3 + hstep, voffB); PG8_STAGE(PG8_SA(1, 0), a3, voffA);
;             PG8_WAIT_V(8); PG8_WAIT_L(0); PG8_BAR; PG8_MMA(1, 0, At, B0); PG8_MMA(1, 1, At, B1); PG8_BAR; PG8_SCHED;
	s_add_i32 s8, s60, s57
	v_lshl_add_u64 v[144:145], v[144:145], 0, s[6:7]
	s_mov_b32 m0, s8
	ds_read_b128 v[190:193], v151 offset:49152
	ds_read_b128 v[194:197], v151 offset:50176
	ds_read_b128 v[198:201], v151 offset:51200
	ds_read_b128 v[202:205], v151 offset:52224
	ds_read_b128 v[206:209], v151 offset:53248
	ds_read_b128 v[210:213], v151 offset:54272
	ds_read_b128 v[214:217], v151 offset:55296
	ds_read_b128 v[218:221], v151 offset:56320
	global_load_lds_dwordx4 v[144:145], off
	s_add_i32 m0, s8, 0x2000
	s_add_u32 s8, s52, 0x40080
	v_lshl_add_u64 v[144:145], v[174:175], 0, s[6:7]
	s_addc_u32 s9, s53, 0
	s_add_i32 s52, s61, s57
	global_load_lds_dwordx4 v[144:145], off
	v_lshl_add_u64 v[144:145], s[8:9], 0, v[132:133]
	s_mov_b32 m0, s52
	s_nop 0
	global_load_lds_dwordx4 v[144:145], off
	v_lshl_add_u64 v[144:145], s[8:9], 0, v[128:129]
	s_add_i32 m0, s52, 0x2000
	s_nop 0
	global_load_lds_dwordx4 v[144:145], off
	v_lshl_add_u64 v[144:145], v[222:223], 0, s[6:7]
	s_mov_b32 m0, s71
	s_nop 0
	global_load_lds_dwordx4 v[144:145], off
	v_lshl_add_u64 v[144:145], v[224:225], 0, s[6:7]
	s_mov_b32 m0, s72
	s_nop 0
	global_load_lds_dwordx4 v[144:145], off
	s_waitcnt vmcnt(8)
	s_waitcnt lgkmcnt(0)
	s_barrier
	s_setprio 1
	s_waitcnt lgkmcnt(0)
	v_mfma_f32_16x16x32_bf16 v[60:63], v[152:155], v[190:193], v[60:63]
	v_mfma_f32_16x16x32_bf16 v[56:59], v[162:165], v[190:193], v[56:59]
	v_mfma_f32_16x16x32_bf16 v[44:47], v[152:155], v[198:201], v[44:47]
	v_mfma_f32_16x16x32_bf16 v[40:43], v[162:165], v[198:201], v[40:43]
	v_mfma_f32_16x16x32_bf16 v[28:31], v[152:155], v[206:209], v[28:31]
	v_mfma_f32_16x16x32_bf16 v[24:27], v[162:165], v[206:209], v[24:27]
	v_mfma_f32_16x16x32_bf16 v[12:15], v[152:155], v[214:217], v[12:15]
	v_mfma_f32_16x16x32_bf16 v[8:11], v[162:165], v[214:217], v[8:11]
	v_mfma_f32_16x16x32_bf16 v[60:63], v[156:159], v[194:197], v[60:63]
	v_mfma_f32_16x16x32_bf16 v[56:59], v[166:169], v[194:197], v[56:59]
	v_mfma_f32_16x16x32_bf16 v[44:47], v[156:159], v[202:205], v[44:47]
	v_mfma_f32_16x16x32_bf16 v[40:43], v[166:169], v[202:205], v[40:43]
	v_mfma_f32_16x16x32_bf16 v[28:31], v[156:159], v[210:213], v[28:31]
	v_mfma_f32_16x16x32_bf16 v[24:27], v[166:169], v[210:213], v[24:27]
	v_mfma_f32_16x16x32_bf16 v[12:15], v[156:159], v[218:221], v[12:15]
	v_mfma_f32_16x16x32_bf16 v[8:11], v[166:169], v[218:221], v[8:11]
	s_setprio 0
	s_setprio 1
	v_mfma_f32_16x16x32_bf16 v[52:55], v[170:173], v[190:193], v[52:55]
	v_mfma_f32_16x16x32_bf16 v[48:51], v[182:185], v[190:193], v[48:51]
	v_mfma_f32_16x16x32_bf16 v[36:39], v[170:173], v[198:201], v[36:39]
	v_mfma_f32_16x16x32_bf16 v[32:35], v[182:185], v[198:201], v[32:35]
	v_mfma_f32_16x16x32_bf16 v[20:23], v[170:173], v[206:209], v[20:23]
	v_mfma_f32_16x16x32_bf16 v[16:19], v[182:185], v[206:209], v[16:19]
	v_mfma_f32_16x16x32_bf16 v[4:7], v[170:173], v[214:217], v[4:7]
	v_mfma_f32_16x16x32_bf16 v[0:3], v[182:185], v[214:217], v[0:3]
	v_mfma_f32_16x16x32_bf16 v[52:55], v[178:181], v[194:197], v[52:55]
	v_mfma_f32_16x16x32_bf16 v[48:51], v[186:189], v[194:197], v[48:51]
	v_mfma_f32_16x16x32_bf16 v[36:39], v[178:181], v[202:205], v[36:39]
	v_mfma_f32_16x16x32_bf16 v[32:35], v[186:189], v[202:205], v[32:35]
	v_mfma_f32_16x16x32_bf16 v[20:23], v[178:181], v[210:213], v[20:23]
	v_mfma_f32_16x16x32_bf16 v[16:19], v[186:189], v[210:213], v[16:19]
	v_mfma_f32_16x16x32_bf16 v[4:7], v[178:181], v[218:221], v[4:7]
	v_mfma_f32_16x16x32_bf16 v[0:3], v[186:189], v[218:221], v[0:3]
	s_setprio 0
	s_add_i32 s83, s83, 2
	s_add_u32 s50, s50, 0x100
	s_addc_u32 s51, s51, 0
	s_add_u32 s81, s81, 0x100
	s_addc_u32 s82, s82, 0
	s_cmp_gt_u32 s83, 13
	s_barrier
	s_cbranch_scc0 .LBB0_557
	s_and_b64 vcc, exec, s[12:13]
	s_cbranch_vccz .LBB0_560
	s_barrier

; #define PG8_STAGE(bufoff, gbase, voff) do { _Pragma("unroll") for (int _i = 0; _i < 2; ++_i) \
;         __builtin_amdgcn_global_load_lds((const unsigned*)((const char*)(gbase) + (voff)[_i]), (PG8_LAS unsigned*)(lds + (bufoff) + ldsw + _i * 8192), 16, 0, 0); } while (0)
; #define PG8_LDA(dst, b, h) do { _Pragma("unroll") for (int m = 0; m < 4; ++m) _Pragma("unroll") for (int k = 0; k < 2; ++k) dst[m][k] = *(const PG8_LAS bf16x8*)(lds + PG8_SA(b, h) + aoff + m * 2048 + k * 1024); } while (0)
; #define PG8_LDB(dst, b, h) do { _Pragma("unroll") for (int n = 0; n < 2; ++n) _Pragma("unroll") for (int k = 0; k < 2; ++k) dst[n][k] = *(const PG8_LAS bf16x8*)(lds + PG8_SB(b, h) + boff + n * 2048 + k * 1024); } while (0)
; #define PG8_MMA(ai, bj, At, Bt) do { __builtin_amdgcn_s_setprio(1); _Pragma("unroll") for (int m = 0; m < 4; ++m) _Pragma("unroll") for (int n = 0; n < 2; ++n) _Pragma("unroll") for (int k = 0; k < 2; ++k) \
;         acc[ai][bj][m][n] = __builtin_amdgcn_mfma_f32_16x16x32_bf16(Bt[n][k], At[m][k], acc[ai][bj][m][n], 0, 0, 0); __builtin_amdgcn_s_setprio(0); } while (0)
; #define PG8_WAIT_V(n) asm volatile("s_waitcnt vmcnt(" #n ")" ::: "memory")
; #define PG8_WAIT_L(n) asm volatile("s_waitcnt lgkmcnt(" #n ")" ::: "memory")
; #define PG8_BAR __builtin_amdgcn_s_barrier()
; #define PG8_SCHED __builtin_amdgcn_sched_barrier(0)
; template <class Epi, class Sched, bool ALIGN_EPI = false, bool SP2 = false>
; __device__ __forceinline__ void gemm_phase(PG8_LAS unsigned char* lds, const Gemm g, const Sched& S, const Epi& E) {
;     ...
;             const bool last = (t == nt - 2);
;             const char* a1 = cA + (size_t)(t + 1) * kstep;
;             const char* a2 = last ? nA : cA + (size_t)(t + 2) * kstep; const char* b2 = last ? nB : cB + (size_t)(t + 2) * kstep;
;             const char* a3 = a2 + kstep; const char* b3 = b2 + kstep;
;             if (last && has_next) S.a_ready(nxt);
;             if constexpr (SP2) {
;             PG8_LDB(B0, 0, 0); PG8_LDB(B1, 0, 1); PG8_SCHED; PG8_LDA(At, 0, 0); PG8_STAGE(PG8_SA(1, 1), a1 + hstep, voffA);
;             PG8_WAIT_V(8); PG8_WAIT_L(0); PG8_BAR; PG8_MMA(0, 0, At, B0); PG8_MMA(0, 1, At, B1); PG8_BAR; PG8_SCHED;
;             PG8_LDA(At, 0, 1); PG8_STAGE(PG8_SB(0, 0), b2, voffB); PG8_STAGE(PG8_SB(0, 1), b2 + hstep, voffB); PG8_STAGE(PG8_SA(0, 0), a2, voffA);
.LBB0_640:
	ds_read_b128 v[164:167], v159
	ds_read_b128 v[168:171], v159 offset:1024
	ds_read_b128 v[172:175], v159 offset:2048
	ds_read_b128 v[178:181], v159 offset:3072
	ds_read_b128 v[182:185], v161
	ds_read_b128 v[186:189], v161 offset:1024
	ds_read_b128 v[190:193], v161 offset:2048
	ds_read_b128 v[194:197], v161 offset:3072
	s_add_u32 s8, s54, 0xfff50080
	s_addc_u32 s9, s55, -1
	s_cmp_eq_u32 s93, 40
	s_cselect_b32 s67, s1, s9
	s_cselect_b32 s66, s0, s8
	s_cselect_b32 s57, s53, s92
	s_cselect_b32 s56, s52, s91
	v_lshl_add_u64 v[146:147], s[54:55], 0, v[136:137]
	s_add_i32 m0, s70, 0xc000
	ds_read_b128 v[198:201], v162
	ds_read_b128 v[202:205], v162 offset:1024
	ds_read_b128 v[206:209], v162 offset:2048
	ds_read_b128 v[210:213], v162 offset:3072
	ds_read_b128 v[214:217], v162 offset:4096
	ds_read_b128 v[218:221], v162 offset:5120
	ds_read_b128 v[222:225], v162 offset:6144
	ds_read_b128 v[226:229], v162 offset:7168
	global_load_lds_dwordx4 v[146:147], off
	v_lshl_add_u64 v[146:147], s[54:55], 0, v[138:139]
	s_add_i32 m0, s70, 0xe000
	s_nop 0
	global_load_lds_dwordx4 v[146:147], off
	s_waitcnt vmcnt(8)
	s_waitcnt lgkmcnt(0)
	s_barrier
	s_setprio 1
	s_waitcnt lgkmcnt(0)
	v_mfma_f32_16x16x32_bf16 v[124:127], v[164:167], v[198:201], v[124:127]
	v_mfma_f32_16x16x32_bf16 v[120:123], v[172:175], v[198:201], v[120:123]
	v_mfma_f32_16x16x32_bf16 v[112:115], v[164:167], v[206:209], v[112:115]
	v_mfma_f32_16x16x32_bf16 v[104:107], v[172:175], v[206:209], v[104:107]
	v_mfma_f32_16x16x32_bf16 v[96:99], v[164:167], v[214:217], v[96:99]
	v_mfma_f32_16x16x32_bf16 v[88:91], v[172:175], v[214:217], v[88:91]
	v_mfma_f32_16x16x32_bf16 v[80:83], v[164:167], v[222:225], v[80:83]
	v_mfma_f32_16x16x32_bf16 v[72:75], v[172:175], v[222:225], v[72:75]
	v_mfma_f32_16x16x32_bf16 v[124:127], v[168:171], v[202:205], v[124:127]
	v_mfma_f32_16x16x32_bf16 v[120:123], v[178:181], v[202:205], v[120:123]
	v_mfma_f32_16x16x32_bf16 v[112:115], v[168:171], v[210:213], v[112:115]
	v_mfma_f32_16x16x32_bf16 v[104:107], v[178:181], v[210:213], v[104:107]
	v_mfma_f32_16x16x32_bf16 v[96:99], v[168:171], v[218:221], v[96:99]
	v_mfma_f32_16x16x32_bf16 v[88:91], v[178:181], v[218:221], v[88:91]
	v_mfma_f32_16x16x32_bf16 v[80:83], v[168:171], v[226:229], v[80:83]
	v_mfma_f32_16x16x32_bf16 v[72:75], v[178:181], v[226:229], v[72:75]
	s_setprio 0
	s_setprio 1
	v_mfma_f32_16x16x32_bf16 v[116:119], v[182:185], v[198:201], v[116:119]
	v_mfma_f32_16x16x32_bf16 v[108:111], v[190:193], v[198:201], v[108:111]
	v_mfma_f32_16x16x32_bf16 v[100:103], v[182:185], v[206:209], v[100:103]
	v_mfma_f32_16x16x32_bf16 v[92:95], v[190:193], v[206:209], v[92:95]
	v_mfma_f32_16x16x32_bf16 v[84:87], v[182:185], v[214:217], v[84:87]
	v_mfma_f32_16x16x32_bf16 v[76:79], v[190:193], v[214:217], v[76:79]
	v_mfma_f32_16x16x32_bf16 v[68:71], v[182:185], v[222:225], v[68:71]
	v_mfma_f32_16x16x32_bf16 v[64:67], v[190:193], v[222:225], v[64:67]
	v_mfma_f32_16x16x32_bf16 v[116:119], v[186:189], v[202:205], v[116:119]
	v_mfma_f32_16x16x32_bf16 v[108:111], v[194:197], v[202:205], v[108:111]
	v_mfma_f32_16x16x32_bf16 v[100:103], v[186:189], v[210:213], v[100:103]
	v_mfma_f32_16x16x32_bf16 v[92:95], v[194:197], v[210:213], v[92:95]
	v_mfma_f32_16x16x32_bf16 v[84:87], v[186:189], v[218:221], v[84:87]
	v_mfma_f32_16x16x32_bf16 v[76:79], v[194:197], v[218:221], v[76:79]
	v_mfma_f32_16x16x32_bf16 v[68:71], v[186:189], v[226:229], v[68:71]
	v_mfma_f32_16x16x32_bf16 v[64:67], v[194:197], v[226:229], v[64:67]
	s_setprio 0
	s_barrier
	s_add_i32 s8, s79, s69
	v_lshl_add_u64 v[146:147], s[56:57], 0, v[130:131]
	s_mov_b32 m0, s8
	ds_read_b128 v[198:201], v162 offset:16384
	ds_read_b128 v[202:205], v162 offset:17408
	ds_read_b128 v[206:209], v162 offset:18432
	ds_read_b128 v[210:213], v162 offset:19456
	ds_read_b128 v[214:217], v162 offset:20480
	ds_read_b128 v[218:221], v162 offset:21504
	ds_read_b128 v[222:225], v162 offset:22528
	ds_read_b128 v[226:229], v162 offset:23552
	global_load_lds_dwordx4 v[146:147], off
	s_add_i32 m0, s8, 0x2000
	s_add_u32 s8, s56, 0xb0000
	v_lshl_add_u64 v[230:231], s[56:57], 0, v[134:135]
	s_addc_u32 s9, s57, 0
	s_add_i32 s60, s80, s69
	global_load_lds_dwordx4 v[230:231], off
	v_lshl_add_u64 v[232:233], s[8:9], 0, v[130:131]
	s_mov_b32 m0, s60
	v_lshl_add_u64 v[234:235], s[66:67], 0, v[132:133]
	global_load_lds_dwordx4 v[232:233], off
	v_lshl_add_u64 v[232:233], s[8:9], 0, v[134:135]
	s_add_i32 m0, s60, 0x2000
	s_nop 0
	global_load_lds_dwordx4 v[232:233], off
	v_lshl_add_u64 v[232:233], s[66:67], 0, v[128:129]
	s_mov_b32 m0, s70
	s_nop 0
	global_load_lds_dwordx4 v[232:233], off
	s_mov_b32 m0, s71
	s_nop 0
	global_load_lds_dwordx4 v[234:235], off
	s_waitcnt vmcnt(8)
	s_waitcnt lgkmcnt(0)
	s_barrier
; #define PG8_STAGE(bufoff, gbase, voff) do { _Pragma("unroll") for (int _i = 0; _i < 2; ++_i) \
;         __builtin_amdgcn_global_load_lds((const unsigned*)((const char*)(gbase) + (voff)[_i]), (PG8_LAS unsigned*)(lds + (bufoff) + ldsw + _i * 8192), 16, 0, 0); } while (0)
; #define PG8_LDA(dst, b, h) do { _Pragma("unroll") for (int m = 0; m < 4; ++m) _Pragma("unroll") for (int k = 0; k < 2; ++k) dst[m][k] = *(const PG8_LAS bf16x8*)(lds + PG8_SA(b, h) + aoff + m * 2048 + k * 1024); } while (0)
; #define PG8_LDB(dst, b, h) do { _Pragma("unroll") for (int n = 0; n < 2; ++n) _Pragma("unroll") for (int k = 0; k < 2; ++k) dst[n][k] = *(const PG8_LAS bf16x8*)(lds + PG8_SB(b, h) + boff + n * 2048 + k * 1024); } while (0)
; #define PG8_MMA(ai, bj, At, Bt) do { __builtin_amdgcn_s_setprio(1); _Pragma("unroll") for (int m = 0; m < 4; ++m) _Pragma("unroll") for (int n = 0; n < 2; ++n) _Pragma("unroll") for (int k = 0; k < 2; ++k) \
;         acc[ai][bj][m][n] = __builtin_amdgcn_mfma_f32_16x16x32_bf16(Bt[n][k], At[m][k], acc[ai][bj][m][n], 0, 0, 0); __builtin_amdgcn_s_setprio(0); } while (0)
; #define PG8_WAIT_V(n) asm volatile("s_waitcnt vmcnt(" #n ")" ::: "memory")
; #define PG8_WAIT_L(n) asm volatile("s_waitcnt lgkmcnt(" #n ")" ::: "memory")
; #define PG8_BAR __builtin_amdgcn_s_barrier()
; #define PG8_SCHED __builtin_amdgcn_sched_barrier(0)
; template <class Epi, class Sched, bool ALIGN_EPI = false, bool SP2 = false>
; __device__ __forceinline__ void gemm_phase(PG8_LAS unsigned char* lds, const Gemm g, const Sched& S, const Epi& E) {
;     ...
;             PG8_WAIT_V(8); PG8_WAIT_L(0); PG8_BAR; PG8_MMA(1, 0, At, B0); PG8_MMA(1, 1, At, B1); PG8_BAR; PG8_SCHED;
;             PG8_LDB(B0, 1, 0); PG8_LDB(B1, 1, 1); PG8_SCHED; PG8_LDA(At, 1, 0); PG8_STAGE(PG8_SA(0, 1), a2 + hstep, voffA);
;             PG8_WAIT_V(8); PG8_WAIT_L(0); PG8_BAR; PG8_MMA(0, 0, At, B0); PG8_MMA(0, 1, At, B1); PG8_BAR; PG8_SCHED;
	s_setprio 1
	s_waitcnt lgkmcnt(0)
	v_mfma_f32_16x16x32_bf16 v[60:63], v[164:167], v[198:201], v[60:63]
	v_mfma_f32_16x16x32_bf16 v[56:59], v[172:175], v[198:201], v[56:59]
	v_mfma_f32_16x16x32_bf16 v[48:51], v[164:167], v[206:209], v[48:51]
	v_mfma_f32_16x16x32_bf16 v[40:43], v[172:175], v[206:209], v[40:43]
	v_mfma_f32_16x16x32_bf16 v[32:35], v[164:167], v[214:217], v[32:35]
	v_mfma_f32_16x16x32_bf16 v[24:27], v[172:175], v[214:217], v[24:27]
	v_mfma_f32_16x16x32_bf16 v[16:19], v[164:167], v[222:225], v[16:19]
	v_mfma_f32_16x16x32_bf16 v[8:11], v[172:175], v[222:225], v[8:11]
	v_mfma_f32_16x16x32_bf16 v[60:63], v[168:171], v[202:205], v[60:63]
	v_mfma_f32_16x16x32_bf16 v[56:59], v[178:181], v[202:205], v[56:59]
	v_mfma_f32_16x16x32_bf16 v[48:51], v[168:171], v[210:213], v[48:51]
	v_mfma_f32_16x16x32_bf16 v[40:43], v[178:181], v[210:213], v[40:43]
	v_mfma_f32_16x16x32_bf16 v[32:35], v[168:171], v[218:221], v[32:35]
	v_mfma_f32_16x16x32_bf16 v[24:27], v[178:181], v[218:221], v[24:27]
	v_mfma_f32_16x16x32_bf16 v[16:19], v[168:171], v[226:229], v[16:19]
	v_mfma_f32_16x16x32_bf16 v[8:11], v[178:181], v[226:229], v[8:11]
	s_setprio 0
	s_setprio 1
	v_mfma_f32_16x16x32_bf16 v[52:55], v[182:185], v[198:201], v[52:55]
	v_mfma_f32_16x16x32_bf16 v[44:47], v[190:193], v[198:201], v[44:47]
	v_mfma_f32_16x16x32_bf16 v[36:39], v[182:185], v[206:209], v[36:39]
	v_mfma_f32_16x16x32_bf16 v[28:31], v[190:193], v[206:209], v[28:31]
	v_mfma_f32_16x16x32_bf16 v[20:23], v[182:185], v[214:217], v[20:23]
	v_mfma_f32_16x16x32_bf16 v[12:15], v[190:193], v[214:217], v[12:15]
	v_mfma_f32_16x16x32_bf16 v[4:7], v[182:185], v[222:225], v[4:7]
	v_mfma_f32_16x16x32_bf16 v[0:3], v[190:193], v[222:225], v[0:3]
	v_mfma_f32_16x16x32_bf16 v[52:55], v[186:189], v[202:205], v[52:55]
	v_mfma_f32_16x16x32_bf16 v[44:47], v[194:197], v[202:205], v[44:47]
	v_mfma_f32_16x16x32_bf16 v[36:39], v[186:189], v[210:213], v[36:39]
	v_mfma_f32_16x16x32_bf16 v[28:31], v[194:197], v[210:213], v[28:31]
	v_mfma_f32_16x16x32_bf16 v[20:23], v[186:189], v[218:221], v[20:23]
	v_mfma_f32_16x16x32_bf16 v[12:15], v[194:197], v[218:221], v[12:15]
	v_mfma_f32_16x16x32_bf16 v[4:7], v[186:189], v[226:229], v[4:7]
	v_mfma_f32_16x16x32_bf16 v[0:3], v[194:197], v[226:229], v[0:3]
	s_setprio 0
	s_barrier
	s_add_i32 s60, 0, 0x18000
	v_add_u32_e32 v144, s60, v157
	s_add_i32 s61, 0, 0x1c000
	ds_read_b128 v[164:167], v144
	ds_read_b128 v[168:171], v144 offset:1024
	ds_read_b128 v[172:175], v144 offset:2048
	ds_read_b128 v[178:181], v144 offset:3072
	v_add_u32_e32 v144, s61, v157
	ds_read_b128 v[182:185], v144
	ds_read_b128 v[186:189], v144 offset:1024
	ds_read_b128 v[190:193], v144 offset:2048
	ds_read_b128 v[194:197], v144 offset:3072
	s_add_u32 s8, s66, 0xb0000
	s_addc_u32 s9, s67, 0
	s_mov_b32 m0, s72
	v_lshl_add_u64 v[236:237], s[8:9], 0, v[128:129]
	ds_read_b128 v[198:201], v162 offset:32768
	ds_read_b128 v[202:205], v162 offset:33792
	ds_read_b128 v[206:209], v162 offset:34816
	ds_read_b128 v[210:213], v162 offset:35840
	ds_read_b128 v[214:217], v162 offset:36864
	ds_read_b128 v[218:221], v162 offset:37888
	ds_read_b128 v[222:225], v162 offset:38912
	ds_read_b128 v[226:229], v162 offset:39936
	global_load_lds_dwordx4 v[236:237], off
	v_lshl_add_u64 v[236:237], s[8:9], 0, v[132:133]
	s_mov_b32 m0, s73
	s_nop 0
	global_load_lds_dwordx4 v[236:237], off
	s_waitcnt vmcnt(8)
	s_waitcnt lgkmcnt(0)
	s_barrier
	s_setprio 1
	s_waitcnt lgkmcnt(0)
	v_mfma_f32_16x16x32_bf16 v[124:127], v[164:167], v[198:201], v[124:127]
	v_mfma_f32_16x16x32_bf16 v[120:123], v[172:175], v[198:201], v[120:123]
	v_mfma_f32_16x16x32_bf16 v[112:115], v[164:167], v[206:209], v[112:115]
	v_mfma_f32_16x16x32_bf16 v[104:107], v[172:175], v[206:209], v[104:107]
	v_mfma_f32_16x16x32_bf16 v[96:99], v[164:167], v[214:217], v[96:99]
	v_mfma_f32_16x16x32_bf16 v[88:91], v[172:175], v[214:217], v[88:91]
	v_mfma_f32_16x16x32_bf16 v[80:83], v[164:167], v[222:225], v[80:83]
	v_mfma_f32_16x16x32_bf16 v[72:75], v[172:175], v[222:225], v[72:75]
	v_mfma_f32_16x16x32_bf16 v[124:127], v[168:171], v[202:205], v[124:127]
	v_mfma_f32_16x16x32_bf16 v[120:123], v[178:181], v[202:205], v[120:123]
	v_mfma_f32_16x16x32_bf16 v[112:115], v[168:171], v[210:213], v[112:115]
	v_mfma_f32_16x16x32_bf16 v[104:107], v[178:181], v[210:213], v[104:107]
	v_mfma_f32_16x16x32_bf16 v[96:99], v[168:171], v[218:221], v[96:99]
	v_mfma_f32_16x16x32_bf16 v[88:91], v[178:181], v[218:221], v[88:91]
	v_mfma_f32_16x16x32_bf16 v[80:83], v[168:171], v[226:229], v[80:83]
	v_mfma_f32_16x16x32_bf16 v[72:75], v[178:181], v[226:229], v[72:75]
	s_setprio 0
	s_setprio 1
	v_mfma_f32_16x16x32_bf16 v[116:119], v[182:185], v[198:201], v[116:119]
	v_mfma_f32_16x16x32_bf16 v[108:111], v[190:193], v[198:201], v[108:111]
	v_mfma_f32_16x16x32_bf16 v[100:103], v[182:185], v[206:209], v[100:103]
	v_mfma_f32_16x16x32_bf16 v[92:95], v[190:193], v[206:209], v[92:95]
	v_mfma_f32_16x16x32_bf16 v[84:87], v[182:185], v[214:217], v[84:87]
	v_mfma_f32_16x16x32_bf16 v[76:79], v[190:193], v[214:217], v[76:79]
	v_mfma_f32_16x16x32_bf16 v[68:71], v[182:185], v[222:225], v[68:71]
	v_mfma_f32_16x16x32_bf16 v[64:67], v[190:193], v[222:225], v[64:67]
	v_mfma_f32_16x16x32_bf16 v[116:119], v[186:189], v[202:205], v[116:119]
	v_mfma_f32_16x16x32_bf16 v[108:111], v[194:197], v[202:205], v[108:111]
	v_mfma_f32_16x16x32_bf16 v[100:103], v[186:189], v[210:213], v[100:103]
	v_mfma_f32_16x16x32_bf16 v[92:95], v[194:197], v[210:213], v[92:95]
	v_mfma_f32_16x16x32_bf16 v[84:87], v[186:189], v[218:221], v[84:87]
	v_mfma_f32_16x16x32_bf16 v[76:79], v[194:197], v[218:221], v[76:79]
	v_mfma_f32_16x16x32_bf16 v[68:71], v[186:189], v[226:229], v[68:71]
	v_mfma_f32_16x16x32_bf16 v[64:67], v[194:197], v[226:229], v[64:67]
	s_setprio 0
	s_barrier
; #define PG8_STAGE(bufoff, gbase, voff) do { _Pragma("unroll") for (int _i = 0; _i < 2; ++_i) \
;         __builtin_amdgcn_global_load_lds((const unsigned*)((const char*)(gbase) + (voff)[_i]), (PG8_LAS unsigned*)(lds + (bufoff) + ldsw + _i * 8192), 16, 0, 0); } while (0)
; #define PG8_LDA(dst, b, h) do { _Pragma("unroll") for (int m = 0; m < 4; ++m) _Pragma("unroll") for (int k = 0; k < 2; ++k) dst[m][k] = *(const PG8_LAS bf16x8*)(lds + PG8_SA(b, h) + aoff + m * 2048 + k * 1024); } while (0)
; #define PG8_MMA(ai, bj, At, Bt) do { __builtin_amdgcn_s_setprio(1); _Pragma("unroll") for (int m = 0; m < 4; ++m) _Pragma("unroll") for (int n = 0; n < 2; ++n) _Pragma("unroll") for (int k = 0; k < 2; ++k) \
;         acc[ai][bj][m][n] = __builtin_amdgcn_mfma_f32_16x16x32_bf16(Bt[n][k], At[m][k], acc[ai][bj][m][n], 0, 0, 0); __builtin_amdgcn_s_setprio(0); } while (0)
; #define PG8_WAIT_V(n) asm volatile("s_waitcnt vmcnt(" #n ")" ::: "memory")
; #define PG8_WAIT_L(n) asm volatile("s_waitcnt lgkmcnt(" #n ")" ::: "memory")
; #define PG8_BAR __builtin_amdgcn_s_barrier()
; #define PG8_SCHED __builtin_amdgcn_sched_barrier(0)
; template <class Epi, class Sched, bool ALIGN_EPI = false, bool SP2 = false>
; __device__ __forceinline__ void gemm_phase(PG8_LAS unsigned char* lds, const Gemm g, const Sched& S, const Epi& E) {
;     ...
;         for (int t = 0; t < nt; t += 2) {
;     ...
;             PG8_LDA(At, 1, 1); PG8_STAGE(PG8_SB(1, 0), b3, voffB); PG8_STAGE(PG8_SB(1, 1), b3 + hstep, voffB); PG8_STAGE(PG8_SA(1, 0), a3, voffA);
;             PG8_WAIT_V(8); PG8_WAIT_L(0); PG8_BAR; PG8_MMA(1, 0, At, B0); PG8_MMA(1, 1, At, B1); PG8_BAR; PG8_SCHED;
	s_add_i32 s8, s60, s69
	v_lshl_add_u64 v[146:147], v[146:147], 0, s[14:15]
	s_mov_b32 m0, s8
	ds_read_b128 v[198:201], v162 offset:49152
	ds_read_b128 v[202:205], v162 offset:50176
	ds_read_b128 v[206:209], v162 offset:51200
	ds_read_b128 v[210:213], v162 offset:52224
	ds_read_b128 v[214:217], v162 offset:53248
	ds_read_b128 v[218:221], v162 offset:54272
	ds_read_b128 v[222:225], v162 offset:55296
	ds_read_b128 v[226:229], v162 offset:56320
	global_load_lds_dwordx4 v[146:147], off
	s_add_i32 m0, s8, 0x2000
	s_add_u32 s8, s56, 0xb0080
	v_lshl_add_u64 v[146:147], v[230:231], 0, s[14:15]
	s_addc_u32 s9, s57, 0
	s_add_i32 s56, s61, s69
	global_load_lds_dwordx4 v[146:147], off
	v_lshl_add_u64 v[146:147], s[8:9], 0, v[130:131]
	s_mov_b32 m0, s56
	s_nop 0
	global_load_lds_dwordx4 v[146:147], off
	v_lshl_add_u64 v[146:147], s[8:9], 0, v[134:135]
	s_add_i32 m0, s56, 0x2000
	s_nop 0
	global_load_lds_dwordx4 v[146:147], off
	v_lshl_add_u64 v[146:147], v[232:233], 0, s[14:15]
	s_mov_b32 m0, s75
	s_nop 0
	global_load_lds_dwordx4 v[146:147], off
	v_lshl_add_u64 v[146:147], v[234:235], 0, s[14:15]
	s_mov_b32 m0, s76
	s_nop 0
	global_load_lds_dwordx4 v[146:147], off
	s_waitcnt vmcnt(8)
	s_waitcnt lgkmcnt(0)
	s_barrier
	s_setprio 1
	s_waitcnt lgkmcnt(0)
	v_mfma_f32_16x16x32_bf16 v[60:63], v[164:167], v[198:201], v[60:63]
	v_mfma_f32_16x16x32_bf16 v[56:59], v[172:175], v[198:201], v[56:59]
	v_mfma_f32_16x16x32_bf16 v[48:51], v[164:167], v[206:209], v[48:51]
	v_mfma_f32_16x16x32_bf16 v[40:43], v[172:175], v[206:209], v[40:43]
	v_mfma_f32_16x16x32_bf16 v[32:35], v[164:167], v[214:217], v[32:35]
	v_mfma_f32_16x16x32_bf16 v[24:27], v[172:175], v[214:217], v[24:27]
	v_mfma_f32_16x16x32_bf16 v[16:19], v[164:167], v[222:225], v[16:19]
	v_mfma_f32_16x16x32_bf16 v[8:11], v[172:175], v[222:225], v[8:11]
	v_mfma_f32_16x16x32_bf16 v[60:63], v[168:171], v[202:205], v[60:63]
	v_mfma_f32_16x16x32_bf16 v[56:59], v[178:181], v[202:205], v[56:59]
	v_mfma_f32_16x16x32_bf16 v[48:51], v[168:171], v[210:213], v[48:51]
	v_mfma_f32_16x16x32_bf16 v[40:43], v[178:181], v[210:213], v[40:43]
	v_mfma_f32_16x16x32_bf16 v[32:35], v[168:171], v[218:221], v[32:35]
	v_mfma_f32_16x16x32_bf16 v[24:27], v[178:181], v[218:221], v[24:27]
	v_mfma_f32_16x16x32_bf16 v[16:19], v[168:171], v[226:229], v[16:19]
	v_mfma_f32_16x16x32_bf16 v[8:11], v[178:181], v[226:229], v[8:11]
	s_setprio 0
	s_setprio 1
	v_mfma_f32_16x16x32_bf16 v[52:55], v[182:185], v[198:201], v[52:55]
	v_mfma_f32_16x16x32_bf16 v[44:47], v[190:193], v[198:201], v[44:47]
	v_mfma_f32_16x16x32_bf16 v[36:39], v[182:185], v[206:209], v[36:39]
	v_mfma_f32_16x16x32_bf16 v[28:31], v[190:193], v[206:209], v[28:31]
	v_mfma_f32_16x16x32_bf16 v[20:23], v[182:185], v[214:217], v[20:23]
	v_mfma_f32_16x16x32_bf16 v[12:15], v[190:193], v[214:217], v[12:15]
	v_mfma_f32_16x16x32_bf16 v[4:7], v[182:185], v[222:225], v[4:7]
	v_mfma_f32_16x16x32_bf16 v[0:3], v[190:193], v[222:225], v[0:3]
	v_mfma_f32_16x16x32_bf16 v[52:55], v[186:189], v[202:205], v[52:55]
	v_mfma_f32_16x16x32_bf16 v[44:47], v[194:197], v[202:205], v[44:47]
	v_mfma_f32_16x16x32_bf16 v[36:39], v[186:189], v[210:213], v[36:39]
	v_mfma_f32_16x16x32_bf16 v[28:31], v[194:197], v[210:213], v[28:31]
	v_mfma_f32_16x16x32_bf16 v[20:23], v[186:189], v[218:221], v[20:23]
	v_mfma_f32_16x16x32_bf16 v[12:15], v[194:197], v[218:221], v[12:15]
	v_mfma_f32_16x16x32_bf16 v[4:7], v[186:189], v[226:229], v[4:7]
	v_mfma_f32_16x16x32_bf16 v[0:3], v[194:197], v[226:229], v[0:3]
	s_setprio 0
	s_add_i32 s93, s93, 2
	s_add_u32 s54, s54, 0x100
	s_addc_u32 s55, s55, 0
	s_add_u32 s91, s91, 0x100
	s_addc_u32 s92, s92, 0
	s_cmp_gt_u32 s93, 41
	s_barrier
	s_cbranch_scc0 .LBB0_640
	s_and_b64 vcc, exec, s[18:19]
	s_cbranch_vccz .LBB0_643
	s_barrier

; #define PG8_STAGE(bufoff, gbase, voff) do { _Pragma("unroll") for (int _i = 0; _i < 2; ++_i) \
;         __builtin_amdgcn_global_load_lds((const unsigned*)((const char*)(gbase) + (voff)[_i]), (PG8_LAS unsigned*)(lds + (bufoff) + ldsw + _i * 8192), 16, 0, 0); } while (0)
; #define PG8_LDA(dst, b, h) do { _Pragma("unroll") for (int m = 0; m < 4; ++m) _Pragma("unroll") for (int k = 0; k < 2; ++k) dst[m][k] = *(const PG8_LAS bf16x8*)(lds + PG8_SA(b, h) + aoff + m * 2048 + k * 1024); } while (0)
; #define PG8_LDB(dst, b, h) do { _Pragma("unroll") for (int n = 0; n < 2; ++n) _Pragma("unroll") for (int k = 0; k < 2; ++k) dst[n][k] = *(const PG8_LAS bf16x8*)(lds + PG8_SB(b, h) + boff + n * 2048 + k * 1024); } while (0)
; #define PG8_MMA(ai, bj, At, Bt) do { __builtin_amdgcn_s_setprio(1); _Pragma("unroll") for (int m = 0; m < 4; ++m) _Pragma("unroll") for (int n = 0; n < 2; ++n) _Pragma("unroll") for (int k = 0; k < 2; ++k) \
;         acc[ai][bj][m][n] = __builtin_amdgcn_mfma_f32_16x16x32_bf16(Bt[n][k], At[m][k], acc[ai][bj][m][n], 0, 0, 0); __builtin_amdgcn_s_setprio(0); } while (0)
; #define PG8_WAIT_V(n) asm volatile("s_waitcnt vmcnt(" #n ")" ::: "memory")
; #define PG8_WAIT_L(n) asm volatile("s_waitcnt lgkmcnt(" #n ")" ::: "memory")
; #define PG8_BAR __builtin_amdgcn_s_barrier()
; #define PG8_SCHED __builtin_amdgcn_sched_barrier(0)
; template <class Epi, class Sched, bool ALIGN_EPI = false, bool SP2 = false>
; __device__ __forceinline__ void gemm_phase(PG8_LAS unsigned char* lds, const Gemm g, const Sched& S, const Epi& E) {
;     ...
;             const char* a1 = cA + (size_t)(t + 1) * kstep;
;             const char* a2 = last ? nA : cA + (size_t)(t + 2) * kstep; const char* b2 = last ? nB : cB + (size_t)(t + 2) * kstep;
;             const char* a3 = a2 + kstep; const char* b3 = b2 + kstep;
;             if (last && has_next) S.a_ready(nxt);
;             if constexpr (SP2) {
;             PG8_LDB(B0, 0, 0); PG8_LDB(B1, 0, 1); PG8_SCHED; PG8_LDA(At, 0, 0); PG8_STAGE(PG8_SA(1, 1), a1 + hstep, voffA);
;             PG8_WAIT_V(8); PG8_WAIT_L(0); PG8_BAR; PG8_MMA(0, 0, At, B0); PG8_MMA(0, 1, At, B1); PG8_BAR; PG8_SCHED;
;             PG8_LDA(At, 0, 1); PG8_STAGE(PG8_SB(0, 0), b2, voffB); PG8_STAGE(PG8_SB(0, 1), b2 + hstep, voffB); PG8_STAGE(PG8_SA(0, 0), a2, voffA);
.LBB0_836:
	ds_read_b128 v[48:51], v162
	ds_read_b128 v[52:55], v162 offset:1024
	ds_read_b128 v[152:155], v162 offset:2048
	ds_read_b128 v[166:169], v162 offset:3072
	ds_read_b128 v[170:173], v163
	ds_read_b128 v[178:181], v163 offset:1024
	ds_read_b128 v[182:185], v163 offset:2048
	ds_read_b128 v[186:189], v163 offset:3072
	s_add_u32 s8, s64, 0xfffc0080
	s_addc_u32 s9, s65, -1
	s_cmp_eq_u32 s87, 12
	s_cselect_b32 s69, s49, s9
	s_cselect_b32 s68, s55, s8
	s_cselect_b32 s67, s43, s86
	s_cselect_b32 s66, s82, s83
	v_lshl_add_u64 v[156:157], s[64:65], 0, v[144:145]
	s_add_i32 m0, s57, 0xc000
	ds_read_b128 v[190:193], v164
	ds_read_b128 v[194:197], v164 offset:1024
	ds_read_b128 v[198:201], v164 offset:2048
	ds_read_b128 v[202:205], v164 offset:3072
	ds_read_b128 v[206:209], v164 offset:4096
	ds_read_b128 v[210:213], v164 offset:5120
	ds_read_b128 v[214:217], v164 offset:6144
	ds_read_b128 v[218:221], v164 offset:7168
	global_load_lds_dwordx4 v[156:157], off
	v_lshl_add_u64 v[156:157], s[64:65], 0, v[146:147]
	s_add_i32 m0, s57, 0xe000
	s_nop 0
	global_load_lds_dwordx4 v[156:157], off
	s_waitcnt vmcnt(8)
	s_waitcnt lgkmcnt(0)
	s_barrier
	s_setprio 1
	s_waitcnt lgkmcnt(0)
	v_mfma_f32_16x16x32_bf16 v[44:47], v[48:51], v[190:193], v[44:47]
	v_mfma_f32_16x16x32_bf16 v[36:39], v[152:155], v[190:193], v[36:39]
	v_mfma_f32_16x16x32_bf16 v[124:127], v[48:51], v[198:201], v[124:127]
	v_mfma_f32_16x16x32_bf16 v[120:123], v[152:155], v[198:201], v[120:123]
	v_mfma_f32_16x16x32_bf16 v[108:111], v[48:51], v[206:209], v[108:111]
	v_mfma_f32_16x16x32_bf16 v[104:107], v[152:155], v[206:209], v[104:107]
	v_mfma_f32_16x16x32_bf16 v[92:95], v[48:51], v[214:217], v[92:95]
	v_mfma_f32_16x16x32_bf16 v[88:91], v[152:155], v[214:217], v[88:91]
	v_mfma_f32_16x16x32_bf16 v[44:47], v[52:55], v[194:197], v[44:47]
	v_mfma_f32_16x16x32_bf16 v[36:39], v[166:169], v[194:197], v[36:39]
	v_mfma_f32_16x16x32_bf16 v[124:127], v[52:55], v[202:205], v[124:127]
	v_mfma_f32_16x16x32_bf16 v[120:123], v[166:169], v[202:205], v[120:123]
	v_mfma_f32_16x16x32_bf16 v[108:111], v[52:55], v[210:213], v[108:111]
	v_mfma_f32_16x16x32_bf16 v[104:107], v[166:169], v[210:213], v[104:107]
	v_mfma_f32_16x16x32_bf16 v[92:95], v[52:55], v[218:221], v[92:95]
	v_mfma_f32_16x16x32_bf16 v[88:91], v[166:169], v[218:221], v[88:91]
	s_setprio 0
	s_setprio 1
	v_mfma_f32_16x16x32_bf16 v[132:135], v[170:173], v[190:193], v[132:135]
	v_mfma_f32_16x16x32_bf16 v[128:131], v[182:185], v[190:193], v[128:131]
	v_mfma_f32_16x16x32_bf16 v[116:119], v[170:173], v[198:201], v[116:119]
	v_mfma_f32_16x16x32_bf16 v[112:115], v[182:185], v[198:201], v[112:115]
	v_mfma_f32_16x16x32_bf16 v[100:103], v[170:173], v[206:209], v[100:103]
	v_mfma_f32_16x16x32_bf16 v[96:99], v[182:185], v[206:209], v[96:99]
	v_mfma_f32_16x16x32_bf16 v[84:87], v[170:173], v[214:217], v[84:87]
	v_mfma_f32_16x16x32_bf16 v[80:83], v[182:185], v[214:217], v[80:83]
	v_mfma_f32_16x16x32_bf16 v[132:135], v[178:181], v[194:197], v[132:135]
	v_mfma_f32_16x16x32_bf16 v[128:131], v[186:189], v[194:197], v[128:131]
	v_mfma_f32_16x16x32_bf16 v[116:119], v[178:181], v[202:205], v[116:119]
	v_mfma_f32_16x16x32_bf16 v[112:115], v[186:189], v[202:205], v[112:115]
	v_mfma_f32_16x16x32_bf16 v[100:103], v[178:181], v[210:213], v[100:103]
	v_mfma_f32_16x16x32_bf16 v[96:99], v[186:189], v[210:213], v[96:99]
	v_mfma_f32_16x16x32_bf16 v[84:87], v[178:181], v[218:221], v[84:87]
	v_mfma_f32_16x16x32_bf16 v[80:83], v[186:189], v[218:221], v[80:83]
	s_setprio 0
	s_barrier
	s_add_i32 s8, s80, s70
	v_lshl_add_u64 v[156:157], s[66:67], 0, v[138:139]
	s_mov_b32 m0, s8
	ds_read_b128 v[190:193], v164 offset:16384
	ds_read_b128 v[194:197], v164 offset:17408
	ds_read_b128 v[198:201], v164 offset:18432
	ds_read_b128 v[202:205], v164 offset:19456
	ds_read_b128 v[206:209], v164 offset:20480
	ds_read_b128 v[210:213], v164 offset:21504
	ds_read_b128 v[214:217], v164 offset:22528
	ds_read_b128 v[218:221], v164 offset:23552
	global_load_lds_dwordx4 v[156:157], off
	s_add_i32 m0, s8, 0x2000
	s_add_u32 s8, s66, 0x40000
	v_lshl_add_u64 v[174:175], s[66:67], 0, v[142:143]
	s_addc_u32 s9, s67, 0
	s_add_i32 s60, s81, s70
	global_load_lds_dwordx4 v[174:175], off
	v_lshl_add_u64 v[222:223], s[8:9], 0, v[138:139]
	s_mov_b32 m0, s60
	v_lshl_add_u64 v[224:225], s[68:69], 0, v[140:141]
	global_load_lds_dwordx4 v[222:223], off
	v_lshl_add_u64 v[222:223], s[8:9], 0, v[142:143]
	s_add_i32 m0, s60, 0x2000
	s_nop 0
	global_load_lds_dwordx4 v[222:223], off
	v_lshl_add_u64 v[222:223], s[68:69], 0, v[136:137]
	s_mov_b32 m0, s57
	s_nop 0
	global_load_lds_dwordx4 v[222:223], off
	s_mov_b32 m0, s71
	s_nop 0
	global_load_lds_dwordx4 v[224:225], off
	s_waitcnt vmcnt(8)
	s_waitcnt lgkmcnt(0)
	s_barrier
; #define PG8_STAGE(bufoff, gbase, voff) do { _Pragma("unroll") for (int _i = 0; _i < 2; ++_i) \
;         __builtin_amdgcn_global_load_lds((const unsigned*)((const char*)(gbase) + (voff)[_i]), (PG8_LAS unsigned*)(lds + (bufoff) + ldsw + _i * 8192), 16, 0, 0); } while (0)
; #define PG8_LDA(dst, b, h) do { _Pragma("unroll") for (int m = 0; m < 4; ++m) _Pragma("unroll") for (int k = 0; k < 2; ++k) dst[m][k] = *(const PG8_LAS bf16x8*)(lds + PG8_SA(b, h) + aoff + m * 2048 + k * 1024); } while (0)
; #define PG8_LDB(dst, b, h) do { _Pragma("unroll") for (int n = 0; n < 2; ++n) _Pragma("unroll") for (int k = 0; k < 2; ++k) dst[n][k] = *(const PG8_LAS bf16x8*)(lds + PG8_SB(b, h) + boff + n * 2048 + k * 1024); } while (0)
; #define PG8_MMA(ai, bj, At, Bt) do { __builtin_amdgcn_s_setprio(1); _Pragma("unroll") for (int m = 0; m < 4; ++m) _Pragma("unroll") for (int n = 0; n < 2; ++n) _Pragma("unroll") for (int k = 0; k < 2; ++k) \
;         acc[ai][bj][m][n] = __builtin_amdgcn_mfma_f32_16x16x32_bf16(Bt[n][k], At[m][k], acc[ai][bj][m][n], 0, 0, 0); __builtin_amdgcn_s_setprio(0); } while (0)
; #define PG8_WAIT_V(n) asm volatile("s_waitcnt vmcnt(" #n ")" ::: "memory")
; #define PG8_WAIT_L(n) asm volatile("s_waitcnt lgkmcnt(" #n ")" ::: "memory")
; #define PG8_BAR __builtin_amdgcn_s_barrier()
; #define PG8_SCHED __builtin_amdgcn_sched_barrier(0)
; template <class Epi, class Sched, bool ALIGN_EPI = false, bool SP2 = false>
; __device__ __forceinline__ void gemm_phase(PG8_LAS unsigned char* lds, const Gemm g, const Sched& S, const Epi& E) {
;     ...
;             PG8_WAIT_V(8); PG8_WAIT_L(0); PG8_BAR; PG8_MMA(1, 0, At, B0); PG8_MMA(1, 1, At, B1); PG8_BAR; PG8_SCHED;
;             PG8_LDB(B0, 1, 0); PG8_LDB(B1, 1, 1); PG8_SCHED; PG8_LDA(At, 1, 0); PG8_STAGE(PG8_SA(0, 1), a2 + hstep, voffA);
;             PG8_WAIT_V(8); PG8_WAIT_L(0); PG8_BAR; PG8_MMA(0, 0, At, B0); PG8_MMA(0, 1, At, B1); PG8_BAR; PG8_SCHED;
	s_setprio 1
	s_waitcnt lgkmcnt(0)
	v_mfma_f32_16x16x32_bf16 v[76:79], v[48:51], v[190:193], v[76:79]
	v_mfma_f32_16x16x32_bf16 v[72:75], v[152:155], v[190:193], v[72:75]
	v_mfma_f32_16x16x32_bf16 v[60:63], v[48:51], v[198:201], v[60:63]
	v_mfma_f32_16x16x32_bf16 v[56:59], v[152:155], v[198:201], v[56:59]
	v_mfma_f32_16x16x32_bf16 v[28:31], v[48:51], v[206:209], v[28:31]
	v_mfma_f32_16x16x32_bf16 v[24:27], v[152:155], v[206:209], v[24:27]
	v_mfma_f32_16x16x32_bf16 v[12:15], v[48:51], v[214:217], v[12:15]
	v_mfma_f32_16x16x32_bf16 v[8:11], v[152:155], v[214:217], v[8:11]
	v_mfma_f32_16x16x32_bf16 v[76:79], v[52:55], v[194:197], v[76:79]
	v_mfma_f32_16x16x32_bf16 v[72:75], v[166:169], v[194:197], v[72:75]
	v_mfma_f32_16x16x32_bf16 v[60:63], v[52:55], v[202:205], v[60:63]
	v_mfma_f32_16x16x32_bf16 v[56:59], v[166:169], v[202:205], v[56:59]
	v_mfma_f32_16x16x32_bf16 v[28:31], v[52:55], v[210:213], v[28:31]
	v_mfma_f32_16x16x32_bf16 v[24:27], v[166:169], v[210:213], v[24:27]
	v_mfma_f32_16x16x32_bf16 v[12:15], v[52:55], v[218:221], v[12:15]
	v_mfma_f32_16x16x32_bf16 v[8:11], v[166:169], v[218:221], v[8:11]
	s_setprio 0
	s_setprio 1
	v_mfma_f32_16x16x32_bf16 v[40:43], v[170:173], v[198:201], v[40:43]
	v_mfma_f32_16x16x32_bf16 v[32:35], v[182:185], v[198:201], v[32:35]
	v_mfma_f32_16x16x32_bf16 v[20:23], v[170:173], v[206:209], v[20:23]
	v_mfma_f32_16x16x32_bf16 v[16:19], v[182:185], v[206:209], v[16:19]
	v_mfma_f32_16x16x32_bf16 v[4:7], v[170:173], v[214:217], v[4:7]
	v_mfma_f32_16x16x32_bf16 v[0:3], v[182:185], v[214:217], v[0:3]
	v_mfma_f32_16x16x32_bf16 v[48:51], v[170:173], v[190:193], v[68:71]
	v_mfma_f32_16x16x32_bf16 v[52:55], v[182:185], v[190:193], v[64:67]
	v_mfma_f32_16x16x32_bf16 v[40:43], v[178:181], v[202:205], v[40:43]
	v_mfma_f32_16x16x32_bf16 v[32:35], v[186:189], v[202:205], v[32:35]
	v_mfma_f32_16x16x32_bf16 v[20:23], v[178:181], v[210:213], v[20:23]
	v_mfma_f32_16x16x32_bf16 v[16:19], v[186:189], v[210:213], v[16:19]
	v_mfma_f32_16x16x32_bf16 v[4:7], v[178:181], v[218:221], v[4:7]
	v_mfma_f32_16x16x32_bf16 v[0:3], v[186:189], v[218:221], v[0:3]
	v_mfma_f32_16x16x32_bf16 v[48:51], v[178:181], v[194:197], v[48:51]
	v_mfma_f32_16x16x32_bf16 v[52:55], v[186:189], v[194:197], v[52:55]
	s_setprio 0
	s_barrier
	s_add_i32 s60, 0, 0x18000
	s_add_i32 s61, 0, 0x1c000
	v_add_u32_e32 v166, s60, v159
	v_add_u32_e32 v177, s61, v159
	ds_read_b128 v[64:67], v166
	ds_read_b128 v[68:71], v166 offset:1024
	ds_read_b128 v[152:155], v166 offset:2048
	ds_read_b128 v[166:169], v166 offset:3072
	ds_read_b128 v[170:173], v177
	ds_read_b128 v[178:181], v177 offset:1024
	ds_read_b128 v[182:185], v177 offset:2048
	ds_read_b128 v[186:189], v177 offset:3072
	s_add_u32 s8, s68, 0x40000
	s_addc_u32 s9, s69, 0
	s_mov_b32 m0, s72
	v_lshl_add_u64 v[226:227], s[8:9], 0, v[136:137]
	ds_read_b128 v[190:193], v164 offset:32768
	ds_read_b128 v[194:197], v164 offset:33792
	ds_read_b128 v[198:201], v164 offset:34816
	ds_read_b128 v[202:205], v164 offset:35840
	ds_read_b128 v[206:209], v164 offset:36864
	ds_read_b128 v[210:213], v164 offset:37888
	ds_read_b128 v[214:217], v164 offset:38912
	ds_read_b128 v[218:221], v164 offset:39936
	global_load_lds_dwordx4 v[226:227], off
	v_lshl_add_u64 v[226:227], s[8:9], 0, v[140:141]
	s_mov_b32 m0, s73
	s_nop 0
	global_load_lds_dwordx4 v[226:227], off
	s_waitcnt vmcnt(8)
	s_waitcnt lgkmcnt(0)
	s_barrier
	s_setprio 1
	s_waitcnt lgkmcnt(0)
	v_mfma_f32_16x16x32_bf16 v[44:47], v[64:67], v[190:193], v[44:47]
	v_mfma_f32_16x16x32_bf16 v[36:39], v[152:155], v[190:193], v[36:39]
	v_mfma_f32_16x16x32_bf16 v[124:127], v[64:67], v[198:201], v[124:127]
	v_mfma_f32_16x16x32_bf16 v[120:123], v[152:155], v[198:201], v[120:123]
	v_mfma_f32_16x16x32_bf16 v[108:111], v[64:67], v[206:209], v[108:111]
	v_mfma_f32_16x16x32_bf16 v[104:107], v[152:155], v[206:209], v[104:107]
	v_mfma_f32_16x16x32_bf16 v[92:95], v[64:67], v[214:217], v[92:95]
	v_mfma_f32_16x16x32_bf16 v[88:91], v[152:155], v[214:217], v[88:91]
	v_mfma_f32_16x16x32_bf16 v[44:47], v[68:71], v[194:197], v[44:47]
	v_mfma_f32_16x16x32_bf16 v[36:39], v[166:169], v[194:197], v[36:39]
	v_mfma_f32_16x16x32_bf16 v[124:127], v[68:71], v[202:205], v[124:127]
	v_mfma_f32_16x16x32_bf16 v[120:123], v[166:169], v[202:205], v[120:123]
	v_mfma_f32_16x16x32_bf16 v[108:111], v[68:71], v[210:213], v[108:111]
	v_mfma_f32_16x16x32_bf16 v[104:107], v[166:169], v[210:213], v[104:107]
	v_mfma_f32_16x16x32_bf16 v[92:95], v[68:71], v[218:221], v[92:95]
	v_mfma_f32_16x16x32_bf16 v[88:91], v[166:169], v[218:221], v[88:91]
	s_setprio 0
	s_setprio 1
	v_mfma_f32_16x16x32_bf16 v[132:135], v[170:173], v[190:193], v[132:135]
	v_mfma_f32_16x16x32_bf16 v[128:131], v[182:185], v[190:193], v[128:131]
	v_mfma_f32_16x16x32_bf16 v[116:119], v[170:173], v[198:201], v[116:119]
	v_mfma_f32_16x16x32_bf16 v[112:115], v[182:185], v[198:201], v[112:115]
	v_mfma_f32_16x16x32_bf16 v[100:103], v[170:173], v[206:209], v[100:103]
	v_mfma_f32_16x16x32_bf16 v[96:99], v[182:185], v[206:209], v[96:99]
	v_mfma_f32_16x16x32_bf16 v[84:87], v[170:173], v[214:217], v[84:87]
	v_mfma_f32_16x16x32_bf16 v[80:83], v[182:185], v[214:217], v[80:83]
	v_mfma_f32_16x16x32_bf16 v[132:135], v[178:181], v[194:197], v[132:135]
	v_mfma_f32_16x16x32_bf16 v[128:131], v[186:189], v[194:197], v[128:131]
	v_mfma_f32_16x16x32_bf16 v[116:119], v[178:181], v[202:205], v[116:119]
	v_mfma_f32_16x16x32_bf16 v[112:115], v[186:189], v[202:205], v[112:115]
	v_mfma_f32_16x16x32_bf16 v[100:103], v[178:181], v[210:213], v[100:103]
	v_mfma_f32_16x16x32_bf16 v[96:99], v[186:189], v[210:213], v[96:99]
	v_mfma_f32_16x16x32_bf16 v[84:87], v[178:181], v[218:221], v[84:87]
	v_mfma_f32_16x16x32_bf16 v[80:83], v[186:189], v[218:221], v[80:83]
	s_setprio 0
	s_barrier
; #define PG8_STAGE(bufoff, gbase, voff) do { _Pragma("unroll") for (int _i = 0; _i < 2; ++_i) \
;         __builtin_amdgcn_global_load_lds((const unsigned*)((const char*)(gbase) + (voff)[_i]), (PG8_LAS unsigned*)(lds + (bufoff) + ldsw + _i * 8192), 16, 0, 0); } while (0)
; #define PG8_LDA(dst, b, h) do { _Pragma("unroll") for (int m = 0; m < 4; ++m) _Pragma("unroll") for (int k = 0; k < 2; ++k) dst[m][k] = *(const PG8_LAS bf16x8*)(lds + PG8_SA(b, h) + aoff + m * 2048 + k * 1024); } while (0)
; #define PG8_MMA(ai, bj, At, Bt) do { __builtin_amdgcn_s_setprio(1); _Pragma("unroll") for (int m = 0; m < 4; ++m) _Pragma("unroll") for (int n = 0; n < 2; ++n) _Pragma("unroll") for (int k = 0; k < 2; ++k) \
;         acc[ai][bj][m][n] = __builtin_amdgcn_mfma_f32_16x16x32_bf16(Bt[n][k], At[m][k], acc[ai][bj][m][n], 0, 0, 0); __builtin_amdgcn_s_setprio(0); } while (0)
; #define PG8_WAIT_V(n) asm volatile("s_waitcnt vmcnt(" #n ")" ::: "memory")
; #define PG8_WAIT_L(n) asm volatile("s_waitcnt lgkmcnt(" #n ")" ::: "memory")
; #define PG8_BAR __builtin_amdgcn_s_barrier()
; #define PG8_SCHED __builtin_amdgcn_sched_barrier(0)
; template <class Epi, class Sched, bool ALIGN_EPI = false, bool SP2 = false>
; __device__ __forceinline__ void gemm_phase(PG8_LAS unsigned char* lds, const Gemm g, const Sched& S, const Epi& E) {
;     ...
;         for (int t = 0; t < nt; t += 2) {
;     ...
;             PG8_LDA(At, 1, 1); PG8_STAGE(PG8_SB(1, 0), b3, voffB); PG8_STAGE(PG8_SB(1, 1), b3 + hstep, voffB); PG8_STAGE(PG8_SA(1, 0), a3, voffA);
;             PG8_WAIT_V(8); PG8_WAIT_L(0); PG8_BAR; PG8_MMA(1, 0, At, B0); PG8_MMA(1, 1, At, B1); PG8_BAR; PG8_SCHED;
	s_add_i32 s8, s60, s70
	v_lshl_add_u64 v[156:157], v[156:157], 0, s[20:21]
	s_mov_b32 m0, s8
	ds_read_b128 v[190:193], v164 offset:49152
	ds_read_b128 v[194:197], v164 offset:50176
	ds_read_b128 v[198:201], v164 offset:51200
	ds_read_b128 v[202:205], v164 offset:52224
	ds_read_b128 v[206:209], v164 offset:53248
	ds_read_b128 v[210:213], v164 offset:54272
	ds_read_b128 v[214:217], v164 offset:55296
	ds_read_b128 v[218:221], v164 offset:56320
	global_load_lds_dwordx4 v[156:157], off
	s_add_i32 m0, s8, 0x2000
	s_add_u32 s8, s66, 0x40080
	v_lshl_add_u64 v[156:157], v[174:175], 0, s[20:21]
	s_addc_u32 s9, s67, 0
	s_add_i32 s60, s61, s70
	global_load_lds_dwordx4 v[156:157], off
	v_lshl_add_u64 v[156:157], s[8:9], 0, v[138:139]
	s_mov_b32 m0, s60
	s_nop 0
	global_load_lds_dwordx4 v[156:157], off
	v_lshl_add_u64 v[156:157], s[8:9], 0, v[142:143]
	s_add_i32 m0, s60, 0x2000
	s_nop 0
	global_load_lds_dwordx4 v[156:157], off
	v_lshl_add_u64 v[156:157], v[222:223], 0, s[20:21]
	s_mov_b32 m0, s75
	s_nop 0
	global_load_lds_dwordx4 v[156:157], off
	v_lshl_add_u64 v[156:157], v[224:225], 0, s[20:21]
	s_mov_b32 m0, s76
	s_nop 0
	global_load_lds_dwordx4 v[156:157], off
	s_waitcnt vmcnt(8)
	s_waitcnt lgkmcnt(0)
	s_barrier
	s_setprio 1
	s_waitcnt lgkmcnt(0)
	v_mfma_f32_16x16x32_bf16 v[76:79], v[64:67], v[190:193], v[76:79]
	v_mfma_f32_16x16x32_bf16 v[72:75], v[152:155], v[190:193], v[72:75]
	v_mfma_f32_16x16x32_bf16 v[60:63], v[64:67], v[198:201], v[60:63]
	v_mfma_f32_16x16x32_bf16 v[56:59], v[152:155], v[198:201], v[56:59]
	v_mfma_f32_16x16x32_bf16 v[28:31], v[64:67], v[206:209], v[28:31]
	v_mfma_f32_16x16x32_bf16 v[24:27], v[152:155], v[206:209], v[24:27]
	v_mfma_f32_16x16x32_bf16 v[12:15], v[64:67], v[214:217], v[12:15]
	v_mfma_f32_16x16x32_bf16 v[8:11], v[152:155], v[214:217], v[8:11]
	v_mfma_f32_16x16x32_bf16 v[76:79], v[68:71], v[194:197], v[76:79]
	v_mfma_f32_16x16x32_bf16 v[72:75], v[166:169], v[194:197], v[72:75]
	v_mfma_f32_16x16x32_bf16 v[60:63], v[68:71], v[202:205], v[60:63]
	v_mfma_f32_16x16x32_bf16 v[56:59], v[166:169], v[202:205], v[56:59]
	v_mfma_f32_16x16x32_bf16 v[28:31], v[68:71], v[210:213], v[28:31]
	v_mfma_f32_16x16x32_bf16 v[24:27], v[166:169], v[210:213], v[24:27]
	v_mfma_f32_16x16x32_bf16 v[12:15], v[68:71], v[218:221], v[12:15]
	v_mfma_f32_16x16x32_bf16 v[8:11], v[166:169], v[218:221], v[8:11]
	s_setprio 0
	s_setprio 1
	v_mfma_f32_16x16x32_bf16 v[48:51], v[170:173], v[190:193], v[48:51]
	v_mfma_f32_16x16x32_bf16 v[68:71], v[178:181], v[194:197], v[48:51]
	v_mfma_f32_16x16x32_bf16 v[48:51], v[182:185], v[190:193], v[52:55]
	v_mfma_f32_16x16x32_bf16 v[40:43], v[170:173], v[198:201], v[40:43]
	v_mfma_f32_16x16x32_bf16 v[32:35], v[182:185], v[198:201], v[32:35]
	v_mfma_f32_16x16x32_bf16 v[20:23], v[170:173], v[206:209], v[20:23]
	v_mfma_f32_16x16x32_bf16 v[16:19], v[182:185], v[206:209], v[16:19]
	v_mfma_f32_16x16x32_bf16 v[4:7], v[170:173], v[214:217], v[4:7]
	v_mfma_f32_16x16x32_bf16 v[0:3], v[182:185], v[214:217], v[0:3]
	v_mfma_f32_16x16x32_bf16 v[64:67], v[186:189], v[194:197], v[48:51]
	v_mfma_f32_16x16x32_bf16 v[40:43], v[178:181], v[202:205], v[40:43]
	v_mfma_f32_16x16x32_bf16 v[32:35], v[186:189], v[202:205], v[32:35]
	v_mfma_f32_16x16x32_bf16 v[20:23], v[178:181], v[210:213], v[20:23]
	v_mfma_f32_16x16x32_bf16 v[16:19], v[186:189], v[210:213], v[16:19]
	v_mfma_f32_16x16x32_bf16 v[4:7], v[178:181], v[218:221], v[4:7]
	v_mfma_f32_16x16x32_bf16 v[0:3], v[186:189], v[218:221], v[0:3]
	s_setprio 0
	s_add_i32 s87, s87, 2
	s_add_u32 s64, s64, 0x100
	s_addc_u32 s65, s65, 0
	s_add_u32 s83, s83, 0x100
	s_addc_u32 s86, s86, 0
	s_cmp_gt_u32 s87, 13
	s_barrier
	s_cbranch_scc0 .LBB0_836
	s_and_b64 vcc, exec, s[38:39]
	s_cbranch_vccz .LBB0_839
	s_barrier

; #define PG8_STAGE(bufoff, gbase, voff) do { _Pragma("unroll") for (int _i = 0; _i < 2; ++_i) \
;         __builtin_amdgcn_global_load_lds((const unsigned*)((const char*)(gbase) + (voff)[_i]), (PG8_LAS unsigned*)(lds + (bufoff) + ldsw + _i * 8192), 16, 0, 0); } while (0)
; #define PG8_LDA(dst, b, h) do { _Pragma("unroll") for (int m = 0; m < 4; ++m) _Pragma("unroll") for (int k = 0; k < 2; ++k) dst[m][k] = *(const PG8_LAS bf16x8*)(lds + PG8_SA(b, h) + aoff + m * 2048 + k * 1024); } while (0)
; #define PG8_LDB(dst, b, h) do { _Pragma("unroll") for (int n = 0; n < 2; ++n) _Pragma("unroll") for (int k = 0; k < 2; ++k) dst[n][k] = *(const PG8_LAS bf16x8*)(lds + PG8_SB(b, h) + boff + n * 2048 + k * 1024); } while (0)
; #define PG8_MMA(ai, bj, At, Bt) do { __builtin_amdgcn_s_setprio(1); _Pragma("unroll") for (int m = 0; m < 4; ++m) _Pragma("unroll") for (int n = 0; n < 2; ++n) _Pragma("unroll") for (int k = 0; k < 2; ++k) \
;         acc[ai][bj][m][n] = __builtin_amdgcn_mfma_f32_16x16x32_bf16(Bt[n][k], At[m][k], acc[ai][bj][m][n], 0, 0, 0); __builtin_amdgcn_s_setprio(0); } while (0)
; #define PG8_WAIT_V(n) asm volatile("s_waitcnt vmcnt(" #n ")" ::: "memory")
; #define PG8_WAIT_L(n) asm volatile("s_waitcnt lgkmcnt(" #n ")" ::: "memory")
; #define PG8_BAR __builtin_amdgcn_s_barrier()
; #define PG8_SCHED __builtin_amdgcn_sched_barrier(0)
; template <class Epi, class Sched, bool ALIGN_EPI = false, bool SP2 = false>
; __device__ __forceinline__ void gemm_phase(PG8_LAS unsigned char* lds, const Gemm g, const Sched& S, const Epi& E) {
;     ...
;             const char* a1 = cA + (size_t)(t + 1) * kstep;
;             const char* a2 = last ? nA : cA + (size_t)(t + 2) * kstep; const char* b2 = last ? nB : cB + (size_t)(t + 2) * kstep;
;             const char* a3 = a2 + kstep; const char* b3 = b2 + kstep;
;             if (last && has_next) S.a_ready(nxt);
;             if constexpr (SP2) {
;             PG8_LDB(B0, 0, 0); PG8_LDB(B1, 0, 1); PG8_SCHED; PG8_LDA(At, 0, 0); PG8_STAGE(PG8_SA(1, 1), a1 + hstep, voffA);
;             PG8_WAIT_V(8); PG8_WAIT_L(0); PG8_BAR; PG8_MMA(0, 0, At, B0); PG8_MMA(0, 1, At, B1); PG8_BAR; PG8_SCHED;
;             PG8_LDA(At, 0, 1); PG8_STAGE(PG8_SB(0, 0), b2, voffB); PG8_STAGE(PG8_SB(0, 1), b2 + hstep, voffB); PG8_STAGE(PG8_SA(0, 0), a2, voffA);
.LBB0_934:
	ds_read_b128 v[144:147], v155
	ds_read_b128 v[148:151], v155 offset:1024
	ds_read_b128 v[162:165], v155 offset:2048
	ds_read_b128 v[166:169], v155 offset:3072
	ds_read_b128 v[170:173], v156
	ds_read_b128 v[178:181], v156 offset:1024
	ds_read_b128 v[182:185], v156 offset:2048
	ds_read_b128 v[186:189], v156 offset:3072
	s_add_u32 s8, s64, 0xfffc0080
	s_addc_u32 s9, s65, -1
	s_cmp_eq_u32 s96, 12
	s_cselect_b32 s69, s53, s9
	s_cselect_b32 s68, s92, s8
	s_cselect_b32 s67, s51, s95
	s_cselect_b32 s66, s93, s94
	v_lshl_add_u64 v[174:175], s[64:65], 0, v[136:137]
	s_add_i32 m0, s74, 0xc000
	ds_read_b128 v[190:193], v157
	ds_read_b128 v[194:197], v157 offset:1024
	ds_read_b128 v[198:201], v157 offset:2048
	ds_read_b128 v[202:205], v157 offset:3072
	ds_read_b128 v[206:209], v157 offset:4096
	ds_read_b128 v[210:213], v157 offset:5120
	ds_read_b128 v[214:217], v157 offset:6144
	ds_read_b128 v[218:221], v157 offset:7168
	global_load_lds_dwordx4 v[174:175], off
	v_lshl_add_u64 v[174:175], s[64:65], 0, v[138:139]
	s_add_i32 m0, s74, 0xe000
	s_nop 0
	global_load_lds_dwordx4 v[174:175], off
	s_waitcnt vmcnt(8)
	s_waitcnt lgkmcnt(0)
	s_barrier
	s_setprio 1
	s_waitcnt lgkmcnt(0)
	v_mfma_f32_16x16x32_bf16 v[124:127], v[144:147], v[190:193], v[124:127]
	v_mfma_f32_16x16x32_bf16 v[120:123], v[162:165], v[190:193], v[120:123]
	v_mfma_f32_16x16x32_bf16 v[108:111], v[144:147], v[198:201], v[108:111]
	v_mfma_f32_16x16x32_bf16 v[104:107], v[162:165], v[198:201], v[104:107]
	v_mfma_f32_16x16x32_bf16 v[92:95], v[144:147], v[206:209], v[92:95]
	v_mfma_f32_16x16x32_bf16 v[88:91], v[162:165], v[206:209], v[88:91]
	v_mfma_f32_16x16x32_bf16 v[76:79], v[144:147], v[214:217], v[76:79]
	v_mfma_f32_16x16x32_bf16 v[72:75], v[162:165], v[214:217], v[72:75]
	v_mfma_f32_16x16x32_bf16 v[124:127], v[148:151], v[194:197], v[124:127]
	v_mfma_f32_16x16x32_bf16 v[120:123], v[166:169], v[194:197], v[120:123]
	v_mfma_f32_16x16x32_bf16 v[108:111], v[148:151], v[202:205], v[108:111]
	v_mfma_f32_16x16x32_bf16 v[104:107], v[166:169], v[202:205], v[104:107]
	v_mfma_f32_16x16x32_bf16 v[92:95], v[148:151], v[210:213], v[92:95]
	v_mfma_f32_16x16x32_bf16 v[88:91], v[166:169], v[210:213], v[88:91]
	v_mfma_f32_16x16x32_bf16 v[76:79], v[148:151], v[218:221], v[76:79]
	v_mfma_f32_16x16x32_bf16 v[72:75], v[166:169], v[218:221], v[72:75]
	s_setprio 0
	s_setprio 1
	v_mfma_f32_16x16x32_bf16 v[116:119], v[170:173], v[190:193], v[116:119]
	v_mfma_f32_16x16x32_bf16 v[112:115], v[182:185], v[190:193], v[112:115]
	v_mfma_f32_16x16x32_bf16 v[100:103], v[170:173], v[198:201], v[100:103]
	v_mfma_f32_16x16x32_bf16 v[96:99], v[182:185], v[198:201], v[96:99]
	v_mfma_f32_16x16x32_bf16 v[84:87], v[170:173], v[206:209], v[84:87]
	v_mfma_f32_16x16x32_bf16 v[80:83], v[182:185], v[206:209], v[80:83]
	v_mfma_f32_16x16x32_bf16 v[68:71], v[170:173], v[214:217], v[68:71]
	v_mfma_f32_16x16x32_bf16 v[64:67], v[182:185], v[214:217], v[64:67]
	v_mfma_f32_16x16x32_bf16 v[116:119], v[178:181], v[194:197], v[116:119]
	v_mfma_f32_16x16x32_bf16 v[112:115], v[186:189], v[194:197], v[112:115]
	v_mfma_f32_16x16x32_bf16 v[100:103], v[178:181], v[202:205], v[100:103]
	v_mfma_f32_16x16x32_bf16 v[96:99], v[186:189], v[202:205], v[96:99]
	v_mfma_f32_16x16x32_bf16 v[84:87], v[178:181], v[210:213], v[84:87]
	v_mfma_f32_16x16x32_bf16 v[80:83], v[186:189], v[210:213], v[80:83]
	v_mfma_f32_16x16x32_bf16 v[68:71], v[178:181], v[218:221], v[68:71]
	v_mfma_f32_16x16x32_bf16 v[64:67], v[186:189], v[218:221], v[64:67]
	s_setprio 0
	s_barrier
	s_add_i32 s8, s83, s73
	v_lshl_add_u64 v[174:175], s[66:67], 0, v[130:131]
	s_mov_b32 m0, s8
	ds_read_b128 v[190:193], v157 offset:16384
	ds_read_b128 v[194:197], v157 offset:17408
	ds_read_b128 v[198:201], v157 offset:18432
	ds_read_b128 v[202:205], v157 offset:19456
	ds_read_b128 v[206:209], v157 offset:20480
	ds_read_b128 v[210:213], v157 offset:21504
	ds_read_b128 v[214:217], v157 offset:22528
	ds_read_b128 v[218:221], v157 offset:23552
	global_load_lds_dwordx4 v[174:175], off
	s_add_i32 m0, s8, 0x2000
	s_add_u32 s8, s66, 0x40000
	v_lshl_add_u64 v[222:223], s[66:67], 0, v[134:135]
	s_addc_u32 s9, s67, 0
	s_add_i32 s60, s86, s73
	global_load_lds_dwordx4 v[222:223], off
	v_lshl_add_u64 v[224:225], s[8:9], 0, v[130:131]
	s_mov_b32 m0, s60
	v_lshl_add_u64 v[226:227], s[68:69], 0, v[132:133]
	global_load_lds_dwordx4 v[224:225], off
	v_lshl_add_u64 v[224:225], s[8:9], 0, v[134:135]
	s_add_i32 m0, s60, 0x2000
	s_nop 0
	global_load_lds_dwordx4 v[224:225], off
	v_lshl_add_u64 v[224:225], s[68:69], 0, v[128:129]
	s_mov_b32 m0, s74
	s_nop 0
	global_load_lds_dwordx4 v[224:225], off
	s_mov_b32 m0, s75
	s_nop 0
	global_load_lds_dwordx4 v[226:227], off
	s_waitcnt vmcnt(8)
	s_waitcnt lgkmcnt(0)
	s_barrier
; #define PG8_STAGE(bufoff, gbase, voff) do { _Pragma("unroll") for (int _i = 0; _i < 2; ++_i) \
;         __builtin_amdgcn_global_load_lds((const unsigned*)((const char*)(gbase) + (voff)[_i]), (PG8_LAS unsigned*)(lds + (bufoff) + ldsw + _i * 8192), 16, 0, 0); } while (0)
; #define PG8_LDA(dst, b, h) do { _Pragma("unroll") for (int m = 0; m < 4; ++m) _Pragma("unroll") for (int k = 0; k < 2; ++k) dst[m][k] = *(const PG8_LAS bf16x8*)(lds + PG8_SA(b, h) + aoff + m * 2048 + k * 1024); } while (0)
; #define PG8_LDB(dst, b, h) do { _Pragma("unroll") for (int n = 0; n < 2; ++n) _Pragma("unroll") for (int k = 0; k < 2; ++k) dst[n][k] = *(const PG8_LAS bf16x8*)(lds + PG8_SB(b, h) + boff + n * 2048 + k * 1024); } while (0)
; #define PG8_MMA(ai, bj, At, Bt) do { __builtin_amdgcn_s_setprio(1); _Pragma("unroll") for (int m = 0; m < 4; ++m) _Pragma("unroll") for (int n = 0; n < 2; ++n) _Pragma("unroll") for (int k = 0; k < 2; ++k) \
;         acc[ai][bj][m][n] = __builtin_amdgcn_mfma_f32_16x16x32_bf16(Bt[n][k], At[m][k], acc[ai][bj][m][n], 0, 0, 0); __builtin_amdgcn_s_setprio(0); } while (0)
; #define PG8_WAIT_V(n) asm volatile("s_waitcnt vmcnt(" #n ")" ::: "memory")
; #define PG8_WAIT_L(n) asm volatile("s_waitcnt lgkmcnt(" #n ")" ::: "memory")
; #define PG8_BAR __builtin_amdgcn_s_barrier()
; #define PG8_SCHED __builtin_amdgcn_sched_barrier(0)
; template <class Epi, class Sched, bool ALIGN_EPI = false, bool SP2 = false>
; __device__ __forceinline__ void gemm_phase(PG8_LAS unsigned char* lds, const Gemm g, const Sched& S, const Epi& E) {
;     ...
;             PG8_WAIT_V(8); PG8_WAIT_L(0); PG8_BAR; PG8_MMA(1, 0, At, B0); PG8_MMA(1, 1, At, B1); PG8_BAR; PG8_SCHED;
;             PG8_LDB(B0, 1, 0); PG8_LDB(B1, 1, 1); PG8_SCHED; PG8_LDA(At, 1, 0); PG8_STAGE(PG8_SA(0, 1), a2 + hstep, voffA);
;             PG8_WAIT_V(8); PG8_WAIT_L(0); PG8_BAR; PG8_MMA(0, 0, At, B0); PG8_MMA(0, 1, At, B1); PG8_BAR; PG8_SCHED;
	s_setprio 1
	s_waitcnt lgkmcnt(0)
	v_mfma_f32_16x16x32_bf16 v[60:63], v[144:147], v[190:193], v[60:63]
	v_mfma_f32_16x16x32_bf16 v[56:59], v[162:165], v[190:193], v[56:59]
	v_mfma_f32_16x16x32_bf16 v[44:47], v[144:147], v[198:201], v[44:47]
	v_mfma_f32_16x16x32_bf16 v[40:43], v[162:165], v[198:201], v[40:43]
	v_mfma_f32_16x16x32_bf16 v[28:31], v[144:147], v[206:209], v[28:31]
	v_mfma_f32_16x16x32_bf16 v[24:27], v[162:165], v[206:209], v[24:27]
	v_mfma_f32_16x16x32_bf16 v[12:15], v[144:147], v[214:217], v[12:15]
	v_mfma_f32_16x16x32_bf16 v[8:11], v[162:165], v[214:217], v[8:11]
	v_mfma_f32_16x16x32_bf16 v[60:63], v[148:151], v[194:197], v[60:63]
	v_mfma_f32_16x16x32_bf16 v[56:59], v[166:169], v[194:197], v[56:59]
	v_mfma_f32_16x16x32_bf16 v[44:47], v[148:151], v[202:205], v[44:47]
	v_mfma_f32_16x16x32_bf16 v[40:43], v[166:169], v[202:205], v[40:43]
	v_mfma_f32_16x16x32_bf16 v[28:31], v[148:151], v[210:213], v[28:31]
	v_mfma_f32_16x16x32_bf16 v[24:27], v[166:169], v[210:213], v[24:27]
	v_mfma_f32_16x16x32_bf16 v[12:15], v[148:151], v[218:221], v[12:15]
	v_mfma_f32_16x16x32_bf16 v[8:11], v[166:169], v[218:221], v[8:11]
	s_setprio 0
	s_setprio 1
	v_mfma_f32_16x16x32_bf16 v[52:55], v[170:173], v[190:193], v[52:55]
	v_mfma_f32_16x16x32_bf16 v[48:51], v[182:185], v[190:193], v[48:51]
	v_mfma_f32_16x16x32_bf16 v[36:39], v[170:173], v[198:201], v[36:39]
	v_mfma_f32_16x16x32_bf16 v[32:35], v[182:185], v[198:201], v[32:35]
	v_mfma_f32_16x16x32_bf16 v[20:23], v[170:173], v[206:209], v[20:23]
	v_mfma_f32_16x16x32_bf16 v[16:19], v[182:185], v[206:209], v[16:19]
	v_mfma_f32_16x16x32_bf16 v[4:7], v[170:173], v[214:217], v[4:7]
	v_mfma_f32_16x16x32_bf16 v[0:3], v[182:185], v[214:217], v[0:3]
	v_mfma_f32_16x16x32_bf16 v[52:55], v[178:181], v[194:197], v[52:55]
	v_mfma_f32_16x16x32_bf16 v[48:51], v[186:189], v[194:197], v[48:51]
	v_mfma_f32_16x16x32_bf16 v[36:39], v[178:181], v[202:205], v[36:39]
	v_mfma_f32_16x16x32_bf16 v[32:35], v[186:189], v[202:205], v[32:35]
	v_mfma_f32_16x16x32_bf16 v[20:23], v[178:181], v[210:213], v[20:23]
	v_mfma_f32_16x16x32_bf16 v[16:19], v[186:189], v[210:213], v[16:19]
	v_mfma_f32_16x16x32_bf16 v[4:7], v[178:181], v[218:221], v[4:7]
	v_mfma_f32_16x16x32_bf16 v[0:3], v[186:189], v[218:221], v[0:3]
	s_setprio 0
	s_barrier
	s_add_i32 s60, 0, 0x18000
	v_add_u32_e32 v161, s60, v153
	s_add_i32 s61, 0, 0x1c000
	ds_read_b128 v[144:147], v161
	ds_read_b128 v[148:151], v161 offset:1024
	ds_read_b128 v[162:165], v161 offset:2048
	ds_read_b128 v[166:169], v161 offset:3072
	v_add_u32_e32 v161, s61, v153
	ds_read_b128 v[170:173], v161
	ds_read_b128 v[178:181], v161 offset:1024
	ds_read_b128 v[182:185], v161 offset:2048
	ds_read_b128 v[186:189], v161 offset:3072
	s_add_u32 s8, s68, 0x40000
	s_addc_u32 s9, s69, 0
	s_mov_b32 m0, s76
	v_lshl_add_u64 v[228:229], s[8:9], 0, v[128:129]
	ds_read_b128 v[190:193], v157 offset:32768
	ds_read_b128 v[194:197], v157 offset:33792
	ds_read_b128 v[198:201], v157 offset:34816
	ds_read_b128 v[202:205], v157 offset:35840
	ds_read_b128 v[206:209], v157 offset:36864
	ds_read_b128 v[210:213], v157 offset:37888
	ds_read_b128 v[214:217], v157 offset:38912
	ds_read_b128 v[218:221], v157 offset:39936
	global_load_lds_dwordx4 v[228:229], off
	v_lshl_add_u64 v[228:229], s[8:9], 0, v[132:133]
	s_mov_b32 m0, s77
	s_nop 0
	global_load_lds_dwordx4 v[228:229], off
	s_waitcnt vmcnt(8)
	s_waitcnt lgkmcnt(0)
	s_barrier
	s_setprio 1
	s_waitcnt lgkmcnt(0)
	v_mfma_f32_16x16x32_bf16 v[124:127], v[144:147], v[190:193], v[124:127]
	v_mfma_f32_16x16x32_bf16 v[120:123], v[162:165], v[190:193], v[120:123]
	v_mfma_f32_16x16x32_bf16 v[108:111], v[144:147], v[198:201], v[108:111]
	v_mfma_f32_16x16x32_bf16 v[104:107], v[162:165], v[198:201], v[104:107]
	v_mfma_f32_16x16x32_bf16 v[92:95], v[144:147], v[206:209], v[92:95]
	v_mfma_f32_16x16x32_bf16 v[88:91], v[162:165], v[206:209], v[88:91]
	v_mfma_f32_16x16x32_bf16 v[76:79], v[144:147], v[214:217], v[76:79]
	v_mfma_f32_16x16x32_bf16 v[72:75], v[162:165], v[214:217], v[72:75]
	v_mfma_f32_16x16x32_bf16 v[124:127], v[148:151], v[194:197], v[124:127]
	v_mfma_f32_16x16x32_bf16 v[120:123], v[166:169], v[194:197], v[120:123]
	v_mfma_f32_16x16x32_bf16 v[108:111], v[148:151], v[202:205], v[108:111]
	v_mfma_f32_16x16x32_bf16 v[104:107], v[166:169], v[202:205], v[104:107]
	v_mfma_f32_16x16x32_bf16 v[92:95], v[148:151], v[210:213], v[92:95]
	v_mfma_f32_16x16x32_bf16 v[88:91], v[166:169], v[210:213], v[88:91]
	v_mfma_f32_16x16x32_bf16 v[76:79], v[148:151], v[218:221], v[76:79]
	v_mfma_f32_16x16x32_bf16 v[72:75], v[166:169], v[218:221], v[72:75]
	s_setprio 0
	s_setprio 1
	v_mfma_f32_16x16x32_bf16 v[116:119], v[170:173], v[190:193], v[116:119]
	v_mfma_f32_16x16x32_bf16 v[112:115], v[182:185], v[190:193], v[112:115]
	v_mfma_f32_16x16x32_bf16 v[100:103], v[170:173], v[198:201], v[100:103]
	v_mfma_f32_16x16x32_bf16 v[96:99], v[182:185], v[198:201], v[96:99]
	v_mfma_f32_16x16x32_bf16 v[84:87], v[170:173], v[206:209], v[84:87]
	v_mfma_f32_16x16x32_bf16 v[80:83], v[182:185], v[206:209], v[80:83]
	v_mfma_f32_16x16x32_bf16 v[68:71], v[170:173], v[214:217], v[68:71]
	v_mfma_f32_16x16x32_bf16 v[64:67], v[182:185], v[214:217], v[64:67]
	v_mfma_f32_16x16x32_bf16 v[116:119], v[178:181], v[194:197], v[116:119]
	v_mfma_f32_16x16x32_bf16 v[112:115], v[186:189], v[194:197], v[112:115]
	v_mfma_f32_16x16x32_bf16 v[100:103], v[178:181], v[202:205], v[100:103]
	v_mfma_f32_16x16x32_bf16 v[96:99], v[186:189], v[202:205], v[96:99]
	v_mfma_f32_16x16x32_bf16 v[84:87], v[178:181], v[210:213], v[84:87]
	v_mfma_f32_16x16x32_bf16 v[80:83], v[186:189], v[210:213], v[80:83]
	v_mfma_f32_16x16x32_bf16 v[68:71], v[178:181], v[218:221], v[68:71]
	v_mfma_f32_16x16x32_bf16 v[64:67], v[186:189], v[218:221], v[64:67]
	s_setprio 0
	s_barrier
; #define PG8_STAGE(bufoff, gbase, voff) do { _Pragma("unroll") for (int _i = 0; _i < 2; ++_i) \
;         __builtin_amdgcn_global_load_lds((const unsigned*)((const char*)(gbase) + (voff)[_i]), (PG8_LAS unsigned*)(lds + (bufoff) + ldsw + _i * 8192), 16, 0, 0); } while (0)
; #define PG8_LDA(dst, b, h) do { _Pragma("unroll") for (int m = 0; m < 4; ++m) _Pragma("unroll") for (int k = 0; k < 2; ++k) dst[m][k] = *(const PG8_LAS bf16x8*)(lds + PG8_SA(b, h) + aoff + m * 2048 + k * 1024); } while (0)
; #define PG8_MMA(ai, bj, At, Bt) do { __builtin_amdgcn_s_setprio(1); _Pragma("unroll") for (int m = 0; m < 4; ++m) _Pragma("unroll") for (int n = 0; n < 2; ++n) _Pragma("unroll") for (int k = 0; k < 2; ++k) \
;         acc[ai][bj][m][n] = __builtin_amdgcn_mfma_f32_16x16x32_bf16(Bt[n][k], At[m][k], acc[ai][bj][m][n], 0, 0, 0); __builtin_amdgcn_s_setprio(0); } while (0)
; #define PG8_WAIT_V(n) asm volatile("s_waitcnt vmcnt(" #n ")" ::: "memory")
; #define PG8_WAIT_L(n) asm volatile("s_waitcnt lgkmcnt(" #n ")" ::: "memory")
; #define PG8_BAR __builtin_amdgcn_s_barrier()
; #define PG8_SCHED __builtin_amdgcn_sched_barrier(0)
; template <class Epi, class Sched, bool ALIGN_EPI = false, bool SP2 = false>
; __device__ __forceinline__ void gemm_phase(PG8_LAS unsigned char* lds, const Gemm g, const Sched& S, const Epi& E) {
;     ...
;         for (int t = 0; t < nt; t += 2) {
;     ...
;             PG8_LDA(At, 1, 1); PG8_STAGE(PG8_SB(1, 0), b3, voffB); PG8_STAGE(PG8_SB(1, 1), b3 + hstep, voffB); PG8_STAGE(PG8_SA(1, 0), a3, voffA);
;             PG8_WAIT_V(8); PG8_WAIT_L(0); PG8_BAR; PG8_MMA(1, 0, At, B0); PG8_MMA(1, 1, At, B1); PG8_BAR; PG8_SCHED;
	s_add_i32 s8, s60, s73
	v_lshl_add_u64 v[174:175], v[174:175], 0, s[14:15]
	s_mov_b32 m0, s8
	ds_read_b128 v[190:193], v157 offset:49152
	ds_read_b128 v[194:197], v157 offset:50176
	ds_read_b128 v[198:201], v157 offset:51200
	ds_read_b128 v[202:205], v157 offset:52224
	ds_read_b128 v[206:209], v157 offset:53248
	ds_read_b128 v[210:213], v157 offset:54272
	ds_read_b128 v[214:217], v157 offset:55296
	ds_read_b128 v[218:221], v157 offset:56320
	global_load_lds_dwordx4 v[174:175], off
	s_add_i32 m0, s8, 0x2000
	s_add_u32 s8, s66, 0x40080
	v_lshl_add_u64 v[174:175], v[222:223], 0, s[14:15]
	s_addc_u32 s9, s67, 0
	s_add_i32 s60, s61, s73
	global_load_lds_dwordx4 v[174:175], off
	v_lshl_add_u64 v[174:175], s[8:9], 0, v[130:131]
	s_mov_b32 m0, s60
	s_nop 0
	global_load_lds_dwordx4 v[174:175], off
	v_lshl_add_u64 v[174:175], s[8:9], 0, v[134:135]
	s_add_i32 m0, s60, 0x2000
	s_nop 0
	global_load_lds_dwordx4 v[174:175], off
	v_lshl_add_u64 v[174:175], v[224:225], 0, s[14:15]
	s_mov_b32 m0, s79
	s_nop 0
	global_load_lds_dwordx4 v[174:175], off
	v_lshl_add_u64 v[174:175], v[226:227], 0, s[14:15]
	s_mov_b32 m0, s80
	s_nop 0
	global_load_lds_dwordx4 v[174:175], off
	s_waitcnt vmcnt(8)
	s_waitcnt lgkmcnt(0)
	s_barrier
	s_setprio 1
	s_waitcnt lgkmcnt(0)
	v_mfma_f32_16x16x32_bf16 v[60:63], v[144:147], v[190:193], v[60:63]
	v_mfma_f32_16x16x32_bf16 v[56:59], v[162:165], v[190:193], v[56:59]
	v_mfma_f32_16x16x32_bf16 v[44:47], v[144:147], v[198:201], v[44:47]
	v_mfma_f32_16x16x32_bf16 v[40:43], v[162:165], v[198:201], v[40:43]
	v_mfma_f32_16x16x32_bf16 v[28:31], v[144:147], v[206:209], v[28:31]
	v_mfma_f32_16x16x32_bf16 v[24:27], v[162:165], v[206:209], v[24:27]
	v_mfma_f32_16x16x32_bf16 v[12:15], v[144:147], v[214:217], v[12:15]
	v_mfma_f32_16x16x32_bf16 v[8:11], v[162:165], v[214:217], v[8:11]
	v_mfma_f32_16x16x32_bf16 v[60:63], v[148:151], v[194:197], v[60:63]
	v_mfma_f32_16x16x32_bf16 v[56:59], v[166:169], v[194:197], v[56:59]
	v_mfma_f32_16x16x32_bf16 v[44:47], v[148:151], v[202:205], v[44:47]
	v_mfma_f32_16x16x32_bf16 v[40:43], v[166:169], v[202:205], v[40:43]
	v_mfma_f32_16x16x32_bf16 v[28:31], v[148:151], v[210:213], v[28:31]
	v_mfma_f32_16x16x32_bf16 v[24:27], v[166:169], v[210:213], v[24:27]
	v_mfma_f32_16x16x32_bf16 v[12:15], v[148:151], v[218:221], v[12:15]
	v_mfma_f32_16x16x32_bf16 v[8:11], v[166:169], v[218:221], v[8:11]
	s_setprio 0
	s_setprio 1
	v_mfma_f32_16x16x32_bf16 v[52:55], v[170:173], v[190:193], v[52:55]
	v_mfma_f32_16x16x32_bf16 v[48:51], v[182:185], v[190:193], v[48:51]
	v_mfma_f32_16x16x32_bf16 v[36:39], v[170:173], v[198:201], v[36:39]
	v_mfma_f32_16x16x32_bf16 v[32:35], v[182:185], v[198:201], v[32:35]
	v_mfma_f32_16x16x32_bf16 v[20:23], v[170:173], v[206:209], v[20:23]
	v_mfma_f32_16x16x32_bf16 v[16:19], v[182:185], v[206:209], v[16:19]
	v_mfma_f32_16x16x32_bf16 v[4:7], v[170:173], v[214:217], v[4:7]
	v_mfma_f32_16x16x32_bf16 v[0:3], v[182:185], v[214:217], v[0:3]
	v_mfma_f32_16x16x32_bf16 v[52:55], v[178:181], v[194:197], v[52:55]
	v_mfma_f32_16x16x32_bf16 v[48:51], v[186:189], v[194:197], v[48:51]
	v_mfma_f32_16x16x32_bf16 v[36:39], v[178:181], v[202:205], v[36:39]
	v_mfma_f32_16x16x32_bf16 v[32:35], v[186:189], v[202:205], v[32:35]
	v_mfma_f32_16x16x32_bf16 v[20:23], v[178:181], v[210:213], v[20:23]
	v_mfma_f32_16x16x32_bf16 v[16:19], v[186:189], v[210:213], v[16:19]
	v_mfma_f32_16x16x32_bf16 v[4:7], v[178:181], v[218:221], v[4:7]
	v_mfma_f32_16x16x32_bf16 v[0:3], v[186:189], v[218:221], v[0:3]
	s_setprio 0
	s_add_i32 s96, s96, 2
	s_add_u32 s64, s64, 0x100
	s_addc_u32 s65, s65, 0
	s_add_u32 s94, s94, 0x100
	s_addc_u32 s95, s95, 0
	s_cmp_gt_u32 s96, 13
	s_barrier
	s_cbranch_scc0 .LBB0_934
	s_and_b64 vcc, exec, s[18:19]
	s_cbranch_vccz .LBB0_937
	s_barrier

; #define PG8_STAGE(bufoff, gbase, voff) do { _Pragma("unroll") for (int _i = 0; _i < 2; ++_i) \
;         __builtin_amdgcn_global_load_lds((const unsigned*)((const char*)(gbase) + (voff)[_i]), (PG8_LAS unsigned*)(lds + (bufoff) + ldsw + _i * 8192), 16, 0, 0); } while (0)
; #define PG8_LDA(dst, b, h) do { _Pragma("unroll") for (int m = 0; m < 4; ++m) _Pragma("unroll") for (int k = 0; k < 2; ++k) dst[m][k] = *(const PG8_LAS bf16x8*)(lds + PG8_SA(b, h) + aoff + m * 2048 + k * 1024); } while (0)
; #define PG8_LDB(dst, b, h) do { _Pragma("unroll") for (int n = 0; n < 2; ++n) _Pragma("unroll") for (int k = 0; k < 2; ++k) dst[n][k] = *(const PG8_LAS bf16x8*)(lds + PG8_SB(b, h) + boff + n * 2048 + k * 1024); } while (0)
; #define PG8_MMA(ai, bj, At, Bt) do { __builtin_amdgcn_s_setprio(1); _Pragma("unroll") for (int m = 0; m < 4; ++m) _Pragma("unroll") for (int n = 0; n < 2; ++n) _Pragma("unroll") for (int k = 0; k < 2; ++k) \
;         acc[ai][bj][m][n] = __builtin_amdgcn_mfma_f32_16x16x32_bf16(Bt[n][k], At[m][k], acc[ai][bj][m][n], 0, 0, 0); __builtin_amdgcn_s_setprio(0); } while (0)
; #define PG8_WAIT_V(n) asm volatile("s_waitcnt vmcnt(" #n ")" ::: "memory")
; #define PG8_WAIT_L(n) asm volatile("s_waitcnt lgkmcnt(" #n ")" ::: "memory")
; #define PG8_BAR __builtin_amdgcn_s_barrier()
; #define PG8_SCHED __builtin_amdgcn_sched_barrier(0)
; template <class Epi, class Sched, bool ALIGN_EPI = false, bool SP2 = false>
; __device__ __forceinline__ void gemm_phase(PG8_LAS unsigned char* lds, const Gemm g, const Sched& S, const Epi& E) {
;     ...
;             const char* a1 = cA + (size_t)(t + 1) * kstep;
;             const char* a2 = last ? nA : cA + (size_t)(t + 2) * kstep; const char* b2 = last ? nB : cB + (size_t)(t + 2) * kstep;
;             const char* a3 = a2 + kstep; const char* b3 = b2 + kstep;
;             if (last && has_next) S.a_ready(nxt);
;             if constexpr (SP2) {
;             PG8_LDB(B0, 0, 0); PG8_LDB(B1, 0, 1); PG8_SCHED; PG8_LDA(At, 0, 0); PG8_STAGE(PG8_SA(1, 1), a1 + hstep, voffA);
;             PG8_WAIT_V(8); PG8_WAIT_L(0); PG8_BAR; PG8_MMA(0, 0, At, B0); PG8_MMA(0, 1, At, B1); PG8_BAR; PG8_SCHED;
;             PG8_LDA(At, 0, 1); PG8_STAGE(PG8_SB(0, 0), b2, voffB); PG8_STAGE(PG8_SB(0, 1), b2 + hstep, voffB); PG8_STAGE(PG8_SA(0, 0), a2, voffA);
.LBB0_1172:
	ds_read_b128 v[154:157], v150
	ds_read_b128 v[162:165], v150 offset:1024
	ds_read_b128 v[166:169], v150 offset:2048
	ds_read_b128 v[170:173], v150 offset:3072
	ds_read_b128 v[178:181], v151
	ds_read_b128 v[182:185], v151 offset:1024
	ds_read_b128 v[186:189], v151 offset:2048
	ds_read_b128 v[190:193], v151 offset:3072
	s_add_u32 s8, s52, 0xfffc0080
	s_addc_u32 s9, s53, -1
	s_cmp_eq_u32 s87, 12
	s_cselect_b32 s57, s45, s9
	s_cselect_b32 s56, s81, s8
	s_cselect_b32 s55, s43, s86
	s_cselect_b32 s54, s82, s83
	v_lshl_add_u64 v[146:147], s[52:53], 0, v[136:137]
	s_add_i32 m0, s51, 0xc000
	ds_read_b128 v[194:197], v152
	ds_read_b128 v[198:201], v152 offset:1024
	ds_read_b128 v[202:205], v152 offset:2048
	ds_read_b128 v[206:209], v152 offset:3072
	ds_read_b128 v[210:213], v152 offset:4096
	ds_read_b128 v[214:217], v152 offset:5120
	ds_read_b128 v[218:221], v152 offset:6144
	ds_read_b128 v[222:225], v152 offset:7168
	global_load_lds_dwordx4 v[146:147], off
	v_lshl_add_u64 v[146:147], s[52:53], 0, v[138:139]
	s_add_i32 m0, s51, 0xe000
	s_nop 0
	global_load_lds_dwordx4 v[146:147], off
	s_waitcnt vmcnt(8)
	s_waitcnt lgkmcnt(0)
	s_barrier
	s_setprio 1
	s_waitcnt lgkmcnt(0)
	v_mfma_f32_16x16x32_bf16 v[124:127], v[154:157], v[194:197], v[124:127]
	v_mfma_f32_16x16x32_bf16 v[120:123], v[166:169], v[194:197], v[120:123]
	v_mfma_f32_16x16x32_bf16 v[112:115], v[154:157], v[202:205], v[112:115]
	v_mfma_f32_16x16x32_bf16 v[104:107], v[166:169], v[202:205], v[104:107]
	v_mfma_f32_16x16x32_bf16 v[96:99], v[154:157], v[210:213], v[96:99]
	v_mfma_f32_16x16x32_bf16 v[88:91], v[166:169], v[210:213], v[88:91]
	v_mfma_f32_16x16x32_bf16 v[80:83], v[154:157], v[218:221], v[80:83]
	v_mfma_f32_16x16x32_bf16 v[72:75], v[166:169], v[218:221], v[72:75]
	v_mfma_f32_16x16x32_bf16 v[124:127], v[162:165], v[198:201], v[124:127]
	v_mfma_f32_16x16x32_bf16 v[120:123], v[170:173], v[198:201], v[120:123]
	v_mfma_f32_16x16x32_bf16 v[112:115], v[162:165], v[206:209], v[112:115]
	v_mfma_f32_16x16x32_bf16 v[104:107], v[170:173], v[206:209], v[104:107]
	v_mfma_f32_16x16x32_bf16 v[96:99], v[162:165], v[214:217], v[96:99]
	v_mfma_f32_16x16x32_bf16 v[88:91], v[170:173], v[214:217], v[88:91]
	v_mfma_f32_16x16x32_bf16 v[80:83], v[162:165], v[222:225], v[80:83]
	v_mfma_f32_16x16x32_bf16 v[72:75], v[170:173], v[222:225], v[72:75]
	s_setprio 0
	s_setprio 1
	v_mfma_f32_16x16x32_bf16 v[116:119], v[178:181], v[194:197], v[116:119]
	v_mfma_f32_16x16x32_bf16 v[108:111], v[186:189], v[194:197], v[108:111]
	v_mfma_f32_16x16x32_bf16 v[100:103], v[178:181], v[202:205], v[100:103]
	v_mfma_f32_16x16x32_bf16 v[92:95], v[186:189], v[202:205], v[92:95]
	v_mfma_f32_16x16x32_bf16 v[84:87], v[178:181], v[210:213], v[84:87]
	v_mfma_f32_16x16x32_bf16 v[76:79], v[186:189], v[210:213], v[76:79]
	v_mfma_f32_16x16x32_bf16 v[68:71], v[178:181], v[218:221], v[68:71]
	v_mfma_f32_16x16x32_bf16 v[64:67], v[186:189], v[218:221], v[64:67]
	v_mfma_f32_16x16x32_bf16 v[116:119], v[182:185], v[198:201], v[116:119]
	v_mfma_f32_16x16x32_bf16 v[108:111], v[190:193], v[198:201], v[108:111]
	v_mfma_f32_16x16x32_bf16 v[100:103], v[182:185], v[206:209], v[100:103]
	v_mfma_f32_16x16x32_bf16 v[92:95], v[190:193], v[206:209], v[92:95]
	v_mfma_f32_16x16x32_bf16 v[84:87], v[182:185], v[214:217], v[84:87]
	v_mfma_f32_16x16x32_bf16 v[76:79], v[190:193], v[214:217], v[76:79]
	v_mfma_f32_16x16x32_bf16 v[68:71], v[182:185], v[222:225], v[68:71]
	v_mfma_f32_16x16x32_bf16 v[64:67], v[190:193], v[222:225], v[64:67]
	s_setprio 0
	s_barrier
	s_add_i32 s8, s74, s65
	v_lshl_add_u64 v[146:147], s[54:55], 0, v[130:131]
	s_mov_b32 m0, s8
	ds_read_b128 v[194:197], v152 offset:16384
	ds_read_b128 v[198:201], v152 offset:17408
	ds_read_b128 v[202:205], v152 offset:18432
	ds_read_b128 v[206:209], v152 offset:19456
	ds_read_b128 v[210:213], v152 offset:20480
	ds_read_b128 v[214:217], v152 offset:21504
	ds_read_b128 v[218:221], v152 offset:22528
	ds_read_b128 v[222:225], v152 offset:23552
	global_load_lds_dwordx4 v[146:147], off
	s_add_i32 m0, s8, 0x2000
	s_add_u32 s8, s54, 0x40000
	v_lshl_add_u64 v[158:159], s[54:55], 0, v[134:135]
	s_addc_u32 s9, s55, 0
	s_add_i32 s60, s75, s65
	global_load_lds_dwordx4 v[158:159], off
	v_lshl_add_u64 v[174:175], s[8:9], 0, v[130:131]
	s_mov_b32 m0, s60
	v_lshl_add_u64 v[226:227], s[56:57], 0, v[132:133]
	global_load_lds_dwordx4 v[174:175], off
	v_lshl_add_u64 v[174:175], s[8:9], 0, v[134:135]
	s_add_i32 m0, s60, 0x2000
	s_nop 0
	global_load_lds_dwordx4 v[174:175], off
	v_lshl_add_u64 v[174:175], s[56:57], 0, v[128:129]
	s_mov_b32 m0, s51
	s_nop 0
	global_load_lds_dwordx4 v[174:175], off
	s_mov_b32 m0, s66
	s_nop 0
	global_load_lds_dwordx4 v[226:227], off
	s_waitcnt vmcnt(8)
	s_waitcnt lgkmcnt(0)
	s_barrier
; #define PG8_STAGE(bufoff, gbase, voff) do { _Pragma("unroll") for (int _i = 0; _i < 2; ++_i) \
;         __builtin_amdgcn_global_load_lds((const unsigned*)((const char*)(gbase) + (voff)[_i]), (PG8_LAS unsigned*)(lds + (bufoff) + ldsw + _i * 8192), 16, 0, 0); } while (0)
; #define PG8_LDA(dst, b, h) do { _Pragma("unroll") for (int m = 0; m < 4; ++m) _Pragma("unroll") for (int k = 0; k < 2; ++k) dst[m][k] = *(const PG8_LAS bf16x8*)(lds + PG8_SA(b, h) + aoff + m * 2048 + k * 1024); } while (0)
; #define PG8_LDB(dst, b, h) do { _Pragma("unroll") for (int n = 0; n < 2; ++n) _Pragma("unroll") for (int k = 0; k < 2; ++k) dst[n][k] = *(const PG8_LAS bf16x8*)(lds + PG8_SB(b, h) + boff + n * 2048 + k * 1024); } while (0)
; #define PG8_MMA(ai, bj, At, Bt) do { __builtin_amdgcn_s_setprio(1); _Pragma("unroll") for (int m = 0; m < 4; ++m) _Pragma("unroll") for (int n = 0; n < 2; ++n) _Pragma("unroll") for (int k = 0; k < 2; ++k) \
;         acc[ai][bj][m][n] = __builtin_amdgcn_mfma_f32_16x16x32_bf16(Bt[n][k], At[m][k], acc[ai][bj][m][n], 0, 0, 0); __builtin_amdgcn_s_setprio(0); } while (0)
; #define PG8_WAIT_V(n) asm volatile("s_waitcnt vmcnt(" #n ")" ::: "memory")
; #define PG8_WAIT_L(n) asm volatile("s_waitcnt lgkmcnt(" #n ")" ::: "memory")
; #define PG8_BAR __builtin_amdgcn_s_barrier()
; #define PG8_SCHED __builtin_amdgcn_sched_barrier(0)
; template <class Epi, class Sched, bool ALIGN_EPI = false, bool SP2 = false>
; __device__ __forceinline__ void gemm_phase(PG8_LAS unsigned char* lds, const Gemm g, const Sched& S, const Epi& E) {
;     ...
;             PG8_WAIT_V(8); PG8_WAIT_L(0); PG8_BAR; PG8_MMA(1, 0, At, B0); PG8_MMA(1, 1, At, B1); PG8_BAR; PG8_SCHED;
;             PG8_LDB(B0, 1, 0); PG8_LDB(B1, 1, 1); PG8_SCHED; PG8_LDA(At, 1, 0); PG8_STAGE(PG8_SA(0, 1), a2 + hstep, voffA);
;             PG8_WAIT_V(8); PG8_WAIT_L(0); PG8_BAR; PG8_MMA(0, 0, At, B0); PG8_MMA(0, 1, At, B1); PG8_BAR; PG8_SCHED;
	s_setprio 1
	s_waitcnt lgkmcnt(0)
	v_mfma_f32_16x16x32_bf16 v[60:63], v[154:157], v[194:197], v[60:63]
	v_mfma_f32_16x16x32_bf16 v[56:59], v[166:169], v[194:197], v[56:59]
	v_mfma_f32_16x16x32_bf16 v[48:51], v[154:157], v[202:205], v[48:51]
	v_mfma_f32_16x16x32_bf16 v[40:43], v[166:169], v[202:205], v[40:43]
	v_mfma_f32_16x16x32_bf16 v[32:35], v[154:157], v[210:213], v[32:35]
	v_mfma_f32_16x16x32_bf16 v[24:27], v[166:169], v[210:213], v[24:27]
	v_mfma_f32_16x16x32_bf16 v[16:19], v[154:157], v[218:221], v[16:19]
	v_mfma_f32_16x16x32_bf16 v[8:11], v[166:169], v[218:221], v[8:11]
	v_mfma_f32_16x16x32_bf16 v[60:63], v[162:165], v[198:201], v[60:63]
	v_mfma_f32_16x16x32_bf16 v[56:59], v[170:173], v[198:201], v[56:59]
	v_mfma_f32_16x16x32_bf16 v[48:51], v[162:165], v[206:209], v[48:51]
	v_mfma_f32_16x16x32_bf16 v[40:43], v[170:173], v[206:209], v[40:43]
	v_mfma_f32_16x16x32_bf16 v[32:35], v[162:165], v[214:217], v[32:35]
	v_mfma_f32_16x16x32_bf16 v[24:27], v[170:173], v[214:217], v[24:27]
	v_mfma_f32_16x16x32_bf16 v[16:19], v[162:165], v[222:225], v[16:19]
	v_mfma_f32_16x16x32_bf16 v[8:11], v[170:173], v[222:225], v[8:11]
	s_setprio 0
	s_setprio 1
	v_mfma_f32_16x16x32_bf16 v[52:55], v[178:181], v[194:197], v[52:55]
	v_mfma_f32_16x16x32_bf16 v[44:47], v[186:189], v[194:197], v[44:47]
	v_mfma_f32_16x16x32_bf16 v[36:39], v[178:181], v[202:205], v[36:39]
	v_mfma_f32_16x16x32_bf16 v[28:31], v[186:189], v[202:205], v[28:31]
	v_mfma_f32_16x16x32_bf16 v[20:23], v[178:181], v[210:213], v[20:23]
	v_mfma_f32_16x16x32_bf16 v[12:15], v[186:189], v[210:213], v[12:15]
	v_mfma_f32_16x16x32_bf16 v[4:7], v[178:181], v[218:221], v[4:7]
	v_mfma_f32_16x16x32_bf16 v[0:3], v[186:189], v[218:221], v[0:3]
	v_mfma_f32_16x16x32_bf16 v[52:55], v[182:185], v[198:201], v[52:55]
	v_mfma_f32_16x16x32_bf16 v[44:47], v[190:193], v[198:201], v[44:47]
	v_mfma_f32_16x16x32_bf16 v[36:39], v[182:185], v[206:209], v[36:39]
	v_mfma_f32_16x16x32_bf16 v[28:31], v[190:193], v[206:209], v[28:31]
	v_mfma_f32_16x16x32_bf16 v[20:23], v[182:185], v[214:217], v[20:23]
	v_mfma_f32_16x16x32_bf16 v[12:15], v[190:193], v[214:217], v[12:15]
	v_mfma_f32_16x16x32_bf16 v[4:7], v[182:185], v[222:225], v[4:7]
	v_mfma_f32_16x16x32_bf16 v[0:3], v[190:193], v[222:225], v[0:3]
	s_setprio 0
	s_barrier
	s_add_i32 s60, 0, 0x18000
	v_add_u32_e32 v144, s60, v148
	s_add_i32 s61, 0, 0x1c000
	ds_read_b128 v[154:157], v144
	ds_read_b128 v[162:165], v144 offset:1024
	ds_read_b128 v[166:169], v144 offset:2048
	ds_read_b128 v[170:173], v144 offset:3072
	v_add_u32_e32 v144, s61, v148
	ds_read_b128 v[178:181], v144
	ds_read_b128 v[182:185], v144 offset:1024
	ds_read_b128 v[186:189], v144 offset:2048
	ds_read_b128 v[190:193], v144 offset:3072
	s_add_u32 s8, s56, 0x40000
	s_addc_u32 s9, s57, 0
	s_mov_b32 m0, s67
	v_lshl_add_u64 v[228:229], s[8:9], 0, v[128:129]
	ds_read_b128 v[194:197], v152 offset:32768
	ds_read_b128 v[198:201], v152 offset:33792
	ds_read_b128 v[202:205], v152 offset:34816
	ds_read_b128 v[206:209], v152 offset:35840
	ds_read_b128 v[210:213], v152 offset:36864
	ds_read_b128 v[214:217], v152 offset:37888
	ds_read_b128 v[218:221], v152 offset:38912
	ds_read_b128 v[222:225], v152 offset:39936
	global_load_lds_dwordx4 v[228:229], off
	v_lshl_add_u64 v[228:229], s[8:9], 0, v[132:133]
	s_mov_b32 m0, s68
	s_nop 0
	global_load_lds_dwordx4 v[228:229], off
	s_waitcnt vmcnt(8)
	s_waitcnt lgkmcnt(0)
	s_barrier
	s_setprio 1
	s_waitcnt lgkmcnt(0)
	v_mfma_f32_16x16x32_bf16 v[124:127], v[154:157], v[194:197], v[124:127]
	v_mfma_f32_16x16x32_bf16 v[120:123], v[166:169], v[194:197], v[120:123]
	v_mfma_f32_16x16x32_bf16 v[112:115], v[154:157], v[202:205], v[112:115]
	v_mfma_f32_16x16x32_bf16 v[104:107], v[166:169], v[202:205], v[104:107]
	v_mfma_f32_16x16x32_bf16 v[96:99], v[154:157], v[210:213], v[96:99]
	v_mfma_f32_16x16x32_bf16 v[88:91], v[166:169], v[210:213], v[88:91]
	v_mfma_f32_16x16x32_bf16 v[80:83], v[154:157], v[218:221], v[80:83]
	v_mfma_f32_16x16x32_bf16 v[72:75], v[166:169], v[218:221], v[72:75]
	v_mfma_f32_16x16x32_bf16 v[124:127], v[162:165], v[198:201], v[124:127]
	v_mfma_f32_16x16x32_bf16 v[120:123], v[170:173], v[198:201], v[120:123]
	v_mfma_f32_16x16x32_bf16 v[112:115], v[162:165], v[206:209], v[112:115]
	v_mfma_f32_16x16x32_bf16 v[104:107], v[170:173], v[206:209], v[104:107]
	v_mfma_f32_16x16x32_bf16 v[96:99], v[162:165], v[214:217], v[96:99]
	v_mfma_f32_16x16x32_bf16 v[88:91], v[170:173], v[214:217], v[88:91]
	v_mfma_f32_16x16x32_bf16 v[80:83], v[162:165], v[222:225], v[80:83]
	v_mfma_f32_16x16x32_bf16 v[72:75], v[170:173], v[222:225], v[72:75]
	s_setprio 0
	s_setprio 1
	v_mfma_f32_16x16x32_bf16 v[116:119], v[178:181], v[194:197], v[116:119]
	v_mfma_f32_16x16x32_bf16 v[108:111], v[186:189], v[194:197], v[108:111]
	v_mfma_f32_16x16x32_bf16 v[100:103], v[178:181], v[202:205], v[100:103]
	v_mfma_f32_16x16x32_bf16 v[92:95], v[186:189], v[202:205], v[92:95]
	v_mfma_f32_16x16x32_bf16 v[84:87], v[178:181], v[210:213], v[84:87]
	v_mfma_f32_16x16x32_bf16 v[76:79], v[186:189], v[210:213], v[76:79]
	v_mfma_f32_16x16x32_bf16 v[68:71], v[178:181], v[218:221], v[68:71]
	v_mfma_f32_16x16x32_bf16 v[64:67], v[186:189], v[218:221], v[64:67]
	v_mfma_f32_16x16x32_bf16 v[116:119], v[182:185], v[198:201], v[116:119]
	v_mfma_f32_16x16x32_bf16 v[108:111], v[190:193], v[198:201], v[108:111]
	v_mfma_f32_16x16x32_bf16 v[100:103], v[182:185], v[206:209], v[100:103]
	v_mfma_f32_16x16x32_bf16 v[92:95], v[190:193], v[206:209], v[92:95]
	v_mfma_f32_16x16x32_bf16 v[84:87], v[182:185], v[214:217], v[84:87]
	v_mfma_f32_16x16x32_bf16 v[76:79], v[190:193], v[214:217], v[76:79]
	v_mfma_f32_16x16x32_bf16 v[68:71], v[182:185], v[222:225], v[68:71]
	v_mfma_f32_16x16x32_bf16 v[64:67], v[190:193], v[222:225], v[64:67]
	s_setprio 0
	s_barrier
; #define PG8_STAGE(bufoff, gbase, voff) do { _Pragma("unroll") for (int _i = 0; _i < 2; ++_i) \
;         __builtin_amdgcn_global_load_lds((const unsigned*)((const char*)(gbase) + (voff)[_i]), (PG8_LAS unsigned*)(lds + (bufoff) + ldsw + _i * 8192), 16, 0, 0); } while (0)
; #define PG8_LDA(dst, b, h) do { _Pragma("unroll") for (int m = 0; m < 4; ++m) _Pragma("unroll") for (int k = 0; k < 2; ++k) dst[m][k] = *(const PG8_LAS bf16x8*)(lds + PG8_SA(b, h) + aoff + m * 2048 + k * 1024); } while (0)
; #define PG8_MMA(ai, bj, At, Bt) do { __builtin_amdgcn_s_setprio(1); _Pragma("unroll") for (int m = 0; m < 4; ++m) _Pragma("unroll") for (int n = 0; n < 2; ++n) _Pragma("unroll") for (int k = 0; k < 2; ++k) \
;         acc[ai][bj][m][n] = __builtin_amdgcn_mfma_f32_16x16x32_bf16(Bt[n][k], At[m][k], acc[ai][bj][m][n], 0, 0, 0); __builtin_amdgcn_s_setprio(0); } while (0)
; #define PG8_WAIT_V(n) asm volatile("s_waitcnt vmcnt(" #n ")" ::: "memory")
; #define PG8_WAIT_L(n) asm volatile("s_waitcnt lgkmcnt(" #n ")" ::: "memory")
; #define PG8_BAR __builtin_amdgcn_s_barrier()
; #define PG8_SCHED __builtin_amdgcn_sched_barrier(0)
; template <class Epi, class Sched, bool ALIGN_EPI = false, bool SP2 = false>
; __device__ __forceinline__ void gemm_phase(PG8_LAS unsigned char* lds, const Gemm g, const Sched& S, const Epi& E) {
;     ...
;         for (int t = 0; t < nt; t += 2) {
;     ...
;             PG8_LDA(At, 1, 1); PG8_STAGE(PG8_SB(1, 0), b3, voffB); PG8_STAGE(PG8_SB(1, 1), b3 + hstep, voffB); PG8_STAGE(PG8_SA(1, 0), a3, voffA);
;             PG8_WAIT_V(8); PG8_WAIT_L(0); PG8_BAR; PG8_MMA(1, 0, At, B0); PG8_MMA(1, 1, At, B1); PG8_BAR; PG8_SCHED;
	s_add_i32 s8, s60, s65
	v_lshl_add_u64 v[146:147], v[146:147], 0, s[12:13]
	s_mov_b32 m0, s8
	ds_read_b128 v[194:197], v152 offset:49152
	ds_read_b128 v[198:201], v152 offset:50176
	ds_read_b128 v[202:205], v152 offset:51200
	ds_read_b128 v[206:209], v152 offset:52224
	ds_read_b128 v[210:213], v152 offset:53248
	ds_read_b128 v[214:217], v152 offset:54272
	ds_read_b128 v[218:221], v152 offset:55296
	ds_read_b128 v[222:225], v152 offset:56320
	global_load_lds_dwordx4 v[146:147], off
	s_add_i32 m0, s8, 0x2000
	s_add_u32 s8, s54, 0x40080
	v_lshl_add_u64 v[146:147], v[158:159], 0, s[12:13]
	s_addc_u32 s9, s55, 0
	s_add_i32 s54, s61, s65
	global_load_lds_dwordx4 v[146:147], off
	v_lshl_add_u64 v[146:147], s[8:9], 0, v[130:131]
	s_mov_b32 m0, s54
	s_nop 0
	global_load_lds_dwordx4 v[146:147], off
	v_lshl_add_u64 v[146:147], s[8:9], 0, v[134:135]
	s_add_i32 m0, s54, 0x2000
	s_nop 0
	global_load_lds_dwordx4 v[146:147], off
	v_lshl_add_u64 v[146:147], v[174:175], 0, s[12:13]
	s_mov_b32 m0, s70
	s_nop 0
	global_load_lds_dwordx4 v[146:147], off
	v_lshl_add_u64 v[146:147], v[226:227], 0, s[12:13]
	s_mov_b32 m0, s71
	s_nop 0
	global_load_lds_dwordx4 v[146:147], off
	s_waitcnt vmcnt(8)
	s_waitcnt lgkmcnt(0)
	s_barrier
	s_setprio 1
	s_waitcnt lgkmcnt(0)
	v_mfma_f32_16x16x32_bf16 v[60:63], v[154:157], v[194:197], v[60:63]
	v_mfma_f32_16x16x32_bf16 v[56:59], v[166:169], v[194:197], v[56:59]
	v_mfma_f32_16x16x32_bf16 v[48:51], v[154:157], v[202:205], v[48:51]
	v_mfma_f32_16x16x32_bf16 v[40:43], v[166:169], v[202:205], v[40:43]
	v_mfma_f32_16x16x32_bf16 v[32:35], v[154:157], v[210:213], v[32:35]
	v_mfma_f32_16x16x32_bf16 v[24:27], v[166:169], v[210:213], v[24:27]
	v_mfma_f32_16x16x32_bf16 v[16:19], v[154:157], v[218:221], v[16:19]
	v_mfma_f32_16x16x32_bf16 v[8:11], v[166:169], v[218:221], v[8:11]
	v_mfma_f32_16x16x32_bf16 v[60:63], v[162:165], v[198:201], v[60:63]
	v_mfma_f32_16x16x32_bf16 v[56:59], v[170:173], v[198:201], v[56:59]
	v_mfma_f32_16x16x32_bf16 v[48:51], v[162:165], v[206:209], v[48:51]
	v_mfma_f32_16x16x32_bf16 v[40:43], v[170:173], v[206:209], v[40:43]
	v_mfma_f32_16x16x32_bf16 v[32:35], v[162:165], v[214:217], v[32:35]
	v_mfma_f32_16x16x32_bf16 v[24:27], v[170:173], v[214:217], v[24:27]
	v_mfma_f32_16x16x32_bf16 v[16:19], v[162:165], v[222:225], v[16:19]
	v_mfma_f32_16x16x32_bf16 v[8:11], v[170:173], v[222:225], v[8:11]
	s_setprio 0
	s_setprio 1
	v_mfma_f32_16x16x32_bf16 v[52:55], v[178:181], v[194:197], v[52:55]
	v_mfma_f32_16x16x32_bf16 v[44:47], v[186:189], v[194:197], v[44:47]
	v_mfma_f32_16x16x32_bf16 v[36:39], v[178:181], v[202:205], v[36:39]
	v_mfma_f32_16x16x32_bf16 v[28:31], v[186:189], v[202:205], v[28:31]
	v_mfma_f32_16x16x32_bf16 v[20:23], v[178:181], v[210:213], v[20:23]
	v_mfma_f32_16x16x32_bf16 v[12:15], v[186:189], v[210:213], v[12:15]
	v_mfma_f32_16x16x32_bf16 v[4:7], v[178:181], v[218:221], v[4:7]
	v_mfma_f32_16x16x32_bf16 v[0:3], v[186:189], v[218:221], v[0:3]
	v_mfma_f32_16x16x32_bf16 v[52:55], v[182:185], v[198:201], v[52:55]
	v_mfma_f32_16x16x32_bf16 v[44:47], v[190:193], v[198:201], v[44:47]
	v_mfma_f32_16x16x32_bf16 v[36:39], v[182:185], v[206:209], v[36:39]
	v_mfma_f32_16x16x32_bf16 v[28:31], v[190:193], v[206:209], v[28:31]
	v_mfma_f32_16x16x32_bf16 v[20:23], v[182:185], v[214:217], v[20:23]
	v_mfma_f32_16x16x32_bf16 v[12:15], v[190:193], v[214:217], v[12:15]
	v_mfma_f32_16x16x32_bf16 v[4:7], v[182:185], v[222:225], v[4:7]
	v_mfma_f32_16x16x32_bf16 v[0:3], v[190:193], v[222:225], v[0:3]
	s_setprio 0
	s_add_i32 s87, s87, 2
	s_add_u32 s52, s52, 0x100
	s_addc_u32 s53, s53, 0
	s_add_u32 s83, s83, 0x100
	s_addc_u32 s86, s86, 0
	s_cmp_gt_u32 s87, 13
	s_barrier
	s_cbranch_scc0 .LBB0_1172
	s_and_b64 vcc, exec, s[14:15]
	s_cbranch_vccz .LBB0_1175
	s_barrier

; #define PG8_STAGE(bufoff, gbase, voff) do { _Pragma("unroll") for (int _i = 0; _i < 2; ++_i) \
;         __builtin_amdgcn_global_load_lds((const unsigned*)((const char*)(gbase) + (voff)[_i]), (PG8_LAS unsigned*)(lds + (bufoff) + ldsw + _i * 8192), 16, 0, 0); } while (0)
; #define PG8_LDA(dst, b, h) do { _Pragma("unroll") for (int m = 0; m < 4; ++m) _Pragma("unroll") for (int k = 0; k < 2; ++k) dst[m][k] = *(const PG8_LAS bf16x8*)(lds + PG8_SA(b, h) + aoff + m * 2048 + k * 1024); } while (0)
; #define PG8_LDB(dst, b, h) do { _Pragma("unroll") for (int n = 0; n < 2; ++n) _Pragma("unroll") for (int k = 0; k < 2; ++k) dst[n][k] = *(const PG8_LAS bf16x8*)(lds + PG8_SB(b, h) + boff + n * 2048 + k * 1024); } while (0)
; #define PG8_MMA(ai, bj, At, Bt) do { __builtin_amdgcn_s_setprio(1); _Pragma("unroll") for (int m = 0; m < 4; ++m) _Pragma("unroll") for (int n = 0; n < 2; ++n) _Pragma("unroll") for (int k = 0; k < 2; ++k) \
;         acc[ai][bj][m][n] = __builtin_amdgcn_mfma_f32_16x16x32_bf16(Bt[n][k], At[m][k], acc[ai][bj][m][n], 0, 0, 0); __builtin_amdgcn_s_setprio(0); } while (0)
; #define PG8_WAIT_V(n) asm volatile("s_waitcnt vmcnt(" #n ")" ::: "memory")
; #define PG8_WAIT_L(n) asm volatile("s_waitcnt lgkmcnt(" #n ")" ::: "memory")
; #define PG8_BAR __builtin_amdgcn_s_barrier()
; #define PG8_SCHED __builtin_amdgcn_sched_barrier(0)
; template <class Epi, class Sched, bool ALIGN_EPI = false, bool SP2 = false>
; __device__ __forceinline__ void gemm_phase(PG8_LAS unsigned char* lds, const Gemm g, const Sched& S, const Epi& E) {
;     ...
;             const char* a1 = cA + (size_t)(t + 1) * kstep;
;             const char* a2 = last ? nA : cA + (size_t)(t + 2) * kstep; const char* b2 = last ? nB : cB + (size_t)(t + 2) * kstep;
;             const char* a3 = a2 + kstep; const char* b3 = b2 + kstep;
;             if (last && has_next) S.a_ready(nxt);
;             if constexpr (SP2) {
;             PG8_LDB(B0, 0, 0); PG8_LDB(B1, 0, 1); PG8_SCHED; PG8_LDA(At, 0, 0); PG8_STAGE(PG8_SA(1, 1), a1 + hstep, voffA);
;             PG8_WAIT_V(8); PG8_WAIT_L(0); PG8_BAR; PG8_MMA(0, 0, At, B0); PG8_MMA(0, 1, At, B1); PG8_BAR; PG8_SCHED;
;             PG8_LDA(At, 0, 1); PG8_STAGE(PG8_SB(0, 0), b2, voffB); PG8_STAGE(PG8_SB(0, 1), b2 + hstep, voffB); PG8_STAGE(PG8_SA(0, 0), a2, voffA);
.LBB0_1337:
	ds_read_b128 v[152:155], v149
	ds_read_b128 v[156:159], v149 offset:1024
	ds_read_b128 v[162:165], v149 offset:2048
	ds_read_b128 v[166:169], v149 offset:3072
	ds_read_b128 v[170:173], v150
	ds_read_b128 v[178:181], v150 offset:1024
	ds_read_b128 v[182:185], v150 offset:2048
	ds_read_b128 v[186:189], v150 offset:3072
	s_add_u32 s8, s38, 0xfffc0080
	s_addc_u32 s9, s39, -1
	s_cmp_eq_u32 s71, 12
	s_cselect_b32 s45, s19, s9
	s_cselect_b32 s44, s67, s8
	s_cselect_b32 s43, s15, s70
	s_cselect_b32 s42, s68, s69
	v_lshl_add_u64 v[144:145], s[38:39], 0, v[136:137]
	s_add_i32 m0, s25, 0xc000
	ds_read_b128 v[190:193], v151
	ds_read_b128 v[194:197], v151 offset:1024
	ds_read_b128 v[198:201], v151 offset:2048
	ds_read_b128 v[202:205], v151 offset:3072
	ds_read_b128 v[206:209], v151 offset:4096
	ds_read_b128 v[210:213], v151 offset:5120
	ds_read_b128 v[214:217], v151 offset:6144
	ds_read_b128 v[218:221], v151 offset:7168
	global_load_lds_dwordx4 v[144:145], off
	v_lshl_add_u64 v[144:145], s[38:39], 0, v[138:139]
	s_add_i32 m0, s25, 0xe000
	s_nop 0
	global_load_lds_dwordx4 v[144:145], off
	s_waitcnt vmcnt(8)
	s_waitcnt lgkmcnt(0)
	s_barrier
	s_setprio 1
	s_waitcnt lgkmcnt(0)
	v_mfma_f32_16x16x32_bf16 v[124:127], v[152:155], v[190:193], v[124:127]
	v_mfma_f32_16x16x32_bf16 v[120:123], v[162:165], v[190:193], v[120:123]
	v_mfma_f32_16x16x32_bf16 v[108:111], v[152:155], v[198:201], v[108:111]
	v_mfma_f32_16x16x32_bf16 v[104:107], v[162:165], v[198:201], v[104:107]
	v_mfma_f32_16x16x32_bf16 v[92:95], v[152:155], v[206:209], v[92:95]
	v_mfma_f32_16x16x32_bf16 v[88:91], v[162:165], v[206:209], v[88:91]
	v_mfma_f32_16x16x32_bf16 v[76:79], v[152:155], v[214:217], v[76:79]
	v_mfma_f32_16x16x32_bf16 v[72:75], v[162:165], v[214:217], v[72:75]
	v_mfma_f32_16x16x32_bf16 v[124:127], v[156:159], v[194:197], v[124:127]
	v_mfma_f32_16x16x32_bf16 v[120:123], v[166:169], v[194:197], v[120:123]
	v_mfma_f32_16x16x32_bf16 v[108:111], v[156:159], v[202:205], v[108:111]
	v_mfma_f32_16x16x32_bf16 v[104:107], v[166:169], v[202:205], v[104:107]
	v_mfma_f32_16x16x32_bf16 v[92:95], v[156:159], v[210:213], v[92:95]
	v_mfma_f32_16x16x32_bf16 v[88:91], v[166:169], v[210:213], v[88:91]
	v_mfma_f32_16x16x32_bf16 v[76:79], v[156:159], v[218:221], v[76:79]
	v_mfma_f32_16x16x32_bf16 v[72:75], v[166:169], v[218:221], v[72:75]
	s_setprio 0
	s_setprio 1
	v_mfma_f32_16x16x32_bf16 v[116:119], v[170:173], v[190:193], v[116:119]
	v_mfma_f32_16x16x32_bf16 v[112:115], v[182:185], v[190:193], v[112:115]
	v_mfma_f32_16x16x32_bf16 v[100:103], v[170:173], v[198:201], v[100:103]
	v_mfma_f32_16x16x32_bf16 v[96:99], v[182:185], v[198:201], v[96:99]
	v_mfma_f32_16x16x32_bf16 v[84:87], v[170:173], v[206:209], v[84:87]
	v_mfma_f32_16x16x32_bf16 v[80:83], v[182:185], v[206:209], v[80:83]
	v_mfma_f32_16x16x32_bf16 v[68:71], v[170:173], v[214:217], v[68:71]
	v_mfma_f32_16x16x32_bf16 v[64:67], v[182:185], v[214:217], v[64:67]
	v_mfma_f32_16x16x32_bf16 v[116:119], v[178:181], v[194:197], v[116:119]
	v_mfma_f32_16x16x32_bf16 v[112:115], v[186:189], v[194:197], v[112:115]
	v_mfma_f32_16x16x32_bf16 v[100:103], v[178:181], v[202:205], v[100:103]
	v_mfma_f32_16x16x32_bf16 v[96:99], v[186:189], v[202:205], v[96:99]
	v_mfma_f32_16x16x32_bf16 v[84:87], v[178:181], v[210:213], v[84:87]
	v_mfma_f32_16x16x32_bf16 v[80:83], v[186:189], v[210:213], v[80:83]
	v_mfma_f32_16x16x32_bf16 v[68:71], v[178:181], v[218:221], v[68:71]
	v_mfma_f32_16x16x32_bf16 v[64:67], v[186:189], v[218:221], v[64:67]
	s_setprio 0
	s_barrier
	s_add_i32 s8, s63, s47
	v_lshl_add_u64 v[144:145], s[42:43], 0, v[132:133]
	s_mov_b32 m0, s8
	ds_read_b128 v[190:193], v151 offset:16384
	ds_read_b128 v[194:197], v151 offset:17408
	ds_read_b128 v[198:201], v151 offset:18432
	ds_read_b128 v[202:205], v151 offset:19456
	ds_read_b128 v[206:209], v151 offset:20480
	ds_read_b128 v[210:213], v151 offset:21504
	ds_read_b128 v[214:217], v151 offset:22528
	ds_read_b128 v[218:221], v151 offset:23552
	global_load_lds_dwordx4 v[144:145], off
	s_add_i32 m0, s8, 0x2000
	s_add_u32 s8, s42, 0x40000
	v_lshl_add_u64 v[174:175], s[42:43], 0, v[128:129]
	s_addc_u32 s9, s43, 0
	s_add_i32 s60, s64, s47
	global_load_lds_dwordx4 v[174:175], off
	v_lshl_add_u64 v[222:223], s[8:9], 0, v[132:133]
	s_mov_b32 m0, s60
	v_lshl_add_u64 v[224:225], s[44:45], 0, v[130:131]
	global_load_lds_dwordx4 v[222:223], off
	v_lshl_add_u64 v[222:223], s[8:9], 0, v[128:129]
	s_add_i32 m0, s60, 0x2000
	s_nop 0
	global_load_lds_dwordx4 v[222:223], off
	v_lshl_add_u64 v[222:223], s[44:45], 0, v[134:135]
	s_mov_b32 m0, s25
	s_nop 0
	global_load_lds_dwordx4 v[222:223], off
	s_mov_b32 m0, s50
	s_nop 0
	global_load_lds_dwordx4 v[224:225], off
	s_waitcnt vmcnt(8)
	s_waitcnt lgkmcnt(0)
	s_barrier
; #define PG8_STAGE(bufoff, gbase, voff) do { _Pragma("unroll") for (int _i = 0; _i < 2; ++_i) \
;         __builtin_amdgcn_global_load_lds((const unsigned*)((const char*)(gbase) + (voff)[_i]), (PG8_LAS unsigned*)(lds + (bufoff) + ldsw + _i * 8192), 16, 0, 0); } while (0)
; #define PG8_LDA(dst, b, h) do { _Pragma("unroll") for (int m = 0; m < 4; ++m) _Pragma("unroll") for (int k = 0; k < 2; ++k) dst[m][k] = *(const PG8_LAS bf16x8*)(lds + PG8_SA(b, h) + aoff + m * 2048 + k * 1024); } while (0)
; #define PG8_LDB(dst, b, h) do { _Pragma("unroll") for (int n = 0; n < 2; ++n) _Pragma("unroll") for (int k = 0; k < 2; ++k) dst[n][k] = *(const PG8_LAS bf16x8*)(lds + PG8_SB(b, h) + boff + n * 2048 + k * 1024); } while (0)
; #define PG8_MMA(ai, bj, At, Bt) do { __builtin_amdgcn_s_setprio(1); _Pragma("unroll") for (int m = 0; m < 4; ++m) _Pragma("unroll") for (int n = 0; n < 2; ++n) _Pragma("unroll") for (int k = 0; k < 2; ++k) \
;         acc[ai][bj][m][n] = __builtin_amdgcn_mfma_f32_16x16x32_bf16(Bt[n][k], At[m][k], acc[ai][bj][m][n], 0, 0, 0); __builtin_amdgcn_s_setprio(0); } while (0)
; #define PG8_WAIT_V(n) asm volatile("s_waitcnt vmcnt(" #n ")" ::: "memory")
; #define PG8_WAIT_L(n) asm volatile("s_waitcnt lgkmcnt(" #n ")" ::: "memory")
; #define PG8_BAR __builtin_amdgcn_s_barrier()
; #define PG8_SCHED __builtin_amdgcn_sched_barrier(0)
; template <class Epi, class Sched, bool ALIGN_EPI = false, bool SP2 = false>
; __device__ __forceinline__ void gemm_phase(PG8_LAS unsigned char* lds, const Gemm g, const Sched& S, const Epi& E) {
;     ...
;             PG8_WAIT_V(8); PG8_WAIT_L(0); PG8_BAR; PG8_MMA(1, 0, At, B0); PG8_MMA(1, 1, At, B1); PG8_BAR; PG8_SCHED;
;             PG8_LDB(B0, 1, 0); PG8_LDB(B1, 1, 1); PG8_SCHED; PG8_LDA(At, 1, 0); PG8_STAGE(PG8_SA(0, 1), a2 + hstep, voffA);
;             PG8_WAIT_V(8); PG8_WAIT_L(0); PG8_BAR; PG8_MMA(0, 0, At, B0); PG8_MMA(0, 1, At, B1); PG8_BAR; PG8_SCHED;
	s_setprio 1
	s_waitcnt lgkmcnt(0)
	v_mfma_f32_16x16x32_bf16 v[60:63], v[152:155], v[190:193], v[60:63]
	v_mfma_f32_16x16x32_bf16 v[56:59], v[162:165], v[190:193], v[56:59]
	v_mfma_f32_16x16x32_bf16 v[44:47], v[152:155], v[198:201], v[44:47]
	v_mfma_f32_16x16x32_bf16 v[40:43], v[162:165], v[198:201], v[40:43]
	v_mfma_f32_16x16x32_bf16 v[28:31], v[152:155], v[206:209], v[28:31]
	v_mfma_f32_16x16x32_bf16 v[24:27], v[162:165], v[206:209], v[24:27]
	v_mfma_f32_16x16x32_bf16 v[12:15], v[152:155], v[214:217], v[12:15]
	v_mfma_f32_16x16x32_bf16 v[8:11], v[162:165], v[214:217], v[8:11]
	v_mfma_f32_16x16x32_bf16 v[60:63], v[156:159], v[194:197], v[60:63]
	v_mfma_f32_16x16x32_bf16 v[56:59], v[166:169], v[194:197], v[56:59]
	v_mfma_f32_16x16x32_bf16 v[44:47], v[156:159], v[202:205], v[44:47]
	v_mfma_f32_16x16x32_bf16 v[40:43], v[166:169], v[202:205], v[40:43]
	v_mfma_f32_16x16x32_bf16 v[28:31], v[156:159], v[210:213], v[28:31]
	v_mfma_f32_16x16x32_bf16 v[24:27], v[166:169], v[210:213], v[24:27]
	v_mfma_f32_16x16x32_bf16 v[12:15], v[156:159], v[218:221], v[12:15]
	v_mfma_f32_16x16x32_bf16 v[8:11], v[166:169], v[218:221], v[8:11]
	s_setprio 0
	s_setprio 1
	v_mfma_f32_16x16x32_bf16 v[52:55], v[170:173], v[190:193], v[52:55]
	v_mfma_f32_16x16x32_bf16 v[48:51], v[182:185], v[190:193], v[48:51]
	v_mfma_f32_16x16x32_bf16 v[36:39], v[170:173], v[198:201], v[36:39]
	v_mfma_f32_16x16x32_bf16 v[32:35], v[182:185], v[198:201], v[32:35]
	v_mfma_f32_16x16x32_bf16 v[20:23], v[170:173], v[206:209], v[20:23]
	v_mfma_f32_16x16x32_bf16 v[16:19], v[182:185], v[206:209], v[16:19]
	v_mfma_f32_16x16x32_bf16 v[4:7], v[170:173], v[214:217], v[4:7]
	v_mfma_f32_16x16x32_bf16 v[0:3], v[182:185], v[214:217], v[0:3]
	v_mfma_f32_16x16x32_bf16 v[52:55], v[178:181], v[194:197], v[52:55]
	v_mfma_f32_16x16x32_bf16 v[48:51], v[186:189], v[194:197], v[48:51]
	v_mfma_f32_16x16x32_bf16 v[36:39], v[178:181], v[202:205], v[36:39]
	v_mfma_f32_16x16x32_bf16 v[32:35], v[186:189], v[202:205], v[32:35]
	v_mfma_f32_16x16x32_bf16 v[20:23], v[178:181], v[210:213], v[20:23]
	v_mfma_f32_16x16x32_bf16 v[16:19], v[186:189], v[210:213], v[16:19]
	v_mfma_f32_16x16x32_bf16 v[4:7], v[178:181], v[218:221], v[4:7]
	v_mfma_f32_16x16x32_bf16 v[0:3], v[186:189], v[218:221], v[0:3]
	s_setprio 0
	s_barrier
	s_add_i32 s60, 0, 0x18000
	v_add_u32_e32 v161, s60, v147
	s_add_i32 s61, 0, 0x1c000
	ds_read_b128 v[152:155], v161
	ds_read_b128 v[156:159], v161 offset:1024
	ds_read_b128 v[162:165], v161 offset:2048
	ds_read_b128 v[166:169], v161 offset:3072
	v_add_u32_e32 v161, s61, v147
	ds_read_b128 v[170:173], v161
	ds_read_b128 v[178:181], v161 offset:1024
	ds_read_b128 v[182:185], v161 offset:2048
	ds_read_b128 v[186:189], v161 offset:3072
	s_add_u32 s8, s44, 0x40000
	s_addc_u32 s9, s45, 0
	s_mov_b32 m0, s51
	v_lshl_add_u64 v[226:227], s[8:9], 0, v[134:135]
	ds_read_b128 v[190:193], v151 offset:32768
	ds_read_b128 v[194:197], v151 offset:33792
	ds_read_b128 v[198:201], v151 offset:34816
	ds_read_b128 v[202:205], v151 offset:35840
	ds_read_b128 v[206:209], v151 offset:36864
	ds_read_b128 v[210:213], v151 offset:37888
	ds_read_b128 v[214:217], v151 offset:38912
	ds_read_b128 v[218:221], v151 offset:39936
	global_load_lds_dwordx4 v[226:227], off
	v_lshl_add_u64 v[226:227], s[8:9], 0, v[130:131]
	s_mov_b32 m0, s52
	s_nop 0
	global_load_lds_dwordx4 v[226:227], off
	s_waitcnt vmcnt(8)
	s_waitcnt lgkmcnt(0)
	s_barrier
	s_setprio 1
	s_waitcnt lgkmcnt(0)
	v_mfma_f32_16x16x32_bf16 v[124:127], v[152:155], v[190:193], v[124:127]
	v_mfma_f32_16x16x32_bf16 v[120:123], v[162:165], v[190:193], v[120:123]
	v_mfma_f32_16x16x32_bf16 v[108:111], v[152:155], v[198:201], v[108:111]
	v_mfma_f32_16x16x32_bf16 v[104:107], v[162:165], v[198:201], v[104:107]
	v_mfma_f32_16x16x32_bf16 v[92:95], v[152:155], v[206:209], v[92:95]
	v_mfma_f32_16x16x32_bf16 v[88:91], v[162:165], v[206:209], v[88:91]
	v_mfma_f32_16x16x32_bf16 v[76:79], v[152:155], v[214:217], v[76:79]
	v_mfma_f32_16x16x32_bf16 v[72:75], v[162:165], v[214:217], v[72:75]
	v_mfma_f32_16x16x32_bf16 v[124:127], v[156:159], v[194:197], v[124:127]
	v_mfma_f32_16x16x32_bf16 v[120:123], v[166:169], v[194:197], v[120:123]
	v_mfma_f32_16x16x32_bf16 v[108:111], v[156:159], v[202:205], v[108:111]
	v_mfma_f32_16x16x32_bf16 v[104:107], v[166:169], v[202:205], v[104:107]
	v_mfma_f32_16x16x32_bf16 v[92:95], v[156:159], v[210:213], v[92:95]
	v_mfma_f32_16x16x32_bf16 v[88:91], v[166:169], v[210:213], v[88:91]
	v_mfma_f32_16x16x32_bf16 v[76:79], v[156:159], v[218:221], v[76:79]
	v_mfma_f32_16x16x32_bf16 v[72:75], v[166:169], v[218:221], v[72:75]
	s_setprio 0
	s_setprio 1
	v_mfma_f32_16x16x32_bf16 v[116:119], v[170:173], v[190:193], v[116:119]
	v_mfma_f32_16x16x32_bf16 v[112:115], v[182:185], v[190:193], v[112:115]
	v_mfma_f32_16x16x32_bf16 v[100:103], v[170:173], v[198:201], v[100:103]
	v_mfma_f32_16x16x32_bf16 v[96:99], v[182:185], v[198:201], v[96:99]
	v_mfma_f32_16x16x32_bf16 v[84:87], v[170:173], v[206:209], v[84:87]
	v_mfma_f32_16x16x32_bf16 v[80:83], v[182:185], v[206:209], v[80:83]
	v_mfma_f32_16x16x32_bf16 v[68:71], v[170:173], v[214:217], v[68:71]
	v_mfma_f32_16x16x32_bf16 v[64:67], v[182:185], v[214:217], v[64:67]
	v_mfma_f32_16x16x32_bf16 v[116:119], v[178:181], v[194:197], v[116:119]
	v_mfma_f32_16x16x32_bf16 v[112:115], v[186:189], v[194:197], v[112:115]
	v_mfma_f32_16x16x32_bf16 v[100:103], v[178:181], v[202:205], v[100:103]
	v_mfma_f32_16x16x32_bf16 v[96:99], v[186:189], v[202:205], v[96:99]
	v_mfma_f32_16x16x32_bf16 v[84:87], v[178:181], v[210:213], v[84:87]
	v_mfma_f32_16x16x32_bf16 v[80:83], v[186:189], v[210:213], v[80:83]
	v_mfma_f32_16x16x32_bf16 v[68:71], v[178:181], v[218:221], v[68:71]
	v_mfma_f32_16x16x32_bf16 v[64:67], v[186:189], v[218:221], v[64:67]
	s_setprio 0
	s_barrier
; #define PG8_STAGE(bufoff, gbase, voff) do { _Pragma("unroll") for (int _i = 0; _i < 2; ++_i) \
;         __builtin_amdgcn_global_load_lds((const unsigned*)((const char*)(gbase) + (voff)[_i]), (PG8_LAS unsigned*)(lds + (bufoff) + ldsw + _i * 8192), 16, 0, 0); } while (0)
; #define PG8_LDA(dst, b, h) do { _Pragma("unroll") for (int m = 0; m < 4; ++m) _Pragma("unroll") for (int k = 0; k < 2; ++k) dst[m][k] = *(const PG8_LAS bf16x8*)(lds + PG8_SA(b, h) + aoff + m * 2048 + k * 1024); } while (0)
; #define PG8_MMA(ai, bj, At, Bt) do { __builtin_amdgcn_s_setprio(1); _Pragma("unroll") for (int m = 0; m < 4; ++m) _Pragma("unroll") for (int n = 0; n < 2; ++n) _Pragma("unroll") for (int k = 0; k < 2; ++k) \
;         acc[ai][bj][m][n] = __builtin_amdgcn_mfma_f32_16x16x32_bf16(Bt[n][k], At[m][k], acc[ai][bj][m][n], 0, 0, 0); __builtin_amdgcn_s_setprio(0); } while (0)
; #define PG8_WAIT_V(n) asm volatile("s_waitcnt vmcnt(" #n ")" ::: "memory")
; #define PG8_WAIT_L(n) asm volatile("s_waitcnt lgkmcnt(" #n ")" ::: "memory")
; #define PG8_BAR __builtin_amdgcn_s_barrier()
; #define PG8_SCHED __builtin_amdgcn_sched_barrier(0)
; template <class Epi, class Sched, bool ALIGN_EPI = false, bool SP2 = false>
; __device__ __forceinline__ void gemm_phase(PG8_LAS unsigned char* lds, const Gemm g, const Sched& S, const Epi& E) {
;     ...
;         for (int t = 0; t < nt; t += 2) {
;     ...
;             PG8_LDA(At, 1, 1); PG8_STAGE(PG8_SB(1, 0), b3, voffB); PG8_STAGE(PG8_SB(1, 1), b3 + hstep, voffB); PG8_STAGE(PG8_SA(1, 0), a3, voffA);
;             PG8_WAIT_V(8); PG8_WAIT_L(0); PG8_BAR; PG8_MMA(1, 0, At, B0); PG8_MMA(1, 1, At, B1); PG8_BAR; PG8_SCHED;
	s_add_i32 s8, s60, s47
	v_lshl_add_u64 v[144:145], v[144:145], 0, s[6:7]
	s_mov_b32 m0, s8
	ds_read_b128 v[190:193], v151 offset:49152
	ds_read_b128 v[194:197], v151 offset:50176
	ds_read_b128 v[198:201], v151 offset:51200
	ds_read_b128 v[202:205], v151 offset:52224
	ds_read_b128 v[206:209], v151 offset:53248
	ds_read_b128 v[210:213], v151 offset:54272
	ds_read_b128 v[214:217], v151 offset:55296
	ds_read_b128 v[218:221], v151 offset:56320
	global_load_lds_dwordx4 v[144:145], off
	s_add_i32 m0, s8, 0x2000
	s_add_u32 s8, s42, 0x40080
	v_lshl_add_u64 v[144:145], v[174:175], 0, s[6:7]
	s_addc_u32 s9, s43, 0
	s_add_i32 s42, s61, s47
	global_load_lds_dwordx4 v[144:145], off
	v_lshl_add_u64 v[144:145], s[8:9], 0, v[132:133]
	s_mov_b32 m0, s42
	s_nop 0
	global_load_lds_dwordx4 v[144:145], off
	v_lshl_add_u64 v[144:145], s[8:9], 0, v[128:129]
	s_add_i32 m0, s42, 0x2000
	s_nop 0
	global_load_lds_dwordx4 v[144:145], off
	v_lshl_add_u64 v[144:145], v[222:223], 0, s[6:7]
	s_mov_b32 m0, s54
	s_nop 0
	global_load_lds_dwordx4 v[144:145], off
	v_lshl_add_u64 v[144:145], v[224:225], 0, s[6:7]
	s_mov_b32 m0, s55
	s_nop 0
	global_load_lds_dwordx4 v[144:145], off
	s_waitcnt vmcnt(8)
	s_waitcnt lgkmcnt(0)
	s_barrier
	s_setprio 1
	s_waitcnt lgkmcnt(0)
	v_mfma_f32_16x16x32_bf16 v[60:63], v[152:155], v[190:193], v[60:63]
	v_mfma_f32_16x16x32_bf16 v[56:59], v[162:165], v[190:193], v[56:59]
	v_mfma_f32_16x16x32_bf16 v[44:47], v[152:155], v[198:201], v[44:47]
	v_mfma_f32_16x16x32_bf16 v[40:43], v[162:165], v[198:201], v[40:43]
	v_mfma_f32_16x16x32_bf16 v[28:31], v[152:155], v[206:209], v[28:31]
	v_mfma_f32_16x16x32_bf16 v[24:27], v[162:165], v[206:209], v[24:27]
	v_mfma_f32_16x16x32_bf16 v[12:15], v[152:155], v[214:217], v[12:15]
	v_mfma_f32_16x16x32_bf16 v[8:11], v[162:165], v[214:217], v[8:11]
	v_mfma_f32_16x16x32_bf16 v[60:63], v[156:159], v[194:197], v[60:63]
	v_mfma_f32_16x16x32_bf16 v[56:59], v[166:169], v[194:197], v[56:59]
	v_mfma_f32_16x16x32_bf16 v[44:47], v[156:159], v[202:205], v[44:47]
	v_mfma_f32_16x16x32_bf16 v[40:43], v[166:169], v[202:205], v[40:43]
	v_mfma_f32_16x16x32_bf16 v[28:31], v[156:159], v[210:213], v[28:31]
	v_mfma_f32_16x16x32_bf16 v[24:27], v[166:169], v[210:213], v[24:27]
	v_mfma_f32_16x16x32_bf16 v[12:15], v[156:159], v[218:221], v[12:15]
	v_mfma_f32_16x16x32_bf16 v[8:11], v[166:169], v[218:221], v[8:11]
	s_setprio 0
	s_setprio 1
	v_mfma_f32_16x16x32_bf16 v[52:55], v[170:173], v[190:193], v[52:55]
	v_mfma_f32_16x16x32_bf16 v[48:51], v[182:185], v[190:193], v[48:51]
	v_mfma_f32_16x16x32_bf16 v[36:39], v[170:173], v[198:201], v[36:39]
	v_mfma_f32_16x16x32_bf16 v[32:35], v[182:185], v[198:201], v[32:35]
	v_mfma_f32_16x16x32_bf16 v[20:23], v[170:173], v[206:209], v[20:23]
	v_mfma_f32_16x16x32_bf16 v[16:19], v[182:185], v[206:209], v[16:19]
	v_mfma_f32_16x16x32_bf16 v[4:7], v[170:173], v[214:217], v[4:7]
	v_mfma_f32_16x16x32_bf16 v[0:3], v[182:185], v[214:217], v[0:3]
	v_mfma_f32_16x16x32_bf16 v[52:55], v[178:181], v[194:197], v[52:55]
	v_mfma_f32_16x16x32_bf16 v[48:51], v[186:189], v[194:197], v[48:51]
	v_mfma_f32_16x16x32_bf16 v[36:39], v[178:181], v[202:205], v[36:39]
	v_mfma_f32_16x16x32_bf16 v[32:35], v[186:189], v[202:205], v[32:35]
	v_mfma_f32_16x16x32_bf16 v[20:23], v[178:181], v[210:213], v[20:23]
	v_mfma_f32_16x16x32_bf16 v[16:19], v[186:189], v[210:213], v[16:19]
	v_mfma_f32_16x16x32_bf16 v[4:7], v[178:181], v[218:221], v[4:7]
	v_mfma_f32_16x16x32_bf16 v[0:3], v[186:189], v[218:221], v[0:3]
	s_setprio 0
	s_add_i32 s71, s71, 2
	s_add_u32 s38, s38, 0x100
	s_addc_u32 s39, s39, 0
	s_add_u32 s69, s69, 0x100
	s_addc_u32 s70, s70, 0
	s_cmp_gt_u32 s71, 13
	s_barrier
	s_cbranch_scc0 .LBB0_1337
	s_and_b64 vcc, exec, s[12:13]
	s_cbranch_vccz .LBB0_1340
	s_barrier

; #define PG8_STAGE(bufoff, gbase, voff) do { _Pragma("unroll") for (int _i = 0; _i < 2; ++_i) \
;         __builtin_amdgcn_global_load_lds((const unsigned*)((const char*)(gbase) + (voff)[_i]), (PG8_LAS unsigned*)(lds + (bufoff) + ldsw + _i * 8192), 16, 0, 0); } while (0)
; #define PG8_LDA(dst, b, h) do { _Pragma("unroll") for (int m = 0; m < 4; ++m) _Pragma("unroll") for (int k = 0; k < 2; ++k) dst[m][k] = *(const PG8_LAS bf16x8*)(lds + PG8_SA(b, h) + aoff + m * 2048 + k * 1024); } while (0)
; #define PG8_LDB(dst, b, h) do { _Pragma("unroll") for (int n = 0; n < 2; ++n) _Pragma("unroll") for (int k = 0; k < 2; ++k) dst[n][k] = *(const PG8_LAS bf16x8*)(lds + PG8_SB(b, h) + boff + n * 2048 + k * 1024); } while (0)
; #define PG8_MMA(ai, bj, At, Bt) do { __builtin_amdgcn_s_setprio(1); _Pragma("unroll") for (int m = 0; m < 4; ++m) _Pragma("unroll") for (int n = 0; n < 2; ++n) _Pragma("unroll") for (int k = 0; k < 2; ++k) \
;         acc[ai][bj][m][n] = __builtin_amdgcn_mfma_f32_16x16x32_bf16(Bt[n][k], At[m][k], acc[ai][bj][m][n], 0, 0, 0); __builtin_amdgcn_s_setprio(0); } while (0)
; #define PG8_WAIT_V(n) asm volatile("s_waitcnt vmcnt(" #n ")" ::: "memory")
; #define PG8_WAIT_L(n) asm volatile("s_waitcnt lgkmcnt(" #n ")" ::: "memory")
; #define PG8_BAR __builtin_amdgcn_s_barrier()
; #define PG8_SCHED __builtin_amdgcn_sched_barrier(0)
; template <class Epi, class Sched, bool ALIGN_EPI = false, bool SP2 = false>
; __device__ __forceinline__ void gemm_phase(PG8_LAS unsigned char* lds, const Gemm g, const Sched& S, const Epi& E) {
;     ...
;             const char* a1 = cA + (size_t)(t + 1) * kstep;
;             const char* a2 = last ? nA : cA + (size_t)(t + 2) * kstep; const char* b2 = last ? nB : cB + (size_t)(t + 2) * kstep;
;             const char* a3 = a2 + kstep; const char* b3 = b2 + kstep;
;             if (last && has_next) S.a_ready(nxt);
;             if constexpr (SP2) {
;             PG8_LDB(B0, 0, 0); PG8_LDB(B1, 0, 1); PG8_SCHED; PG8_LDA(At, 0, 0); PG8_STAGE(PG8_SA(1, 1), a1 + hstep, voffA);
;             PG8_WAIT_V(8); PG8_WAIT_L(0); PG8_BAR; PG8_MMA(0, 0, At, B0); PG8_MMA(0, 1, At, B1); PG8_BAR; PG8_SCHED;
;             PG8_LDA(At, 0, 1); PG8_STAGE(PG8_SB(0, 0), b2, voffB); PG8_STAGE(PG8_SB(0, 1), b2 + hstep, voffB); PG8_STAGE(PG8_SA(0, 0), a2, voffA);
.LBB0_1420:
	ds_read_b128 v[164:167], v159
	ds_read_b128 v[168:171], v159 offset:1024
	ds_read_b128 v[172:175], v159 offset:2048
	ds_read_b128 v[178:181], v159 offset:3072
	ds_read_b128 v[182:185], v161
	ds_read_b128 v[186:189], v161 offset:1024
	ds_read_b128 v[190:193], v161 offset:2048
	ds_read_b128 v[194:197], v161 offset:3072
	s_add_u32 s8, s44, 0xfff50080
	s_addc_u32 s9, s45, -1
	s_cmp_eq_u32 s79, 40
	s_cselect_b32 s49, s1, s9
	s_cselect_b32 s48, s0, s8
	s_cselect_b32 s47, s43, s78
	s_cselect_b32 s46, s42, s77
	v_lshl_add_u64 v[146:147], s[44:45], 0, v[136:137]
	s_add_i32 m0, s53, 0xc000
	ds_read_b128 v[198:201], v162
	ds_read_b128 v[202:205], v162 offset:1024
	ds_read_b128 v[206:209], v162 offset:2048
	ds_read_b128 v[210:213], v162 offset:3072
	ds_read_b128 v[214:217], v162 offset:4096
	ds_read_b128 v[218:221], v162 offset:5120
	ds_read_b128 v[222:225], v162 offset:6144
	ds_read_b128 v[226:229], v162 offset:7168
	global_load_lds_dwordx4 v[146:147], off
	v_lshl_add_u64 v[146:147], s[44:45], 0, v[138:139]
	s_add_i32 m0, s53, 0xe000
	s_nop 0
	global_load_lds_dwordx4 v[146:147], off
	s_waitcnt vmcnt(8)
	s_waitcnt lgkmcnt(0)
	s_barrier
	s_setprio 1
	s_waitcnt lgkmcnt(0)
	v_mfma_f32_16x16x32_bf16 v[124:127], v[164:167], v[198:201], v[124:127]
	v_mfma_f32_16x16x32_bf16 v[120:123], v[172:175], v[198:201], v[120:123]
	v_mfma_f32_16x16x32_bf16 v[112:115], v[164:167], v[206:209], v[112:115]
	v_mfma_f32_16x16x32_bf16 v[104:107], v[172:175], v[206:209], v[104:107]
	v_mfma_f32_16x16x32_bf16 v[96:99], v[164:167], v[214:217], v[96:99]
	v_mfma_f32_16x16x32_bf16 v[88:91], v[172:175], v[214:217], v[88:91]
	v_mfma_f32_16x16x32_bf16 v[80:83], v[164:167], v[222:225], v[80:83]
	v_mfma_f32_16x16x32_bf16 v[72:75], v[172:175], v[222:225], v[72:75]
	v_mfma_f32_16x16x32_bf16 v[124:127], v[168:171], v[202:205], v[124:127]
	v_mfma_f32_16x16x32_bf16 v[120:123], v[178:181], v[202:205], v[120:123]
	v_mfma_f32_16x16x32_bf16 v[112:115], v[168:171], v[210:213], v[112:115]
	v_mfma_f32_16x16x32_bf16 v[104:107], v[178:181], v[210:213], v[104:107]
	v_mfma_f32_16x16x32_bf16 v[96:99], v[168:171], v[218:221], v[96:99]
	v_mfma_f32_16x16x32_bf16 v[88:91], v[178:181], v[218:221], v[88:91]
	v_mfma_f32_16x16x32_bf16 v[80:83], v[168:171], v[226:229], v[80:83]
	v_mfma_f32_16x16x32_bf16 v[72:75], v[178:181], v[226:229], v[72:75]
	s_setprio 0
	s_setprio 1
	v_mfma_f32_16x16x32_bf16 v[116:119], v[182:185], v[198:201], v[116:119]
	v_mfma_f32_16x16x32_bf16 v[108:111], v[190:193], v[198:201], v[108:111]
	v_mfma_f32_16x16x32_bf16 v[100:103], v[182:185], v[206:209], v[100:103]
	v_mfma_f32_16x16x32_bf16 v[92:95], v[190:193], v[206:209], v[92:95]
	v_mfma_f32_16x16x32_bf16 v[84:87], v[182:185], v[214:217], v[84:87]
	v_mfma_f32_16x16x32_bf16 v[76:79], v[190:193], v[214:217], v[76:79]
	v_mfma_f32_16x16x32_bf16 v[68:71], v[182:185], v[222:225], v[68:71]
	v_mfma_f32_16x16x32_bf16 v[64:67], v[190:193], v[222:225], v[64:67]
	v_mfma_f32_16x16x32_bf16 v[116:119], v[186:189], v[202:205], v[116:119]
	v_mfma_f32_16x16x32_bf16 v[108:111], v[194:197], v[202:205], v[108:111]
	v_mfma_f32_16x16x32_bf16 v[100:103], v[186:189], v[210:213], v[100:103]
	v_mfma_f32_16x16x32_bf16 v[92:95], v[194:197], v[210:213], v[92:95]
	v_mfma_f32_16x16x32_bf16 v[84:87], v[186:189], v[218:221], v[84:87]
	v_mfma_f32_16x16x32_bf16 v[76:79], v[194:197], v[218:221], v[76:79]
	v_mfma_f32_16x16x32_bf16 v[68:71], v[186:189], v[226:229], v[68:71]
	v_mfma_f32_16x16x32_bf16 v[64:67], v[194:197], v[226:229], v[64:67]
	s_setprio 0
	s_barrier
	s_add_i32 s8, s67, s52
	v_lshl_add_u64 v[146:147], s[46:47], 0, v[130:131]
	s_mov_b32 m0, s8
	ds_read_b128 v[198:201], v162 offset:16384
	ds_read_b128 v[202:205], v162 offset:17408
	ds_read_b128 v[206:209], v162 offset:18432
	ds_read_b128 v[210:213], v162 offset:19456
	ds_read_b128 v[214:217], v162 offset:20480
	ds_read_b128 v[218:221], v162 offset:21504
	ds_read_b128 v[222:225], v162 offset:22528
	ds_read_b128 v[226:229], v162 offset:23552
	global_load_lds_dwordx4 v[146:147], off
	s_add_i32 m0, s8, 0x2000
	s_add_u32 s8, s46, 0xb0000
	v_lshl_add_u64 v[230:231], s[46:47], 0, v[134:135]
	s_addc_u32 s9, s47, 0
	s_add_i32 s60, s68, s52
	global_load_lds_dwordx4 v[230:231], off
	v_lshl_add_u64 v[232:233], s[8:9], 0, v[130:131]
	s_mov_b32 m0, s60
	v_lshl_add_u64 v[234:235], s[48:49], 0, v[132:133]
	global_load_lds_dwordx4 v[232:233], off
	v_lshl_add_u64 v[232:233], s[8:9], 0, v[134:135]
	s_add_i32 m0, s60, 0x2000
	s_nop 0
	global_load_lds_dwordx4 v[232:233], off
	v_lshl_add_u64 v[232:233], s[48:49], 0, v[128:129]
	s_mov_b32 m0, s53
	s_nop 0
	global_load_lds_dwordx4 v[232:233], off
	s_mov_b32 m0, s54
	s_nop 0
	global_load_lds_dwordx4 v[234:235], off
	s_waitcnt vmcnt(8)
	s_waitcnt lgkmcnt(0)
	s_barrier
; #define PG8_STAGE(bufoff, gbase, voff) do { _Pragma("unroll") for (int _i = 0; _i < 2; ++_i) \
;         __builtin_amdgcn_global_load_lds((const unsigned*)((const char*)(gbase) + (voff)[_i]), (PG8_LAS unsigned*)(lds + (bufoff) + ldsw + _i * 8192), 16, 0, 0); } while (0)
; #define PG8_LDA(dst, b, h) do { _Pragma("unroll") for (int m = 0; m < 4; ++m) _Pragma("unroll") for (int k = 0; k < 2; ++k) dst[m][k] = *(const PG8_LAS bf16x8*)(lds + PG8_SA(b, h) + aoff + m * 2048 + k * 1024); } while (0)
; #define PG8_LDB(dst, b, h) do { _Pragma("unroll") for (int n = 0; n < 2; ++n) _Pragma("unroll") for (int k = 0; k < 2; ++k) dst[n][k] = *(const PG8_LAS bf16x8*)(lds + PG8_SB(b, h) + boff + n * 2048 + k * 1024); } while (0)
; #define PG8_MMA(ai, bj, At, Bt) do { __builtin_amdgcn_s_setprio(1); _Pragma("unroll") for (int m = 0; m < 4; ++m) _Pragma("unroll") for (int n = 0; n < 2; ++n) _Pragma("unroll") for (int k = 0; k < 2; ++k) \
;         acc[ai][bj][m][n] = __builtin_amdgcn_mfma_f32_16x16x32_bf16(Bt[n][k], At[m][k], acc[ai][bj][m][n], 0, 0, 0); __builtin_amdgcn_s_setprio(0); } while (0)
; #define PG8_WAIT_V(n) asm volatile("s_waitcnt vmcnt(" #n ")" ::: "memory")
; #define PG8_WAIT_L(n) asm volatile("s_waitcnt lgkmcnt(" #n ")" ::: "memory")
; #define PG8_BAR __builtin_amdgcn_s_barrier()
; #define PG8_SCHED __builtin_amdgcn_sched_barrier(0)
; template <class Epi, class Sched, bool ALIGN_EPI = false, bool SP2 = false>
; __device__ __forceinline__ void gemm_phase(PG8_LAS unsigned char* lds, const Gemm g, const Sched& S, const Epi& E) {
;     ...
;             PG8_WAIT_V(8); PG8_WAIT_L(0); PG8_BAR; PG8_MMA(1, 0, At, B0); PG8_MMA(1, 1, At, B1); PG8_BAR; PG8_SCHED;
;             PG8_LDB(B0, 1, 0); PG8_LDB(B1, 1, 1); PG8_SCHED; PG8_LDA(At, 1, 0); PG8_STAGE(PG8_SA(0, 1), a2 + hstep, voffA);
;             PG8_WAIT_V(8); PG8_WAIT_L(0); PG8_BAR; PG8_MMA(0, 0, At, B0); PG8_MMA(0, 1, At, B1); PG8_BAR; PG8_SCHED;
	s_setprio 1
	s_waitcnt lgkmcnt(0)
	v_mfma_f32_16x16x32_bf16 v[60:63], v[164:167], v[198:201], v[60:63]
	v_mfma_f32_16x16x32_bf16 v[56:59], v[172:175], v[198:201], v[56:59]
	v_mfma_f32_16x16x32_bf16 v[48:51], v[164:167], v[206:209], v[48:51]
	v_mfma_f32_16x16x32_bf16 v[40:43], v[172:175], v[206:209], v[40:43]
	v_mfma_f32_16x16x32_bf16 v[32:35], v[164:167], v[214:217], v[32:35]
	v_mfma_f32_16x16x32_bf16 v[24:27], v[172:175], v[214:217], v[24:27]
	v_mfma_f32_16x16x32_bf16 v[16:19], v[164:167], v[222:225], v[16:19]
	v_mfma_f32_16x16x32_bf16 v[8:11], v[172:175], v[222:225], v[8:11]
	v_mfma_f32_16x16x32_bf16 v[60:63], v[168:171], v[202:205], v[60:63]
	v_mfma_f32_16x16x32_bf16 v[56:59], v[178:181], v[202:205], v[56:59]
	v_mfma_f32_16x16x32_bf16 v[48:51], v[168:171], v[210:213], v[48:51]
	v_mfma_f32_16x16x32_bf16 v[40:43], v[178:181], v[210:213], v[40:43]
	v_mfma_f32_16x16x32_bf16 v[32:35], v[168:171], v[218:221], v[32:35]
	v_mfma_f32_16x16x32_bf16 v[24:27], v[178:181], v[218:221], v[24:27]
	v_mfma_f32_16x16x32_bf16 v[16:19], v[168:171], v[226:229], v[16:19]
	v_mfma_f32_16x16x32_bf16 v[8:11], v[178:181], v[226:229], v[8:11]
	s_setprio 0
	s_setprio 1
	v_mfma_f32_16x16x32_bf16 v[52:55], v[182:185], v[198:201], v[52:55]
	v_mfma_f32_16x16x32_bf16 v[44:47], v[190:193], v[198:201], v[44:47]
	v_mfma_f32_16x16x32_bf16 v[36:39], v[182:185], v[206:209], v[36:39]
	v_mfma_f32_16x16x32_bf16 v[28:31], v[190:193], v[206:209], v[28:31]
	v_mfma_f32_16x16x32_bf16 v[20:23], v[182:185], v[214:217], v[20:23]
	v_mfma_f32_16x16x32_bf16 v[12:15], v[190:193], v[214:217], v[12:15]
	v_mfma_f32_16x16x32_bf16 v[4:7], v[182:185], v[222:225], v[4:7]
	v_mfma_f32_16x16x32_bf16 v[0:3], v[190:193], v[222:225], v[0:3]
	v_mfma_f32_16x16x32_bf16 v[52:55], v[186:189], v[202:205], v[52:55]
	v_mfma_f32_16x16x32_bf16 v[44:47], v[194:197], v[202:205], v[44:47]
	v_mfma_f32_16x16x32_bf16 v[36:39], v[186:189], v[210:213], v[36:39]
	v_mfma_f32_16x16x32_bf16 v[28:31], v[194:197], v[210:213], v[28:31]
	v_mfma_f32_16x16x32_bf16 v[20:23], v[186:189], v[218:221], v[20:23]
	v_mfma_f32_16x16x32_bf16 v[12:15], v[194:197], v[218:221], v[12:15]
	v_mfma_f32_16x16x32_bf16 v[4:7], v[186:189], v[226:229], v[4:7]
	v_mfma_f32_16x16x32_bf16 v[0:3], v[194:197], v[226:229], v[0:3]
	s_setprio 0
	s_barrier
	s_add_i32 s60, 0, 0x18000
	v_add_u32_e32 v144, s60, v157
	s_add_i32 s61, 0, 0x1c000
	ds_read_b128 v[164:167], v144
	ds_read_b128 v[168:171], v144 offset:1024
	ds_read_b128 v[172:175], v144 offset:2048
	ds_read_b128 v[178:181], v144 offset:3072
	v_add_u32_e32 v144, s61, v157
	ds_read_b128 v[182:185], v144
	ds_read_b128 v[186:189], v144 offset:1024
	ds_read_b128 v[190:193], v144 offset:2048
	ds_read_b128 v[194:197], v144 offset:3072
	s_add_u32 s8, s48, 0xb0000
	s_addc_u32 s9, s49, 0
	s_mov_b32 m0, s55
	v_lshl_add_u64 v[236:237], s[8:9], 0, v[128:129]
	ds_read_b128 v[198:201], v162 offset:32768
	ds_read_b128 v[202:205], v162 offset:33792
	ds_read_b128 v[206:209], v162 offset:34816
	ds_read_b128 v[210:213], v162 offset:35840
	ds_read_b128 v[214:217], v162 offset:36864
	ds_read_b128 v[218:221], v162 offset:37888
	ds_read_b128 v[222:225], v162 offset:38912
	ds_read_b128 v[226:229], v162 offset:39936
	global_load_lds_dwordx4 v[236:237], off
	v_lshl_add_u64 v[236:237], s[8:9], 0, v[132:133]
	s_mov_b32 m0, s56
	s_nop 0
	global_load_lds_dwordx4 v[236:237], off
	s_waitcnt vmcnt(8)
	s_waitcnt lgkmcnt(0)
	s_barrier
	s_setprio 1
	s_waitcnt lgkmcnt(0)
	v_mfma_f32_16x16x32_bf16 v[124:127], v[164:167], v[198:201], v[124:127]
	v_mfma_f32_16x16x32_bf16 v[120:123], v[172:175], v[198:201], v[120:123]
	v_mfma_f32_16x16x32_bf16 v[112:115], v[164:167], v[206:209], v[112:115]
	v_mfma_f32_16x16x32_bf16 v[104:107], v[172:175], v[206:209], v[104:107]
	v_mfma_f32_16x16x32_bf16 v[96:99], v[164:167], v[214:217], v[96:99]
	v_mfma_f32_16x16x32_bf16 v[88:91], v[172:175], v[214:217], v[88:91]
	v_mfma_f32_16x16x32_bf16 v[80:83], v[164:167], v[222:225], v[80:83]
	v_mfma_f32_16x16x32_bf16 v[72:75], v[172:175], v[222:225], v[72:75]
	v_mfma_f32_16x16x32_bf16 v[124:127], v[168:171], v[202:205], v[124:127]
	v_mfma_f32_16x16x32_bf16 v[120:123], v[178:181], v[202:205], v[120:123]
	v_mfma_f32_16x16x32_bf16 v[112:115], v[168:171], v[210:213], v[112:115]
	v_mfma_f32_16x16x32_bf16 v[104:107], v[178:181], v[210:213], v[104:107]
	v_mfma_f32_16x16x32_bf16 v[96:99], v[168:171], v[218:221], v[96:99]
	v_mfma_f32_16x16x32_bf16 v[88:91], v[178:181], v[218:221], v[88:91]
	v_mfma_f32_16x16x32_bf16 v[80:83], v[168:171], v[226:229], v[80:83]
	v_mfma_f32_16x16x32_bf16 v[72:75], v[178:181], v[226:229], v[72:75]
	s_setprio 0
	s_setprio 1
	v_mfma_f32_16x16x32_bf16 v[116:119], v[182:185], v[198:201], v[116:119]
	v_mfma_f32_16x16x32_bf16 v[108:111], v[190:193], v[198:201], v[108:111]
	v_mfma_f32_16x16x32_bf16 v[100:103], v[182:185], v[206:209], v[100:103]
	v_mfma_f32_16x16x32_bf16 v[92:95], v[190:193], v[206:209], v[92:95]
	v_mfma_f32_16x16x32_bf16 v[84:87], v[182:185], v[214:217], v[84:87]
	v_mfma_f32_16x16x32_bf16 v[76:79], v[190:193], v[214:217], v[76:79]
	v_mfma_f32_16x16x32_bf16 v[68:71], v[182:185], v[222:225], v[68:71]
	v_mfma_f32_16x16x32_bf16 v[64:67], v[190:193], v[222:225], v[64:67]
	v_mfma_f32_16x16x32_bf16 v[116:119], v[186:189], v[202:205], v[116:119]
	v_mfma_f32_16x16x32_bf16 v[108:111], v[194:197], v[202:205], v[108:111]
	v_mfma_f32_16x16x32_bf16 v[100:103], v[186:189], v[210:213], v[100:103]
	v_mfma_f32_16x16x32_bf16 v[92:95], v[194:197], v[210:213], v[92:95]
	v_mfma_f32_16x16x32_bf16 v[84:87], v[186:189], v[218:221], v[84:87]
	v_mfma_f32_16x16x32_bf16 v[76:79], v[194:197], v[218:221], v[76:79]
	v_mfma_f32_16x16x32_bf16 v[68:71], v[186:189], v[226:229], v[68:71]
	v_mfma_f32_16x16x32_bf16 v[64:67], v[194:197], v[226:229], v[64:67]
	s_setprio 0
	s_barrier
; #define PG8_STAGE(bufoff, gbase, voff) do { _Pragma("unroll") for (int _i = 0; _i < 2; ++_i) \
;         __builtin_amdgcn_global_load_lds((const unsigned*)((const char*)(gbase) + (voff)[_i]), (PG8_LAS unsigned*)(lds + (bufoff) + ldsw + _i * 8192), 16, 0, 0); } while (0)
; #define PG8_LDA(dst, b, h) do { _Pragma("unroll") for (int m = 0; m < 4; ++m) _Pragma("unroll") for (int k = 0; k < 2; ++k) dst[m][k] = *(const PG8_LAS bf16x8*)(lds + PG8_SA(b, h) + aoff + m * 2048 + k * 1024); } while (0)
; #define PG8_MMA(ai, bj, At, Bt) do { __builtin_amdgcn_s_setprio(1); _Pragma("unroll") for (int m = 0; m < 4; ++m) _Pragma("unroll") for (int n = 0; n < 2; ++n) _Pragma("unroll") for (int k = 0; k < 2; ++k) \
;         acc[ai][bj][m][n] = __builtin_amdgcn_mfma_f32_16x16x32_bf16(Bt[n][k], At[m][k], acc[ai][bj][m][n], 0, 0, 0); __builtin_amdgcn_s_setprio(0); } while (0)
; #define PG8_WAIT_V(n) asm volatile("s_waitcnt vmcnt(" #n ")" ::: "memory")
; #define PG8_WAIT_L(n) asm volatile("s_waitcnt lgkmcnt(" #n ")" ::: "memory")
; #define PG8_BAR __builtin_amdgcn_s_barrier()
; #define PG8_SCHED __builtin_amdgcn_sched_barrier(0)
; template <class Epi, class Sched, bool ALIGN_EPI = false, bool SP2 = false>
; __device__ __forceinline__ void gemm_phase(PG8_LAS unsigned char* lds, const Gemm g, const Sched& S, const Epi& E) {
;     ...
;         for (int t = 0; t < nt; t += 2) {
;     ...
;             PG8_LDA(At, 1, 1); PG8_STAGE(PG8_SB(1, 0), b3, voffB); PG8_STAGE(PG8_SB(1, 1), b3 + hstep, voffB); PG8_STAGE(PG8_SA(1, 0), a3, voffA);
;             PG8_WAIT_V(8); PG8_WAIT_L(0); PG8_BAR; PG8_MMA(1, 0, At, B0); PG8_MMA(1, 1, At, B1); PG8_BAR; PG8_SCHED;
	s_add_i32 s8, s60, s52
	v_lshl_add_u64 v[146:147], v[146:147], 0, s[14:15]
	s_mov_b32 m0, s8
	ds_read_b128 v[198:201], v162 offset:49152
	ds_read_b128 v[202:205], v162 offset:50176
	ds_read_b128 v[206:209], v162 offset:51200
	ds_read_b128 v[210:213], v162 offset:52224
	ds_read_b128 v[214:217], v162 offset:53248
	ds_read_b128 v[218:221], v162 offset:54272
	ds_read_b128 v[222:225], v162 offset:55296
	ds_read_b128 v[226:229], v162 offset:56320
	global_load_lds_dwordx4 v[146:147], off
	s_add_i32 m0, s8, 0x2000
	s_add_u32 s8, s46, 0xb0080
	v_lshl_add_u64 v[146:147], v[230:231], 0, s[14:15]
	s_addc_u32 s9, s47, 0
	s_add_i32 s46, s61, s52
	global_load_lds_dwordx4 v[146:147], off
	v_lshl_add_u64 v[146:147], s[8:9], 0, v[130:131]
	s_mov_b32 m0, s46
	s_nop 0
	global_load_lds_dwordx4 v[146:147], off
	v_lshl_add_u64 v[146:147], s[8:9], 0, v[134:135]
	s_add_i32 m0, s46, 0x2000
	s_nop 0
	global_load_lds_dwordx4 v[146:147], off
	v_lshl_add_u64 v[146:147], v[232:233], 0, s[14:15]
	s_mov_b32 m0, s63
	s_nop 0
	global_load_lds_dwordx4 v[146:147], off
	v_lshl_add_u64 v[146:147], v[234:235], 0, s[14:15]
	s_mov_b32 m0, s64
	s_nop 0
	global_load_lds_dwordx4 v[146:147], off
	s_waitcnt vmcnt(8)
	s_waitcnt lgkmcnt(0)
	s_barrier
	s_setprio 1
	s_waitcnt lgkmcnt(0)
	v_mfma_f32_16x16x32_bf16 v[60:63], v[164:167], v[198:201], v[60:63]
	v_mfma_f32_16x16x32_bf16 v[56:59], v[172:175], v[198:201], v[56:59]
	v_mfma_f32_16x16x32_bf16 v[48:51], v[164:167], v[206:209], v[48:51]
	v_mfma_f32_16x16x32_bf16 v[40:43], v[172:175], v[206:209], v[40:43]
	v_mfma_f32_16x16x32_bf16 v[32:35], v[164:167], v[214:217], v[32:35]
	v_mfma_f32_16x16x32_bf16 v[24:27], v[172:175], v[214:217], v[24:27]
	v_mfma_f32_16x16x32_bf16 v[16:19], v[164:167], v[222:225], v[16:19]
	v_mfma_f32_16x16x32_bf16 v[8:11], v[172:175], v[222:225], v[8:11]
	v_mfma_f32_16x16x32_bf16 v[60:63], v[168:171], v[202:205], v[60:63]
	v_mfma_f32_16x16x32_bf16 v[56:59], v[178:181], v[202:205], v[56:59]
	v_mfma_f32_16x16x32_bf16 v[48:51], v[168:171], v[210:213], v[48:51]
	v_mfma_f32_16x16x32_bf16 v[40:43], v[178:181], v[210:213], v[40:43]
	v_mfma_f32_16x16x32_bf16 v[32:35], v[168:171], v[218:221], v[32:35]
	v_mfma_f32_16x16x32_bf16 v[24:27], v[178:181], v[218:221], v[24:27]
	v_mfma_f32_16x16x32_bf16 v[16:19], v[168:171], v[226:229], v[16:19]
	v_mfma_f32_16x16x32_bf16 v[8:11], v[178:181], v[226:229], v[8:11]
	s_setprio 0
	s_setprio 1
	v_mfma_f32_16x16x32_bf16 v[52:55], v[182:185], v[198:201], v[52:55]
	v_mfma_f32_16x16x32_bf16 v[44:47], v[190:193], v[198:201], v[44:47]
	v_mfma_f32_16x16x32_bf16 v[36:39], v[182:185], v[206:209], v[36:39]
	v_mfma_f32_16x16x32_bf16 v[28:31], v[190:193], v[206:209], v[28:31]
	v_mfma_f32_16x16x32_bf16 v[20:23], v[182:185], v[214:217], v[20:23]
	v_mfma_f32_16x16x32_bf16 v[12:15], v[190:193], v[214:217], v[12:15]
	v_mfma_f32_16x16x32_bf16 v[4:7], v[182:185], v[222:225], v[4:7]
	v_mfma_f32_16x16x32_bf16 v[0:3], v[190:193], v[222:225], v[0:3]
	v_mfma_f32_16x16x32_bf16 v[52:55], v[186:189], v[202:205], v[52:55]
	v_mfma_f32_16x16x32_bf16 v[44:47], v[194:197], v[202:205], v[44:47]
	v_mfma_f32_16x16x32_bf16 v[36:39], v[186:189], v[210:213], v[36:39]
	v_mfma_f32_16x16x32_bf16 v[28:31], v[194:197], v[210:213], v[28:31]
	v_mfma_f32_16x16x32_bf16 v[20:23], v[186:189], v[218:221], v[20:23]
	v_mfma_f32_16x16x32_bf16 v[12:15], v[194:197], v[218:221], v[12:15]
	v_mfma_f32_16x16x32_bf16 v[4:7], v[186:189], v[226:229], v[4:7]
	v_mfma_f32_16x16x32_bf16 v[0:3], v[194:197], v[226:229], v[0:3]
	s_setprio 0
	s_add_i32 s79, s79, 2
	s_add_u32 s44, s44, 0x100
	s_addc_u32 s45, s45, 0
	s_add_u32 s77, s77, 0x100
	s_addc_u32 s78, s78, 0
	s_cmp_gt_u32 s79, 41
	s_barrier
	s_cbranch_scc0 .LBB0_1420
	s_and_b64 vcc, exec, s[18:19]
	s_cbranch_vccz .LBB0_1423
	s_barrier

; #define PG8_STAGE(bufoff, gbase, voff) do { _Pragma("unroll") for (int _i = 0; _i < 2; ++_i) \
;         __builtin_amdgcn_global_load_lds((const unsigned*)((const char*)(gbase) + (voff)[_i]), (PG8_LAS unsigned*)(lds + (bufoff) + ldsw + _i * 8192), 16, 0, 0); } while (0)
; #define PG8_LDA(dst, b, h) do { _Pragma("unroll") for (int m = 0; m < 4; ++m) _Pragma("unroll") for (int k = 0; k < 2; ++k) dst[m][k] = *(const PG8_LAS bf16x8*)(lds + PG8_SA(b, h) + aoff + m * 2048 + k * 1024); } while (0)
; #define PG8_LDB(dst, b, h) do { _Pragma("unroll") for (int n = 0; n < 2; ++n) _Pragma("unroll") for (int k = 0; k < 2; ++k) dst[n][k] = *(const PG8_LAS bf16x8*)(lds + PG8_SB(b, h) + boff + n * 2048 + k * 1024); } while (0)
; #define PG8_MMA(ai, bj, At, Bt) do { __builtin_amdgcn_s_setprio(1); _Pragma("unroll") for (int m = 0; m < 4; ++m) _Pragma("unroll") for (int n = 0; n < 2; ++n) _Pragma("unroll") for (int k = 0; k < 2; ++k) \
;         acc[ai][bj][m][n] = __builtin_amdgcn_mfma_f32_16x16x32_bf16(Bt[n][k], At[m][k], acc[ai][bj][m][n], 0, 0, 0); __builtin_amdgcn_s_setprio(0); } while (0)
; #define PG8_WAIT_V(n) asm volatile("s_waitcnt vmcnt(" #n ")" ::: "memory")
; #define PG8_WAIT_L(n) asm volatile("s_waitcnt lgkmcnt(" #n ")" ::: "memory")
; #define PG8_BAR __builtin_amdgcn_s_barrier()
; #define PG8_SCHED __builtin_amdgcn_sched_barrier(0)
; template <class Epi, class Sched, bool ALIGN_EPI = false, bool SP2 = false>
; __device__ __forceinline__ void gemm_phase(PG8_LAS unsigned char* lds, const Gemm g, const Sched& S, const Epi& E) {
;     ...
;             const char* a1 = cA + (size_t)(t + 1) * kstep;
;             const char* a2 = last ? nA : cA + (size_t)(t + 2) * kstep; const char* b2 = last ? nB : cB + (size_t)(t + 2) * kstep;
;             const char* a3 = a2 + kstep; const char* b3 = b2 + kstep;
;             if (last && has_next) S.a_ready(nxt);
;             if constexpr (SP2) {
;             PG8_LDB(B0, 0, 0); PG8_LDB(B1, 0, 1); PG8_SCHED; PG8_LDA(At, 0, 0); PG8_STAGE(PG8_SA(1, 1), a1 + hstep, voffA);
;             PG8_WAIT_V(8); PG8_WAIT_L(0); PG8_BAR; PG8_MMA(0, 0, At, B0); PG8_MMA(0, 1, At, B1); PG8_BAR; PG8_SCHED;
;             PG8_LDA(At, 0, 1); PG8_STAGE(PG8_SB(0, 0), b2, voffB); PG8_STAGE(PG8_SB(0, 1), b2 + hstep, voffB); PG8_STAGE(PG8_SA(0, 0), a2, voffA);
.LBB0_1617:
	ds_read_b128 v[144:147], v153
	ds_read_b128 v[156:159], v153 offset:1024
	ds_read_b128 v[160:163], v153 offset:2048
	ds_read_b128 v[164:167], v153 offset:3072
	ds_read_b128 v[168:171], v154
	ds_read_b128 v[172:175], v154 offset:1024
	ds_read_b128 v[176:179], v154 offset:2048
	ds_read_b128 v[180:183], v154 offset:3072
	s_add_u32 s40, s38, 0xfffc0080
	s_addc_u32 s41, s39, -1
	s_cmp_eq_u32 s61, 12
	s_cselect_b32 s43, s25, s41
	s_cselect_b32 s42, s55, s40
	s_cselect_b32 s41, s23, s60
	s_cselect_b32 s40, s56, s57
	v_lshl_add_u64 v[148:149], s[38:39], 0, v[136:137]
	s_add_i32 m0, s31, 0xc000
	ds_read_b128 v[184:187], v155
	ds_read_b128 v[188:191], v155 offset:1024
	ds_read_b128 v[192:195], v155 offset:2048
	ds_read_b128 v[196:199], v155 offset:3072
	ds_read_b128 v[200:203], v155 offset:4096
	ds_read_b128 v[204:207], v155 offset:5120
	ds_read_b128 v[208:211], v155 offset:6144
	ds_read_b128 v[212:215], v155 offset:7168
	global_load_lds_dwordx4 v[148:149], off
	v_lshl_add_u64 v[148:149], s[38:39], 0, v[138:139]
	s_add_i32 m0, s31, 0xe000
	s_nop 0
	global_load_lds_dwordx4 v[148:149], off
	s_waitcnt vmcnt(8)
	s_waitcnt lgkmcnt(0)
	s_barrier
	s_setprio 1
	s_waitcnt lgkmcnt(0)
	v_mfma_f32_16x16x32_bf16 v[124:127], v[144:147], v[184:187], v[124:127]
	v_mfma_f32_16x16x32_bf16 v[120:123], v[160:163], v[184:187], v[120:123]
	v_mfma_f32_16x16x32_bf16 v[108:111], v[144:147], v[192:195], v[108:111]
	v_mfma_f32_16x16x32_bf16 v[104:107], v[160:163], v[192:195], v[104:107]
	v_mfma_f32_16x16x32_bf16 v[92:95], v[144:147], v[200:203], v[92:95]
	v_mfma_f32_16x16x32_bf16 v[88:91], v[160:163], v[200:203], v[88:91]
	v_mfma_f32_16x16x32_bf16 v[76:79], v[144:147], v[208:211], v[76:79]
	v_mfma_f32_16x16x32_bf16 v[72:75], v[160:163], v[208:211], v[72:75]
	v_mfma_f32_16x16x32_bf16 v[124:127], v[156:159], v[188:191], v[124:127]
	v_mfma_f32_16x16x32_bf16 v[120:123], v[164:167], v[188:191], v[120:123]
	v_mfma_f32_16x16x32_bf16 v[108:111], v[156:159], v[196:199], v[108:111]
	v_mfma_f32_16x16x32_bf16 v[104:107], v[164:167], v[196:199], v[104:107]
	v_mfma_f32_16x16x32_bf16 v[92:95], v[156:159], v[204:207], v[92:95]
	v_mfma_f32_16x16x32_bf16 v[88:91], v[164:167], v[204:207], v[88:91]
	v_mfma_f32_16x16x32_bf16 v[76:79], v[156:159], v[212:215], v[76:79]
	v_mfma_f32_16x16x32_bf16 v[72:75], v[164:167], v[212:215], v[72:75]
	s_setprio 0
	s_setprio 1
	v_mfma_f32_16x16x32_bf16 v[116:119], v[168:171], v[184:187], v[116:119]
	v_mfma_f32_16x16x32_bf16 v[112:115], v[176:179], v[184:187], v[112:115]
	v_mfma_f32_16x16x32_bf16 v[100:103], v[168:171], v[192:195], v[100:103]
	v_mfma_f32_16x16x32_bf16 v[96:99], v[176:179], v[192:195], v[96:99]
	v_mfma_f32_16x16x32_bf16 v[84:87], v[168:171], v[200:203], v[84:87]
	v_mfma_f32_16x16x32_bf16 v[80:83], v[176:179], v[200:203], v[80:83]
	v_mfma_f32_16x16x32_bf16 v[68:71], v[168:171], v[208:211], v[68:71]
	v_mfma_f32_16x16x32_bf16 v[64:67], v[176:179], v[208:211], v[64:67]
	v_mfma_f32_16x16x32_bf16 v[116:119], v[172:175], v[188:191], v[116:119]
	v_mfma_f32_16x16x32_bf16 v[112:115], v[180:183], v[188:191], v[112:115]
	v_mfma_f32_16x16x32_bf16 v[100:103], v[172:175], v[196:199], v[100:103]
	v_mfma_f32_16x16x32_bf16 v[96:99], v[180:183], v[196:199], v[96:99]
	v_mfma_f32_16x16x32_bf16 v[84:87], v[172:175], v[204:207], v[84:87]
	v_mfma_f32_16x16x32_bf16 v[80:83], v[180:183], v[204:207], v[80:83]
	v_mfma_f32_16x16x32_bf16 v[68:71], v[172:175], v[212:215], v[68:71]
	v_mfma_f32_16x16x32_bf16 v[64:67], v[180:183], v[212:215], v[64:67]
	s_setprio 0
	s_barrier
	s_add_i32 s62, s52, s44
	v_lshl_add_u64 v[148:149], s[40:41], 0, v[130:131]
	s_mov_b32 m0, s62
	ds_read_b128 v[184:187], v155 offset:16384
	ds_read_b128 v[188:191], v155 offset:17408
	ds_read_b128 v[192:195], v155 offset:18432
	ds_read_b128 v[196:199], v155 offset:19456
	ds_read_b128 v[200:203], v155 offset:20480
	ds_read_b128 v[204:207], v155 offset:21504
	ds_read_b128 v[208:211], v155 offset:22528
	ds_read_b128 v[212:215], v155 offset:23552
	global_load_lds_dwordx4 v[148:149], off
	s_add_i32 m0, s62, 0x2000
	s_add_u32 s62, s40, 0x40000
	v_lshl_add_u64 v[216:217], s[40:41], 0, v[134:135]
	s_addc_u32 s63, s41, 0
	s_add_i32 s64, s53, s44
	global_load_lds_dwordx4 v[216:217], off
	v_lshl_add_u64 v[218:219], s[62:63], 0, v[130:131]
	s_mov_b32 m0, s64
	v_lshl_add_u64 v[220:221], s[42:43], 0, v[132:133]
	global_load_lds_dwordx4 v[218:219], off
	v_lshl_add_u64 v[218:219], s[62:63], 0, v[134:135]
	s_add_i32 m0, s64, 0x2000
	s_nop 0
	global_load_lds_dwordx4 v[218:219], off
	v_lshl_add_u64 v[218:219], s[42:43], 0, v[128:129]
	s_mov_b32 m0, s31
	s_nop 0
	global_load_lds_dwordx4 v[218:219], off
	s_mov_b32 m0, s45
	s_nop 0
	global_load_lds_dwordx4 v[220:221], off
	s_waitcnt vmcnt(8)
	s_waitcnt lgkmcnt(0)
	s_barrier
; #define PG8_STAGE(bufoff, gbase, voff) do { _Pragma("unroll") for (int _i = 0; _i < 2; ++_i) \
;         __builtin_amdgcn_global_load_lds((const unsigned*)((const char*)(gbase) + (voff)[_i]), (PG8_LAS unsigned*)(lds + (bufoff) + ldsw + _i * 8192), 16, 0, 0); } while (0)
; #define PG8_LDA(dst, b, h) do { _Pragma("unroll") for (int m = 0; m < 4; ++m) _Pragma("unroll") for (int k = 0; k < 2; ++k) dst[m][k] = *(const PG8_LAS bf16x8*)(lds + PG8_SA(b, h) + aoff + m * 2048 + k * 1024); } while (0)
; #define PG8_LDB(dst, b, h) do { _Pragma("unroll") for (int n = 0; n < 2; ++n) _Pragma("unroll") for (int k = 0; k < 2; ++k) dst[n][k] = *(const PG8_LAS bf16x8*)(lds + PG8_SB(b, h) + boff + n * 2048 + k * 1024); } while (0)
; #define PG8_MMA(ai, bj, At, Bt) do { __builtin_amdgcn_s_setprio(1); _Pragma("unroll") for (int m = 0; m < 4; ++m) _Pragma("unroll") for (int n = 0; n < 2; ++n) _Pragma("unroll") for (int k = 0; k < 2; ++k) \
;         acc[ai][bj][m][n] = __builtin_amdgcn_mfma_f32_16x16x32_bf16(Bt[n][k], At[m][k], acc[ai][bj][m][n], 0, 0, 0); __builtin_amdgcn_s_setprio(0); } while (0)
; #define PG8_WAIT_V(n) asm volatile("s_waitcnt vmcnt(" #n ")" ::: "memory")
; #define PG8_WAIT_L(n) asm volatile("s_waitcnt lgkmcnt(" #n ")" ::: "memory")
; #define PG8_BAR __builtin_amdgcn_s_barrier()
; #define PG8_SCHED __builtin_amdgcn_sched_barrier(0)
; template <class Epi, class Sched, bool ALIGN_EPI = false, bool SP2 = false>
; __device__ __forceinline__ void gemm_phase(PG8_LAS unsigned char* lds, const Gemm g, const Sched& S, const Epi& E) {
;     ...
;             PG8_WAIT_V(8); PG8_WAIT_L(0); PG8_BAR; PG8_MMA(1, 0, At, B0); PG8_MMA(1, 1, At, B1); PG8_BAR; PG8_SCHED;
;             PG8_LDB(B0, 1, 0); PG8_LDB(B1, 1, 1); PG8_SCHED; PG8_LDA(At, 1, 0); PG8_STAGE(PG8_SA(0, 1), a2 + hstep, voffA);
;             PG8_WAIT_V(8); PG8_WAIT_L(0); PG8_BAR; PG8_MMA(0, 0, At, B0); PG8_MMA(0, 1, At, B1); PG8_BAR; PG8_SCHED;
	s_setprio 1
	s_waitcnt lgkmcnt(0)
	v_mfma_f32_16x16x32_bf16 v[60:63], v[144:147], v[184:187], v[60:63]
	v_mfma_f32_16x16x32_bf16 v[56:59], v[160:163], v[184:187], v[56:59]
	v_mfma_f32_16x16x32_bf16 v[44:47], v[144:147], v[192:195], v[44:47]
	v_mfma_f32_16x16x32_bf16 v[40:43], v[160:163], v[192:195], v[40:43]
	v_mfma_f32_16x16x32_bf16 v[28:31], v[144:147], v[200:203], v[28:31]
	v_mfma_f32_16x16x32_bf16 v[24:27], v[160:163], v[200:203], v[24:27]
	v_mfma_f32_16x16x32_bf16 v[12:15], v[144:147], v[208:211], v[12:15]
	v_mfma_f32_16x16x32_bf16 v[8:11], v[160:163], v[208:211], v[8:11]
	v_mfma_f32_16x16x32_bf16 v[60:63], v[156:159], v[188:191], v[60:63]
	v_mfma_f32_16x16x32_bf16 v[56:59], v[164:167], v[188:191], v[56:59]
	v_mfma_f32_16x16x32_bf16 v[44:47], v[156:159], v[196:199], v[44:47]
	v_mfma_f32_16x16x32_bf16 v[40:43], v[164:167], v[196:199], v[40:43]
	v_mfma_f32_16x16x32_bf16 v[28:31], v[156:159], v[204:207], v[28:31]
	v_mfma_f32_16x16x32_bf16 v[24:27], v[164:167], v[204:207], v[24:27]
	v_mfma_f32_16x16x32_bf16 v[12:15], v[156:159], v[212:215], v[12:15]
	v_mfma_f32_16x16x32_bf16 v[8:11], v[164:167], v[212:215], v[8:11]
	s_setprio 0
	s_setprio 1
	v_mfma_f32_16x16x32_bf16 v[52:55], v[168:171], v[184:187], v[52:55]
	v_mfma_f32_16x16x32_bf16 v[48:51], v[176:179], v[184:187], v[48:51]
	v_mfma_f32_16x16x32_bf16 v[36:39], v[168:171], v[192:195], v[36:39]
	v_mfma_f32_16x16x32_bf16 v[32:35], v[176:179], v[192:195], v[32:35]
	v_mfma_f32_16x16x32_bf16 v[20:23], v[168:171], v[200:203], v[20:23]
	v_mfma_f32_16x16x32_bf16 v[16:19], v[176:179], v[200:203], v[16:19]
	v_mfma_f32_16x16x32_bf16 v[4:7], v[168:171], v[208:211], v[4:7]
	v_mfma_f32_16x16x32_bf16 v[0:3], v[176:179], v[208:211], v[0:3]
	v_mfma_f32_16x16x32_bf16 v[52:55], v[172:175], v[188:191], v[52:55]
	v_mfma_f32_16x16x32_bf16 v[48:51], v[180:183], v[188:191], v[48:51]
	v_mfma_f32_16x16x32_bf16 v[36:39], v[172:175], v[196:199], v[36:39]
	v_mfma_f32_16x16x32_bf16 v[32:35], v[180:183], v[196:199], v[32:35]
	v_mfma_f32_16x16x32_bf16 v[20:23], v[172:175], v[204:207], v[20:23]
	v_mfma_f32_16x16x32_bf16 v[16:19], v[180:183], v[204:207], v[16:19]
	v_mfma_f32_16x16x32_bf16 v[4:7], v[172:175], v[212:215], v[4:7]
	v_mfma_f32_16x16x32_bf16 v[0:3], v[180:183], v[212:215], v[0:3]
	s_setprio 0
	s_barrier
	s_add_i32 s62, 0, 0x18000
	s_add_i32 s63, 0, 0x1c000
	v_add_u32_e32 v164, s62, v151
	v_add_u32_e32 v180, s63, v151
	ds_read_b128 v[144:147], v164
	ds_read_b128 v[156:159], v164 offset:1024
	ds_read_b128 v[160:163], v164 offset:2048
	ds_read_b128 v[164:167], v164 offset:3072
	ds_read_b128 v[168:171], v180
	ds_read_b128 v[172:175], v180 offset:1024
	ds_read_b128 v[176:179], v180 offset:2048
	ds_read_b128 v[180:183], v180 offset:3072
	s_add_u32 s42, s42, 0x40000
	s_addc_u32 s43, s43, 0
	s_mov_b32 m0, s46
	v_lshl_add_u64 v[222:223], s[42:43], 0, v[128:129]
	ds_read_b128 v[184:187], v155 offset:32768
	ds_read_b128 v[188:191], v155 offset:33792
	ds_read_b128 v[192:195], v155 offset:34816
	ds_read_b128 v[196:199], v155 offset:35840
	ds_read_b128 v[200:203], v155 offset:36864
	ds_read_b128 v[204:207], v155 offset:37888
	ds_read_b128 v[208:211], v155 offset:38912
	ds_read_b128 v[212:215], v155 offset:39936
	global_load_lds_dwordx4 v[222:223], off
	v_lshl_add_u64 v[222:223], s[42:43], 0, v[132:133]
	s_mov_b32 m0, s47
	s_nop 0
	global_load_lds_dwordx4 v[222:223], off
	s_waitcnt vmcnt(8)
	s_waitcnt lgkmcnt(0)
	s_barrier
	s_setprio 1
	s_waitcnt lgkmcnt(0)
	v_mfma_f32_16x16x32_bf16 v[124:127], v[144:147], v[184:187], v[124:127]
	v_mfma_f32_16x16x32_bf16 v[120:123], v[160:163], v[184:187], v[120:123]
	v_mfma_f32_16x16x32_bf16 v[108:111], v[144:147], v[192:195], v[108:111]
	v_mfma_f32_16x16x32_bf16 v[104:107], v[160:163], v[192:195], v[104:107]
	v_mfma_f32_16x16x32_bf16 v[92:95], v[144:147], v[200:203], v[92:95]
	v_mfma_f32_16x16x32_bf16 v[88:91], v[160:163], v[200:203], v[88:91]
	v_mfma_f32_16x16x32_bf16 v[76:79], v[144:147], v[208:211], v[76:79]
	v_mfma_f32_16x16x32_bf16 v[72:75], v[160:163], v[208:211], v[72:75]
	v_mfma_f32_16x16x32_bf16 v[124:127], v[156:159], v[188:191], v[124:127]
	v_mfma_f32_16x16x32_bf16 v[120:123], v[164:167], v[188:191], v[120:123]
	v_mfma_f32_16x16x32_bf16 v[108:111], v[156:159], v[196:199], v[108:111]
	v_mfma_f32_16x16x32_bf16 v[104:107], v[164:167], v[196:199], v[104:107]
	v_mfma_f32_16x16x32_bf16 v[92:95], v[156:159], v[204:207], v[92:95]
	v_mfma_f32_16x16x32_bf16 v[88:91], v[164:167], v[204:207], v[88:91]
	v_mfma_f32_16x16x32_bf16 v[76:79], v[156:159], v[212:215], v[76:79]
	v_mfma_f32_16x16x32_bf16 v[72:75], v[164:167], v[212:215], v[72:75]
	s_setprio 0
	s_setprio 1
	v_mfma_f32_16x16x32_bf16 v[116:119], v[168:171], v[184:187], v[116:119]
	v_mfma_f32_16x16x32_bf16 v[112:115], v[176:179], v[184:187], v[112:115]
	v_mfma_f32_16x16x32_bf16 v[100:103], v[168:171], v[192:195], v[100:103]
	v_mfma_f32_16x16x32_bf16 v[96:99], v[176:179], v[192:195], v[96:99]
	v_mfma_f32_16x16x32_bf16 v[84:87], v[168:171], v[200:203], v[84:87]
	v_mfma_f32_16x16x32_bf16 v[80:83], v[176:179], v[200:203], v[80:83]
	v_mfma_f32_16x16x32_bf16 v[68:71], v[168:171], v[208:211], v[68:71]
	v_mfma_f32_16x16x32_bf16 v[64:67], v[176:179], v[208:211], v[64:67]
	v_mfma_f32_16x16x32_bf16 v[116:119], v[172:175], v[188:191], v[116:119]
	v_mfma_f32_16x16x32_bf16 v[112:115], v[180:183], v[188:191], v[112:115]
	v_mfma_f32_16x16x32_bf16 v[100:103], v[172:175], v[196:199], v[100:103]
	v_mfma_f32_16x16x32_bf16 v[96:99], v[180:183], v[196:199], v[96:99]
	v_mfma_f32_16x16x32_bf16 v[84:87], v[172:175], v[204:207], v[84:87]
	v_mfma_f32_16x16x32_bf16 v[80:83], v[180:183], v[204:207], v[80:83]
	v_mfma_f32_16x16x32_bf16 v[68:71], v[172:175], v[212:215], v[68:71]
	v_mfma_f32_16x16x32_bf16 v[64:67], v[180:183], v[212:215], v[64:67]
	s_setprio 0
	s_barrier
; #define PG8_STAGE(bufoff, gbase, voff) do { _Pragma("unroll") for (int _i = 0; _i < 2; ++_i) \
;         __builtin_amdgcn_global_load_lds((const unsigned*)((const char*)(gbase) + (voff)[_i]), (PG8_LAS unsigned*)(lds + (bufoff) + ldsw + _i * 8192), 16, 0, 0); } while (0)
; #define PG8_LDA(dst, b, h) do { _Pragma("unroll") for (int m = 0; m < 4; ++m) _Pragma("unroll") for (int k = 0; k < 2; ++k) dst[m][k] = *(const PG8_LAS bf16x8*)(lds + PG8_SA(b, h) + aoff + m * 2048 + k * 1024); } while (0)
; #define PG8_MMA(ai, bj, At, Bt) do { __builtin_amdgcn_s_setprio(1); _Pragma("unroll") for (int m = 0; m < 4; ++m) _Pragma("unroll") for (int n = 0; n < 2; ++n) _Pragma("unroll") for (int k = 0; k < 2; ++k) \
;         acc[ai][bj][m][n] = __builtin_amdgcn_mfma_f32_16x16x32_bf16(Bt[n][k], At[m][k], acc[ai][bj][m][n], 0, 0, 0); __builtin_amdgcn_s_setprio(0); } while (0)
; #define PG8_WAIT_V(n) asm volatile("s_waitcnt vmcnt(" #n ")" ::: "memory")
; #define PG8_WAIT_L(n) asm volatile("s_waitcnt lgkmcnt(" #n ")" ::: "memory")
; #define PG8_BAR __builtin_amdgcn_s_barrier()
; #define PG8_SCHED __builtin_amdgcn_sched_barrier(0)
; template <class Epi, class Sched, bool ALIGN_EPI = false, bool SP2 = false>
; __device__ __forceinline__ void gemm_phase(PG8_LAS unsigned char* lds, const Gemm g, const Sched& S, const Epi& E) {
;     ...
;         for (int t = 0; t < nt; t += 2) {
;     ...
;             PG8_LDA(At, 1, 1); PG8_STAGE(PG8_SB(1, 0), b3, voffB); PG8_STAGE(PG8_SB(1, 1), b3 + hstep, voffB); PG8_STAGE(PG8_SA(1, 0), a3, voffA);
;             PG8_WAIT_V(8); PG8_WAIT_L(0); PG8_BAR; PG8_MMA(1, 0, At, B0); PG8_MMA(1, 1, At, B1); PG8_BAR; PG8_SCHED;
	s_add_i32 s42, s62, s44
	v_lshl_add_u64 v[148:149], v[148:149], 0, s[6:7]
	s_mov_b32 m0, s42
	ds_read_b128 v[184:187], v155 offset:49152
	ds_read_b128 v[188:191], v155 offset:50176
	ds_read_b128 v[192:195], v155 offset:51200
	ds_read_b128 v[196:199], v155 offset:52224
	ds_read_b128 v[200:203], v155 offset:53248
	ds_read_b128 v[204:207], v155 offset:54272
	ds_read_b128 v[208:211], v155 offset:55296
	ds_read_b128 v[212:215], v155 offset:56320
	global_load_lds_dwordx4 v[148:149], off
	s_add_i32 m0, s42, 0x2000
	s_add_u32 s40, s40, 0x40080
	v_lshl_add_u64 v[148:149], v[216:217], 0, s[6:7]
	s_addc_u32 s41, s41, 0
	s_add_i32 s42, s63, s44
	global_load_lds_dwordx4 v[148:149], off
	v_lshl_add_u64 v[148:149], s[40:41], 0, v[130:131]
	s_mov_b32 m0, s42
	s_nop 0
	global_load_lds_dwordx4 v[148:149], off
	v_lshl_add_u64 v[148:149], s[40:41], 0, v[134:135]
	s_add_i32 m0, s42, 0x2000
	s_nop 0
	global_load_lds_dwordx4 v[148:149], off
	v_lshl_add_u64 v[148:149], v[218:219], 0, s[6:7]
	s_mov_b32 m0, s49
	s_nop 0
	global_load_lds_dwordx4 v[148:149], off
	v_lshl_add_u64 v[148:149], v[220:221], 0, s[6:7]
	s_mov_b32 m0, s50
	s_nop 0
	global_load_lds_dwordx4 v[148:149], off
	s_waitcnt vmcnt(8)
	s_waitcnt lgkmcnt(0)
	s_barrier
	s_setprio 1
	s_waitcnt lgkmcnt(0)
	v_mfma_f32_16x16x32_bf16 v[60:63], v[144:147], v[184:187], v[60:63]
	v_mfma_f32_16x16x32_bf16 v[56:59], v[160:163], v[184:187], v[56:59]
	v_mfma_f32_16x16x32_bf16 v[44:47], v[144:147], v[192:195], v[44:47]
	v_mfma_f32_16x16x32_bf16 v[40:43], v[160:163], v[192:195], v[40:43]
	v_mfma_f32_16x16x32_bf16 v[28:31], v[144:147], v[200:203], v[28:31]
	v_mfma_f32_16x16x32_bf16 v[24:27], v[160:163], v[200:203], v[24:27]
	v_mfma_f32_16x16x32_bf16 v[12:15], v[144:147], v[208:211], v[12:15]
	v_mfma_f32_16x16x32_bf16 v[8:11], v[160:163], v[208:211], v[8:11]
	v_mfma_f32_16x16x32_bf16 v[60:63], v[156:159], v[188:191], v[60:63]
	v_mfma_f32_16x16x32_bf16 v[56:59], v[164:167], v[188:191], v[56:59]
	v_mfma_f32_16x16x32_bf16 v[44:47], v[156:159], v[196:199], v[44:47]
	v_mfma_f32_16x16x32_bf16 v[40:43], v[164:167], v[196:199], v[40:43]
	v_mfma_f32_16x16x32_bf16 v[28:31], v[156:159], v[204:207], v[28:31]
	v_mfma_f32_16x16x32_bf16 v[24:27], v[164:167], v[204:207], v[24:27]
	v_mfma_f32_16x16x32_bf16 v[12:15], v[156:159], v[212:215], v[12:15]
	v_mfma_f32_16x16x32_bf16 v[8:11], v[164:167], v[212:215], v[8:11]
	s_setprio 0
	s_setprio 1
	v_mfma_f32_16x16x32_bf16 v[52:55], v[168:171], v[184:187], v[52:55]
	v_mfma_f32_16x16x32_bf16 v[48:51], v[176:179], v[184:187], v[48:51]
	v_mfma_f32_16x16x32_bf16 v[36:39], v[168:171], v[192:195], v[36:39]
	v_mfma_f32_16x16x32_bf16 v[32:35], v[176:179], v[192:195], v[32:35]
	v_mfma_f32_16x16x32_bf16 v[20:23], v[168:171], v[200:203], v[20:23]
	v_mfma_f32_16x16x32_bf16 v[16:19], v[176:179], v[200:203], v[16:19]
	v_mfma_f32_16x16x32_bf16 v[4:7], v[168:171], v[208:211], v[4:7]
	v_mfma_f32_16x16x32_bf16 v[0:3], v[176:179], v[208:211], v[0:3]
	v_mfma_f32_16x16x32_bf16 v[52:55], v[172:175], v[188:191], v[52:55]
	v_mfma_f32_16x16x32_bf16 v[48:51], v[180:183], v[188:191], v[48:51]
	v_mfma_f32_16x16x32_bf16 v[36:39], v[172:175], v[196:199], v[36:39]
	v_mfma_f32_16x16x32_bf16 v[32:35], v[180:183], v[196:199], v[32:35]
	v_mfma_f32_16x16x32_bf16 v[20:23], v[172:175], v[204:207], v[20:23]
	v_mfma_f32_16x16x32_bf16 v[16:19], v[180:183], v[204:207], v[16:19]
	v_mfma_f32_16x16x32_bf16 v[4:7], v[172:175], v[212:215], v[4:7]
	v_mfma_f32_16x16x32_bf16 v[0:3], v[180:183], v[212:215], v[0:3]
	s_setprio 0
	s_add_i32 s61, s61, 2
	s_add_u32 s38, s38, 0x100
	s_addc_u32 s39, s39, 0
	s_add_u32 s57, s57, 0x100
	s_addc_u32 s60, s60, 0
	s_cmp_gt_u32 s61, 13
	s_barrier
	s_cbranch_scc0 .LBB0_1617
	s_and_b64 vcc, exec, s[8:9]
	s_cbranch_vccz .LBB0_1620
	s_barrier
